# v26 + GEMM k-loops: counter, next-tile LDS read bases and exit test moved in front of the k-tile barrier (loop-edge rotation)
# speedup vs baseline: 1.0111x; 1.0111x over previous
; DI f32x4 mfma16(bf16x8 a, bf16x8 b, f32x4 c) { return __builtin_amdgcn_mfma_f32_16x16x32_bf16(a, b, c, 0, 0, 0); }
; template <int MI, int NJ, bool SWAP, class AP, class BP>
; DI void gemm_main(f32x4 (&acc)[MI][NJ], const AP& ap, int a_kstep, const BP& bp, int b_kstep, int nk, bf16_t* smem) {
;     ...
;   for (int kt = 0; kt < nk; ++kt) {
;     const int buf = kt & 1;
;     sstore(buf ^ 1);
;     gload(kt + 2 < nk ? kt + 2 : nk - 1);
;     __builtin_amdgcn_sched_barrier(0);
;     const bf16_t* As = smem + buf * L::STAGE + (wm * 16 * MI + l15) * LDT + quad * 8;
;     const bf16_t* Bs = smem + buf * L::STAGE + L::A_ELEMS + (wn * 16 * NJ + l15) * LDT + quad * 8;
; #pragma unroll
;     for (int ks = 0; ks < 2; ++ks) {
;       if (MI * NJ >= 32 && ks == 1) asm volatile("" ::: "memory");
;       bf16x8 b[NJ];
; #pragma unroll
;       for (int j = 0; j < NJ; ++j) b[j] = *(const bf16x8*)(Bs + j * 16 * LDT + ks * 32);
; #pragma unroll
;       for (int i = 0; i < MI; ++i) {
;         const bf16x8 a = *(const bf16x8*)(As + i * 16 * LDT + ks * 32);
; #pragma unroll
;         for (int j = 0; j < NJ; ++j) acc[i][j] = SWAP ? mfma16(b[j], a, acc[i][j]) : mfma16(a, b[j], acc[i][j]);
;       }
;     }
;     __syncthreads();
;   }
.Lgm0_main:
	ds_read_b128 v[242:245], v176 offset:4608
	s_waitcnt lgkmcnt(4)
	v_mfma_f32_16x16x32_bf16 v[124:127], v[178:181], v[212:215], v[124:127]
	s_waitcnt lgkmcnt(3)
	v_mfma_f32_16x16x32_bf16 v[120:123], v[200:203], v[212:215], v[120:123]
	s_waitcnt lgkmcnt(2)
	v_mfma_f32_16x16x32_bf16 v[116:119], v[204:207], v[212:215], v[116:119]
	s_and_b32 s5, s4, 1
	s_min_u32 s6, s4, 13
	s_xor_b32 s7, s5, 1
	s_mul_i32 s7, s7, 0x12000
	v_add3_u32 v250, s7, v171, v169
	s_waitcnt vmcnt(7)
	ds_write_b128 v250, v[128:131]
	s_waitcnt lgkmcnt(2)
	v_mfma_f32_16x16x32_bf16 v[112:115], v[208:211], v[212:215], v[112:115]
	ds_read_b128 v[246:249], v176 offset:6912
	v_mfma_f32_16x16x32_bf16 v[108:111], v[178:181], v[216:219], v[108:111]
	s_lshl_b32 s33, s6, 7
	s_add_u32 s6, s0, s33
	v_add3_u32 v251, s7, v173, v169
	v_add3_u32 v252, s7, v174, v169
	v_add3_u32 v253, s7, v175, v169
	s_addc_u32 s7, s1, 0
	v_lshl_add_u64 v[128:129], s[6:7], 0, v[160:161]
	s_nop 0
	global_load_dwordx4 v[128:131], v[128:129], off offset:256
	v_mfma_f32_16x16x32_bf16 v[104:107], v[200:203], v[216:219], v[104:107]
	v_mfma_f32_16x16x32_bf16 v[100:103], v[204:207], v[216:219], v[100:103]
	v_mfma_f32_16x16x32_bf16 v[96:99], v[208:211], v[216:219], v[96:99]
	ds_read_b128 v[212:215], v176 offset:9216
	s_waitcnt lgkmcnt(3)
	v_mfma_f32_16x16x32_bf16 v[92:95], v[178:181], v[242:245], v[92:95]
	s_waitcnt vmcnt(7)
	ds_write_b128 v251, v[132:135]
	v_mfma_f32_16x16x32_bf16 v[88:91], v[200:203], v[242:245], v[88:91]
	v_mfma_f32_16x16x32_bf16 v[84:87], v[204:207], v[242:245], v[84:87]
	v_lshl_add_u64 v[132:133], s[6:7], 0, v[162:163]
	s_nop 0
	global_load_dwordx4 v[132:135], v[132:133], off offset:256
	v_mfma_f32_16x16x32_bf16 v[80:83], v[208:211], v[242:245], v[80:83]
	ds_read_b128 v[216:219], v176 offset:11520
	s_waitcnt lgkmcnt(3)
	v_mfma_f32_16x16x32_bf16 v[76:79], v[178:181], v[246:249], v[76:79]
	v_mfma_f32_16x16x32_bf16 v[72:75], v[200:203], v[246:249], v[72:75]
	v_mfma_f32_16x16x32_bf16 v[68:71], v[204:207], v[246:249], v[68:71]
	s_waitcnt vmcnt(7)
	ds_write_b128 v252, v[136:139]
	v_mfma_f32_16x16x32_bf16 v[64:67], v[208:211], v[246:249], v[64:67]
	ds_read_b128 v[242:245], v176 offset:13824
	s_waitcnt lgkmcnt(4)
	v_mfma_f32_16x16x32_bf16 v[60:63], v[178:181], v[212:215], v[60:63]
	v_lshl_add_u64 v[136:137], s[6:7], 0, v[164:165]
	s_nop 0
	global_load_dwordx4 v[136:139], v[136:137], off offset:256
	v_mfma_f32_16x16x32_bf16 v[56:59], v[200:203], v[212:215], v[56:59]
	v_mfma_f32_16x16x32_bf16 v[52:55], v[204:207], v[212:215], v[52:55]
	v_mfma_f32_16x16x32_bf16 v[48:51], v[208:211], v[212:215], v[48:51]
	ds_read_b128 v[246:249], v176 offset:16128
	s_waitcnt lgkmcnt(3)
	v_mfma_f32_16x16x32_bf16 v[44:47], v[178:181], v[216:219], v[44:47]
	s_waitcnt vmcnt(7)
	ds_write_b128 v253, v[140:143]
	v_mfma_f32_16x16x32_bf16 v[40:43], v[200:203], v[216:219], v[40:43]
	v_mfma_f32_16x16x32_bf16 v[36:39], v[204:207], v[216:219], v[36:39]
	v_lshl_add_u64 v[140:141], s[6:7], 0, v[166:167]
	s_nop 0
	global_load_dwordx4 v[140:143], v[140:141], off offset:256
	v_mfma_f32_16x16x32_bf16 v[32:35], v[208:211], v[216:219], v[32:35]
	ds_read_b128 v[212:215], v176 offset:64
	s_waitcnt lgkmcnt(3)
	v_mfma_f32_16x16x32_bf16 v[28:31], v[178:181], v[242:245], v[28:31]
	v_mfma_f32_16x16x32_bf16 v[24:27], v[200:203], v[242:245], v[24:27]
	v_mfma_f32_16x16x32_bf16 v[20:23], v[204:207], v[242:245], v[20:23]
	s_waitcnt vmcnt(7)
	ds_write_b128 v250, v[144:147] offset:36864
	v_mfma_f32_16x16x32_bf16 v[16:19], v[208:211], v[242:245], v[16:19]
	ds_read_b128 v[216:219], v176 offset:2368
	s_waitcnt lgkmcnt(4)
	v_mfma_f32_16x16x32_bf16 v[12:15], v[178:181], v[246:249], v[12:15]
	ds_read_b128 v[178:181], v182 offset:36928
	s_add_u32 s6, s2, s33
	s_addc_u32 s7, s3, 0
	v_lshl_add_u64 v[144:145], s[6:7], 0, v[160:161]
	s_nop 0
	global_load_dwordx4 v[144:147], v[144:145], off offset:256
	v_mfma_f32_16x16x32_bf16 v[8:11], v[200:203], v[246:249], v[8:11]
	ds_read_b128 v[200:203], v182 offset:39232
	v_mfma_f32_16x16x32_bf16 v[0:3], v[204:207], v[246:249], v[0:3]
	ds_read_b128 v[204:207], v182 offset:41536
	v_mfma_f32_16x16x32_bf16 v[4:7], v[208:211], v[246:249], v[4:7]
	ds_read_b128 v[208:211], v182 offset:43840
	ds_read_b128 v[242:245], v176 offset:4672
	s_waitcnt lgkmcnt(4)
	v_mfma_f32_16x16x32_bf16 v[124:127], v[178:181], v[212:215], v[124:127]
	s_waitcnt vmcnt(7)
	ds_write_b128 v251, v[148:151] offset:36864
	s_waitcnt lgkmcnt(4)
	v_mfma_f32_16x16x32_bf16 v[120:123], v[200:203], v[212:215], v[120:123]
	s_waitcnt lgkmcnt(3)
	v_mfma_f32_16x16x32_bf16 v[116:119], v[204:207], v[212:215], v[116:119]
	v_lshl_add_u64 v[148:149], s[6:7], 0, v[162:163]
	s_nop 0
	global_load_dwordx4 v[148:151], v[148:149], off offset:256
	s_waitcnt lgkmcnt(2)
	v_mfma_f32_16x16x32_bf16 v[112:115], v[208:211], v[212:215], v[112:115]
	ds_read_b128 v[246:249], v176 offset:6976
	v_mfma_f32_16x16x32_bf16 v[108:111], v[178:181], v[216:219], v[108:111]
	v_mfma_f32_16x16x32_bf16 v[104:107], v[200:203], v[216:219], v[104:107]
	v_mfma_f32_16x16x32_bf16 v[100:103], v[204:207], v[216:219], v[100:103]
	s_waitcnt vmcnt(7)
	ds_write_b128 v252, v[152:155] offset:36864
	v_mfma_f32_16x16x32_bf16 v[96:99], v[208:211], v[216:219], v[96:99]
	ds_read_b128 v[212:215], v176 offset:9280
	s_waitcnt lgkmcnt(4)
	v_mfma_f32_16x16x32_bf16 v[92:95], v[178:181], v[242:245], v[92:95]
	v_lshl_add_u64 v[152:153], s[6:7], 0, v[164:165]
	s_nop 0
	global_load_dwordx4 v[152:155], v[152:153], off offset:256
	v_mfma_f32_16x16x32_bf16 v[88:91], v[200:203], v[242:245], v[88:91]
	v_mfma_f32_16x16x32_bf16 v[84:87], v[204:207], v[242:245], v[84:87]
	v_mfma_f32_16x16x32_bf16 v[80:83], v[208:211], v[242:245], v[80:83]
	ds_read_b128 v[216:219], v176 offset:11584
	s_waitcnt lgkmcnt(3)
	v_mfma_f32_16x16x32_bf16 v[76:79], v[178:181], v[246:249], v[76:79]
	s_waitcnt vmcnt(7)
	ds_write_b128 v253, v[156:159] offset:36864
	v_mfma_f32_16x16x32_bf16 v[72:75], v[200:203], v[246:249], v[72:75]
	v_mfma_f32_16x16x32_bf16 v[68:71], v[204:207], v[246:249], v[68:71]
	v_lshl_add_u64 v[156:157], s[6:7], 0, v[166:167]
	s_nop 0
	global_load_dwordx4 v[156:159], v[156:157], off offset:256
	v_mfma_f32_16x16x32_bf16 v[64:67], v[208:211], v[246:249], v[64:67]
	ds_read_b128 v[242:245], v176 offset:13888
	s_waitcnt lgkmcnt(3)
	v_mfma_f32_16x16x32_bf16 v[60:63], v[178:181], v[212:215], v[60:63]
	v_mfma_f32_16x16x32_bf16 v[56:59], v[200:203], v[212:215], v[56:59]
	v_mfma_f32_16x16x32_bf16 v[52:55], v[204:207], v[212:215], v[52:55]
	v_mfma_f32_16x16x32_bf16 v[48:51], v[208:211], v[212:215], v[48:51]
	ds_read_b128 v[246:249], v176 offset:16192
	s_waitcnt lgkmcnt(3)
	v_mfma_f32_16x16x32_bf16 v[44:47], v[178:181], v[216:219], v[44:47]
	v_mfma_f32_16x16x32_bf16 v[40:43], v[200:203], v[216:219], v[40:43]
	v_mfma_f32_16x16x32_bf16 v[36:39], v[204:207], v[216:219], v[36:39]
	v_mfma_f32_16x16x32_bf16 v[32:35], v[208:211], v[216:219], v[32:35]
	s_add_i32 s4, s4, 1
	s_and_b32 s98, s4, 1
	s_mul_i32 s98, s98, 0x12000
	v_add3_u32 v182, s98, v168, v172
	v_add3_u32 v176, s98, v170, v172
	s_cmp_lg_u32 s4, 16
	s_waitcnt lgkmcnt(0)
	s_barrier
; DI f32x4 mfma16(bf16x8 a, bf16x8 b, f32x4 c) { return __builtin_amdgcn_mfma_f32_16x16x32_bf16(a, b, c, 0, 0, 0); }
; template <int MI, int NJ, bool SWAP, class AP, class BP>
; DI void gemm_main(f32x4 (&acc)[MI][NJ], const AP& ap, int a_kstep, const BP& bp, int b_kstep, int nk, bf16_t* smem) {
;     ...
;   for (int kt = 0; kt < nk; ++kt) {
;     const int buf = kt & 1;
;     sstore(buf ^ 1);
;     gload(kt + 2 < nk ? kt + 2 : nk - 1);
;     __builtin_amdgcn_sched_barrier(0);
;     const bf16_t* As = smem + buf * L::STAGE + (wm * 16 * MI + l15) * LDT + quad * 8;
;     const bf16_t* Bs = smem + buf * L::STAGE + L::A_ELEMS + (wn * 16 * NJ + l15) * LDT + quad * 8;
; #pragma unroll
;     for (int ks = 0; ks < 2; ++ks) {
;       if (MI * NJ >= 32 && ks == 1) asm volatile("" ::: "memory");
;       bf16x8 b[NJ];
; #pragma unroll
;       for (int j = 0; j < NJ; ++j) b[j] = *(const bf16x8*)(Bs + j * 16 * LDT + ks * 32);
; #pragma unroll
;       for (int i = 0; i < MI; ++i) {
;         const bf16x8 a = *(const bf16x8*)(As + i * 16 * LDT + ks * 32);
; #pragma unroll
;         for (int j = 0; j < NJ; ++j) acc[i][j] = SWAP ? mfma16(b[j], a, acc[i][j]) : mfma16(a, b[j], acc[i][j]);
;       }
;     }
;     __syncthreads();
;   }
	s_cbranch_scc0 .Lgm0_exit
	ds_read_b128 v[212:215], v176
	ds_read_b128 v[216:219], v176 offset:2304
	v_mfma_f32_16x16x32_bf16 v[28:31], v[178:181], v[242:245], v[28:31]
	v_mfma_f32_16x16x32_bf16 v[12:15], v[178:181], v[246:249], v[12:15]
	ds_read_b128 v[178:181], v182 offset:36864
	v_mfma_f32_16x16x32_bf16 v[24:27], v[200:203], v[242:245], v[24:27]
	v_mfma_f32_16x16x32_bf16 v[8:11], v[200:203], v[246:249], v[8:11]
	ds_read_b128 v[200:203], v182 offset:39168
	v_mfma_f32_16x16x32_bf16 v[20:23], v[204:207], v[242:245], v[20:23]
	v_mfma_f32_16x16x32_bf16 v[0:3], v[204:207], v[246:249], v[0:3]
	ds_read_b128 v[204:207], v182 offset:41472
	v_mfma_f32_16x16x32_bf16 v[16:19], v[208:211], v[242:245], v[16:19]
	v_mfma_f32_16x16x32_bf16 v[4:7], v[208:211], v[246:249], v[4:7]
	ds_read_b128 v[208:211], v182 offset:43776
	s_branch .Lgm0_main

; DI f32x4 mfma16(bf16x8 a, bf16x8 b, f32x4 c) { return __builtin_amdgcn_mfma_f32_16x16x32_bf16(a, b, c, 0, 0, 0); }
; template <int MI, int NJ, bool SWAP, class AP, class BP>
; DI void gemm_main(f32x4 (&acc)[MI][NJ], const AP& ap, int a_kstep, const BP& bp, int b_kstep, int nk, bf16_t* smem) {
;     ...
;   for (int kt = 0; kt < nk; ++kt) {
;     const int buf = kt & 1;
;     sstore(buf ^ 1);
;     gload(kt + 2 < nk ? kt + 2 : nk - 1);
;     __builtin_amdgcn_sched_barrier(0);
;     const bf16_t* As = smem + buf * L::STAGE + (wm * 16 * MI + l15) * LDT + quad * 8;
;     const bf16_t* Bs = smem + buf * L::STAGE + L::A_ELEMS + (wn * 16 * NJ + l15) * LDT + quad * 8;
; #pragma unroll
;     for (int ks = 0; ks < 2; ++ks) {
;       if (MI * NJ >= 32 && ks == 1) asm volatile("" ::: "memory");
;       bf16x8 b[NJ];
; #pragma unroll
;       for (int j = 0; j < NJ; ++j) b[j] = *(const bf16x8*)(Bs + j * 16 * LDT + ks * 32);
; #pragma unroll
;       for (int i = 0; i < MI; ++i) {
;         const bf16x8 a = *(const bf16x8*)(As + i * 16 * LDT + ks * 32);
; #pragma unroll
;         for (int j = 0; j < NJ; ++j) acc[i][j] = SWAP ? mfma16(b[j], a, acc[i][j]) : mfma16(a, b[j], acc[i][j]);
;       }
;     }
;     __syncthreads();
;   }
.Lgm1_main:
	ds_read_b128 v[242:245], v176 offset:4608
	s_waitcnt lgkmcnt(4)
	v_mfma_f32_16x16x32_bf16 v[124:127], v[212:215], v[178:181], v[124:127]
	s_waitcnt lgkmcnt(3)
	v_mfma_f32_16x16x32_bf16 v[120:123], v[212:215], v[200:203], v[120:123]
	s_waitcnt lgkmcnt(2)
	v_mfma_f32_16x16x32_bf16 v[116:119], v[212:215], v[204:207], v[116:119]
	v_lshlrev_b32_e32 v250, 1, v168
	s_and_b32 s5, s4, 1
	s_min_u32 s6, s4, 13
	s_xor_b32 s7, s5, 1
	s_mul_i32 s7, s7, 0x12000
	v_add3_u32 v250, s7, v250, v170
	s_waitcnt vmcnt(7)
	ds_write_b128 v250, v[128:131]
	s_waitcnt lgkmcnt(2)
	v_mfma_f32_16x16x32_bf16 v[112:115], v[212:215], v[208:211], v[112:115]
	ds_read_b128 v[246:249], v176 offset:6912
	v_mfma_f32_16x16x32_bf16 v[108:111], v[216:219], v[178:181], v[108:111]
	s_lshl_b32 s33, s6, 7
	s_add_u32 s6, s0, s33
	v_lshlrev_b32_e32 v251, 1, v171
	v_add3_u32 v251, s7, v251, v170
	v_lshlrev_b32_e32 v252, 1, v172
	v_add3_u32 v252, s7, v252, v170
	v_lshlrev_b32_e32 v253, 1, v173
	v_add3_u32 v253, s7, v253, v170
	s_addc_u32 s7, s1, 0
	v_lshl_add_u64 v[128:129], s[6:7], 0, v[160:161]
	s_nop 0
	global_load_dwordx4 v[128:131], v[128:129], off offset:256
	v_mfma_f32_16x16x32_bf16 v[104:107], v[216:219], v[200:203], v[104:107]
	v_mfma_f32_16x16x32_bf16 v[100:103], v[216:219], v[204:207], v[100:103]
	v_mfma_f32_16x16x32_bf16 v[96:99], v[216:219], v[208:211], v[96:99]
	ds_read_b128 v[212:215], v176 offset:9216
	s_waitcnt lgkmcnt(3)
	v_mfma_f32_16x16x32_bf16 v[92:95], v[242:245], v[178:181], v[92:95]
	s_waitcnt vmcnt(7)
	ds_write_b128 v251, v[132:135]
	v_mfma_f32_16x16x32_bf16 v[88:91], v[242:245], v[200:203], v[88:91]
	v_mfma_f32_16x16x32_bf16 v[84:87], v[242:245], v[204:207], v[84:87]
	v_lshl_add_u64 v[132:133], s[6:7], 0, v[162:163]
	s_nop 0
	global_load_dwordx4 v[132:135], v[132:133], off offset:256
	v_mfma_f32_16x16x32_bf16 v[80:83], v[242:245], v[208:211], v[80:83]
	ds_read_b128 v[216:219], v176 offset:11520
	s_waitcnt lgkmcnt(3)
	v_mfma_f32_16x16x32_bf16 v[76:79], v[246:249], v[178:181], v[76:79]
	v_mfma_f32_16x16x32_bf16 v[72:75], v[246:249], v[200:203], v[72:75]
	v_mfma_f32_16x16x32_bf16 v[68:71], v[246:249], v[204:207], v[68:71]
	s_waitcnt vmcnt(7)
	ds_write_b128 v252, v[136:139]
	v_mfma_f32_16x16x32_bf16 v[64:67], v[246:249], v[208:211], v[64:67]
	ds_read_b128 v[242:245], v176 offset:13824
	s_waitcnt lgkmcnt(4)
	v_mfma_f32_16x16x32_bf16 v[60:63], v[212:215], v[178:181], v[60:63]
	v_lshl_add_u64 v[136:137], s[6:7], 0, v[164:165]
	s_nop 0
	global_load_dwordx4 v[136:139], v[136:137], off offset:256
	v_mfma_f32_16x16x32_bf16 v[56:59], v[212:215], v[200:203], v[56:59]
	v_mfma_f32_16x16x32_bf16 v[52:55], v[212:215], v[204:207], v[52:55]
	v_mfma_f32_16x16x32_bf16 v[48:51], v[212:215], v[208:211], v[48:51]
	ds_read_b128 v[246:249], v176 offset:16128
	s_waitcnt lgkmcnt(3)
	v_mfma_f32_16x16x32_bf16 v[44:47], v[216:219], v[178:181], v[44:47]
	s_waitcnt vmcnt(7)
	ds_write_b128 v253, v[140:143]
	v_mfma_f32_16x16x32_bf16 v[40:43], v[216:219], v[200:203], v[40:43]
	v_mfma_f32_16x16x32_bf16 v[36:39], v[216:219], v[204:207], v[36:39]
	v_lshl_add_u64 v[140:141], s[6:7], 0, v[166:167]
	s_nop 0
	global_load_dwordx4 v[140:143], v[140:141], off offset:256
	v_mfma_f32_16x16x32_bf16 v[32:35], v[216:219], v[208:211], v[32:35]
	ds_read_b128 v[212:215], v176 offset:64
	s_waitcnt lgkmcnt(3)
	v_mfma_f32_16x16x32_bf16 v[28:31], v[242:245], v[178:181], v[28:31]
	v_mfma_f32_16x16x32_bf16 v[24:27], v[242:245], v[200:203], v[24:27]
	v_mfma_f32_16x16x32_bf16 v[20:23], v[242:245], v[204:207], v[20:23]
	s_waitcnt vmcnt(7)
	ds_write_b128 v250, v[144:147] offset:36864
	v_mfma_f32_16x16x32_bf16 v[16:19], v[242:245], v[208:211], v[16:19]
	ds_read_b128 v[216:219], v176 offset:2368
	s_waitcnt lgkmcnt(4)
; DI f32x4 mfma16(bf16x8 a, bf16x8 b, f32x4 c) { return __builtin_amdgcn_mfma_f32_16x16x32_bf16(a, b, c, 0, 0, 0); }
; template <int MI, int NJ, bool SWAP, class AP, class BP>
; DI void gemm_main(f32x4 (&acc)[MI][NJ], const AP& ap, int a_kstep, const BP& bp, int b_kstep, int nk, bf16_t* smem) {
;     ...
;   for (int kt = 0; kt < nk; ++kt) {
;     const int buf = kt & 1;
;     sstore(buf ^ 1);
;     gload(kt + 2 < nk ? kt + 2 : nk - 1);
;     __builtin_amdgcn_sched_barrier(0);
;     const bf16_t* As = smem + buf * L::STAGE + (wm * 16 * MI + l15) * LDT + quad * 8;
;     const bf16_t* Bs = smem + buf * L::STAGE + L::A_ELEMS + (wn * 16 * NJ + l15) * LDT + quad * 8;
; #pragma unroll
;     for (int ks = 0; ks < 2; ++ks) {
;       if (MI * NJ >= 32 && ks == 1) asm volatile("" ::: "memory");
;       bf16x8 b[NJ];
; #pragma unroll
;       for (int j = 0; j < NJ; ++j) b[j] = *(const bf16x8*)(Bs + j * 16 * LDT + ks * 32);
; #pragma unroll
;       for (int i = 0; i < MI; ++i) {
;         const bf16x8 a = *(const bf16x8*)(As + i * 16 * LDT + ks * 32);
; #pragma unroll
;         for (int j = 0; j < NJ; ++j) acc[i][j] = SWAP ? mfma16(b[j], a, acc[i][j]) : mfma16(a, b[j], acc[i][j]);
;       }
;     }
;     __syncthreads();
;   }
	v_mfma_f32_16x16x32_bf16 v[8:11], v[246:249], v[178:181], v[8:11]
	ds_read_b128 v[178:181], v182 offset:36928
	s_add_u32 s6, s2, s33
	s_addc_u32 s7, s3, 0
	v_lshl_add_u64 v[144:145], s[6:7], 0, v[160:161]
	s_nop 0
	global_load_dwordx4 v[144:147], v[144:145], off offset:256
	v_mfma_f32_16x16x32_bf16 v[4:7], v[246:249], v[200:203], v[4:7]
	ds_read_b128 v[200:203], v182 offset:39232
	v_mfma_f32_16x16x32_bf16 v[0:3], v[246:249], v[204:207], v[0:3]
	ds_read_b128 v[204:207], v182 offset:41536
	v_mfma_f32_16x16x32_bf16 v[12:15], v[246:249], v[208:211], v[12:15]
	ds_read_b128 v[208:211], v182 offset:43840
	ds_read_b128 v[242:245], v176 offset:4672
	s_waitcnt lgkmcnt(4)
	v_mfma_f32_16x16x32_bf16 v[124:127], v[212:215], v[178:181], v[124:127]
	s_waitcnt vmcnt(7)
	ds_write_b128 v251, v[148:151] offset:36864
	s_waitcnt lgkmcnt(4)
	v_mfma_f32_16x16x32_bf16 v[120:123], v[212:215], v[200:203], v[120:123]
	s_waitcnt lgkmcnt(3)
	v_mfma_f32_16x16x32_bf16 v[116:119], v[212:215], v[204:207], v[116:119]
	v_lshl_add_u64 v[148:149], s[6:7], 0, v[162:163]
	s_nop 0
	global_load_dwordx4 v[148:151], v[148:149], off offset:256
	s_waitcnt lgkmcnt(2)
	v_mfma_f32_16x16x32_bf16 v[112:115], v[212:215], v[208:211], v[112:115]
	ds_read_b128 v[246:249], v176 offset:6976
	v_mfma_f32_16x16x32_bf16 v[108:111], v[216:219], v[178:181], v[108:111]
	v_mfma_f32_16x16x32_bf16 v[104:107], v[216:219], v[200:203], v[104:107]
	v_mfma_f32_16x16x32_bf16 v[100:103], v[216:219], v[204:207], v[100:103]
	s_waitcnt vmcnt(7)
	ds_write_b128 v252, v[152:155] offset:36864
	v_mfma_f32_16x16x32_bf16 v[96:99], v[216:219], v[208:211], v[96:99]
	ds_read_b128 v[212:215], v176 offset:9280
	s_waitcnt lgkmcnt(4)
	v_mfma_f32_16x16x32_bf16 v[92:95], v[242:245], v[178:181], v[92:95]
	v_lshl_add_u64 v[152:153], s[6:7], 0, v[164:165]
	s_nop 0
	global_load_dwordx4 v[152:155], v[152:153], off offset:256
	v_mfma_f32_16x16x32_bf16 v[88:91], v[242:245], v[200:203], v[88:91]
	v_mfma_f32_16x16x32_bf16 v[84:87], v[242:245], v[204:207], v[84:87]
	v_mfma_f32_16x16x32_bf16 v[80:83], v[242:245], v[208:211], v[80:83]
	ds_read_b128 v[216:219], v176 offset:11584
	s_waitcnt lgkmcnt(3)
	v_mfma_f32_16x16x32_bf16 v[76:79], v[246:249], v[178:181], v[76:79]
	s_waitcnt vmcnt(7)
	ds_write_b128 v253, v[156:159] offset:36864
	v_mfma_f32_16x16x32_bf16 v[72:75], v[246:249], v[200:203], v[72:75]
	v_mfma_f32_16x16x32_bf16 v[68:71], v[246:249], v[204:207], v[68:71]
	v_lshl_add_u64 v[156:157], s[6:7], 0, v[166:167]
	s_nop 0
	global_load_dwordx4 v[156:159], v[156:157], off offset:256
	v_mfma_f32_16x16x32_bf16 v[64:67], v[246:249], v[208:211], v[64:67]
	ds_read_b128 v[242:245], v176 offset:13888
	s_waitcnt lgkmcnt(3)
	v_mfma_f32_16x16x32_bf16 v[60:63], v[212:215], v[178:181], v[60:63]
	v_mfma_f32_16x16x32_bf16 v[56:59], v[212:215], v[200:203], v[56:59]
	v_mfma_f32_16x16x32_bf16 v[52:55], v[212:215], v[204:207], v[52:55]
	v_mfma_f32_16x16x32_bf16 v[48:51], v[212:215], v[208:211], v[48:51]
	ds_read_b128 v[246:249], v176 offset:16192
	s_waitcnt lgkmcnt(3)
	v_mfma_f32_16x16x32_bf16 v[44:47], v[216:219], v[178:181], v[44:47]
	v_mfma_f32_16x16x32_bf16 v[40:43], v[216:219], v[200:203], v[40:43]
	v_mfma_f32_16x16x32_bf16 v[36:39], v[216:219], v[204:207], v[36:39]
	v_mfma_f32_16x16x32_bf16 v[32:35], v[216:219], v[208:211], v[32:35]
	s_add_i32 s4, s4, 1
	s_and_b32 s98, s4, 1
	s_mul_i32 s98, s98, 0x12000
	v_add3_u32 v176, s98, v174, v175
	v_add3_u32 v182, s98, v169, v175
	s_cmp_lg_u32 s4, 16
	s_waitcnt lgkmcnt(0)
	s_barrier
	s_cbranch_scc0 .Lgm1_exit
	ds_read_b128 v[212:215], v176
	ds_read_b128 v[216:219], v176 offset:2304
	v_mfma_f32_16x16x32_bf16 v[28:31], v[242:245], v[178:181], v[28:31]
	v_mfma_f32_16x16x32_bf16 v[8:11], v[246:249], v[178:181], v[8:11]
	ds_read_b128 v[178:181], v182 offset:36864
	v_mfma_f32_16x16x32_bf16 v[24:27], v[242:245], v[200:203], v[24:27]
	v_mfma_f32_16x16x32_bf16 v[4:7], v[246:249], v[200:203], v[4:7]
	ds_read_b128 v[200:203], v182 offset:39168
	v_mfma_f32_16x16x32_bf16 v[20:23], v[242:245], v[204:207], v[20:23]
	v_mfma_f32_16x16x32_bf16 v[0:3], v[246:249], v[204:207], v[0:3]
	ds_read_b128 v[204:207], v182 offset:41472
	v_mfma_f32_16x16x32_bf16 v[16:19], v[242:245], v[208:211], v[16:19]
	v_mfma_f32_16x16x32_bf16 v[12:15], v[246:249], v[208:211], v[12:15]
	ds_read_b128 v[208:211], v182 offset:43776
	s_branch .Lgm1_main

; DI f32x4 mfma16(bf16x8 a, bf16x8 b, f32x4 c) { return __builtin_amdgcn_mfma_f32_16x16x32_bf16(a, b, c, 0, 0, 0); }
; template <int MI, int NJ, bool SWAP, class AP, class BP>
; DI void gemm_main(f32x4 (&acc)[MI][NJ], const AP& ap, int a_kstep, const BP& bp, int b_kstep, int nk, bf16_t* smem) {
;     ...
;   for (int kt = 0; kt < nk; ++kt) {
;     const int buf = kt & 1;
;     sstore(buf ^ 1);
;     gload(kt + 2 < nk ? kt + 2 : nk - 1);
;     __builtin_amdgcn_sched_barrier(0);
;     const bf16_t* As = smem + buf * L::STAGE + (wm * 16 * MI + l15) * LDT + quad * 8;
;     const bf16_t* Bs = smem + buf * L::STAGE + L::A_ELEMS + (wn * 16 * NJ + l15) * LDT + quad * 8;
; #pragma unroll
;     for (int ks = 0; ks < 2; ++ks) {
;       if (MI * NJ >= 32 && ks == 1) asm volatile("" ::: "memory");
;       bf16x8 b[NJ];
; #pragma unroll
;       for (int j = 0; j < NJ; ++j) b[j] = *(const bf16x8*)(Bs + j * 16 * LDT + ks * 32);
; #pragma unroll
;       for (int i = 0; i < MI; ++i) {
;         const bf16x8 a = *(const bf16x8*)(As + i * 16 * LDT + ks * 32);
; #pragma unroll
;         for (int j = 0; j < NJ; ++j) acc[i][j] = SWAP ? mfma16(b[j], a, acc[i][j]) : mfma16(a, b[j], acc[i][j]);
;       }
;     }
;     __syncthreads();
;   }
.Lgm2_main:
	ds_read_b128 v[242:245], v182 offset:4608
	s_waitcnt lgkmcnt(4)
	v_mfma_f32_16x16x32_bf16 v[156:159], v[178:181], v[198:201], v[156:159]
	s_waitcnt lgkmcnt(3)
	v_mfma_f32_16x16x32_bf16 v[152:155], v[186:189], v[198:201], v[152:155]
	s_waitcnt lgkmcnt(2)
	v_mfma_f32_16x16x32_bf16 v[148:151], v[190:193], v[198:201], v[148:151]
	s_and_b32 s33, s16, 1
	s_min_u32 s52, s16, 3
	s_xor_b32 s53, s33, 1
	s_mul_i32 s53, s53, 0x12000
	v_add3_u32 v250, s53, v173, v171
	s_waitcnt vmcnt(7)
	ds_write_b128 v250, v[112:115]
	s_waitcnt lgkmcnt(2)
	v_mfma_f32_16x16x32_bf16 v[144:147], v[194:197], v[198:201], v[144:147]
	ds_read_b128 v[246:249], v182 offset:6912
	v_mfma_f32_16x16x32_bf16 v[108:111], v[178:181], v[202:205], v[108:111]
	s_lshl_b32 s54, s52, 7
	s_add_u32 s52, s0, s54
	v_add3_u32 v251, s53, v174, v171
	v_add3_u32 v252, s53, v175, v171
	v_add3_u32 v253, s53, v176, v171
	s_addc_u32 s53, s1, 0
	v_lshl_add_u64 v[112:113], s[52:53], 0, v[162:163]
	s_nop 0
	global_load_dwordx4 v[112:115], v[112:113], off offset:256
	v_mfma_f32_16x16x32_bf16 v[104:107], v[186:189], v[202:205], v[104:107]
	v_mfma_f32_16x16x32_bf16 v[100:103], v[190:193], v[202:205], v[100:103]
	v_mfma_f32_16x16x32_bf16 v[96:99], v[194:197], v[202:205], v[96:99]
	ds_read_b128 v[198:201], v182 offset:9216
	s_waitcnt lgkmcnt(3)
	v_mfma_f32_16x16x32_bf16 v[92:95], v[178:181], v[242:245], v[92:95]
	s_waitcnt vmcnt(6)
	ds_write_b128 v251, v[116:119]
	v_mfma_f32_16x16x32_bf16 v[88:91], v[186:189], v[242:245], v[88:91]
	v_mfma_f32_16x16x32_bf16 v[84:87], v[190:193], v[242:245], v[84:87]
	v_lshl_add_u64 v[116:117], s[52:53], 0, v[164:165]
	s_nop 0
	global_load_dwordx4 v[116:119], v[116:117], off offset:256
	v_mfma_f32_16x16x32_bf16 v[80:83], v[194:197], v[242:245], v[80:83]
	ds_read_b128 v[202:205], v182 offset:11520
	s_waitcnt lgkmcnt(3)
	v_mfma_f32_16x16x32_bf16 v[76:79], v[178:181], v[246:249], v[76:79]
	v_mfma_f32_16x16x32_bf16 v[72:75], v[186:189], v[246:249], v[72:75]
	v_mfma_f32_16x16x32_bf16 v[68:71], v[190:193], v[246:249], v[68:71]
	s_waitcnt vmcnt(6)
	ds_write_b128 v252, v[120:123]
	v_mfma_f32_16x16x32_bf16 v[64:67], v[194:197], v[246:249], v[64:67]
	ds_read_b128 v[242:245], v182 offset:13824
	s_waitcnt lgkmcnt(4)
	v_mfma_f32_16x16x32_bf16 v[60:63], v[178:181], v[198:201], v[60:63]
	v_lshl_add_u64 v[120:121], s[52:53], 0, v[166:167]
	s_nop 0
	global_load_dwordx4 v[120:123], v[120:121], off offset:256
	v_mfma_f32_16x16x32_bf16 v[56:59], v[186:189], v[198:201], v[56:59]
	v_mfma_f32_16x16x32_bf16 v[52:55], v[190:193], v[198:201], v[52:55]
	v_mfma_f32_16x16x32_bf16 v[48:51], v[194:197], v[198:201], v[48:51]
	ds_read_b128 v[246:249], v182 offset:16128
	s_waitcnt lgkmcnt(3)
	v_mfma_f32_16x16x32_bf16 v[44:47], v[178:181], v[202:205], v[44:47]
	s_waitcnt vmcnt(6)
	ds_write_b128 v253, v[124:127]
	v_mfma_f32_16x16x32_bf16 v[40:43], v[186:189], v[202:205], v[40:43]
	v_mfma_f32_16x16x32_bf16 v[36:39], v[190:193], v[202:205], v[36:39]
	v_lshl_add_u64 v[124:125], s[52:53], 0, v[168:169]
	s_nop 0
	global_load_dwordx4 v[124:127], v[124:125], off offset:256
	v_mfma_f32_16x16x32_bf16 v[32:35], v[194:197], v[202:205], v[32:35]
	ds_read_b128 v[198:201], v182 offset:64
	s_waitcnt lgkmcnt(3)
	v_mfma_f32_16x16x32_bf16 v[28:31], v[178:181], v[242:245], v[28:31]
	v_mfma_f32_16x16x32_bf16 v[24:27], v[186:189], v[242:245], v[24:27]
	v_mfma_f32_16x16x32_bf16 v[20:23], v[190:193], v[242:245], v[20:23]
	ds_write_b128 v250, v[128:131] offset:36864
	v_mfma_f32_16x16x32_bf16 v[16:19], v[194:197], v[242:245], v[16:19]
	ds_read_b128 v[202:205], v182 offset:2368
	s_waitcnt lgkmcnt(4)
	v_mfma_f32_16x16x32_bf16 v[8:11], v[178:181], v[246:249], v[8:11]
	ds_read_b128 v[178:181], v183 offset:36928
	s_add_u32 s52, s2, s54
	s_addc_u32 s53, s3, 0
	v_lshl_add_u64 v[128:129], s[52:53], 0, v[162:163]
	s_nop 0
	global_load_dwordx4 v[128:131], v[128:129], off offset:256
	v_mfma_f32_16x16x32_bf16 v[4:7], v[186:189], v[246:249], v[4:7]
	ds_read_b128 v[186:189], v183 offset:39232
	v_mfma_f32_16x16x32_bf16 v[0:3], v[190:193], v[246:249], v[0:3]
	ds_read_b128 v[190:193], v183 offset:41536
	v_mfma_f32_16x16x32_bf16 v[12:15], v[194:197], v[246:249], v[12:15]
	ds_read_b128 v[194:197], v183 offset:43840
	ds_read_b128 v[242:245], v182 offset:4672
	s_waitcnt lgkmcnt(4)
; DI f32x4 mfma16(bf16x8 a, bf16x8 b, f32x4 c) { return __builtin_amdgcn_mfma_f32_16x16x32_bf16(a, b, c, 0, 0, 0); }
; template <int MI, int NJ, bool SWAP, class AP, class BP>
; DI void gemm_main(f32x4 (&acc)[MI][NJ], const AP& ap, int a_kstep, const BP& bp, int b_kstep, int nk, bf16_t* smem) {
;     ...
;   for (int kt = 0; kt < nk; ++kt) {
;     const int buf = kt & 1;
;     sstore(buf ^ 1);
;     gload(kt + 2 < nk ? kt + 2 : nk - 1);
;     __builtin_amdgcn_sched_barrier(0);
;     const bf16_t* As = smem + buf * L::STAGE + (wm * 16 * MI + l15) * LDT + quad * 8;
;     const bf16_t* Bs = smem + buf * L::STAGE + L::A_ELEMS + (wn * 16 * NJ + l15) * LDT + quad * 8;
; #pragma unroll
;     for (int ks = 0; ks < 2; ++ks) {
;       if (MI * NJ >= 32 && ks == 1) asm volatile("" ::: "memory");
;       bf16x8 b[NJ];
; #pragma unroll
;       for (int j = 0; j < NJ; ++j) b[j] = *(const bf16x8*)(Bs + j * 16 * LDT + ks * 32);
; #pragma unroll
;       for (int i = 0; i < MI; ++i) {
;         const bf16x8 a = *(const bf16x8*)(As + i * 16 * LDT + ks * 32);
; #pragma unroll
;         for (int j = 0; j < NJ; ++j) acc[i][j] = SWAP ? mfma16(b[j], a, acc[i][j]) : mfma16(a, b[j], acc[i][j]);
;       }
;     }
;     __syncthreads();
;   }
	v_mfma_f32_16x16x32_bf16 v[156:159], v[178:181], v[198:201], v[156:159]
	s_waitcnt vmcnt(7)
	ds_write_b128 v251, v[132:135] offset:36864
	s_waitcnt lgkmcnt(4)
	v_mfma_f32_16x16x32_bf16 v[152:155], v[186:189], v[198:201], v[152:155]
	s_waitcnt lgkmcnt(3)
	v_mfma_f32_16x16x32_bf16 v[148:151], v[190:193], v[198:201], v[148:151]
	v_lshl_add_u64 v[132:133], s[52:53], 0, v[164:165]
	s_nop 0
	global_load_dwordx4 v[132:135], v[132:133], off offset:256
	s_waitcnt lgkmcnt(2)
	v_mfma_f32_16x16x32_bf16 v[144:147], v[194:197], v[198:201], v[144:147]
	ds_read_b128 v[246:249], v182 offset:6976
	v_mfma_f32_16x16x32_bf16 v[108:111], v[178:181], v[202:205], v[108:111]
	v_mfma_f32_16x16x32_bf16 v[104:107], v[186:189], v[202:205], v[104:107]
	v_mfma_f32_16x16x32_bf16 v[100:103], v[190:193], v[202:205], v[100:103]
	s_waitcnt vmcnt(7)
	ds_write_b128 v252, v[136:139] offset:36864
	v_mfma_f32_16x16x32_bf16 v[96:99], v[194:197], v[202:205], v[96:99]
	ds_read_b128 v[198:201], v182 offset:9280
	s_waitcnt lgkmcnt(4)
	v_mfma_f32_16x16x32_bf16 v[92:95], v[178:181], v[242:245], v[92:95]
	v_lshl_add_u64 v[136:137], s[52:53], 0, v[166:167]
	s_nop 0
	global_load_dwordx4 v[136:139], v[136:137], off offset:256
	v_mfma_f32_16x16x32_bf16 v[88:91], v[186:189], v[242:245], v[88:91]
	v_mfma_f32_16x16x32_bf16 v[84:87], v[190:193], v[242:245], v[84:87]
	v_mfma_f32_16x16x32_bf16 v[80:83], v[194:197], v[242:245], v[80:83]
	ds_read_b128 v[202:205], v182 offset:11584
	s_waitcnt lgkmcnt(3)
	v_mfma_f32_16x16x32_bf16 v[76:79], v[178:181], v[246:249], v[76:79]
	s_waitcnt vmcnt(7)
	ds_write_b128 v253, v[140:143] offset:36864
	v_mfma_f32_16x16x32_bf16 v[72:75], v[186:189], v[246:249], v[72:75]
	v_mfma_f32_16x16x32_bf16 v[68:71], v[190:193], v[246:249], v[68:71]
	v_lshl_add_u64 v[140:141], s[52:53], 0, v[168:169]
	s_nop 0
	global_load_dwordx4 v[140:143], v[140:141], off offset:256
	v_mfma_f32_16x16x32_bf16 v[64:67], v[194:197], v[246:249], v[64:67]
	ds_read_b128 v[242:245], v182 offset:13888
	s_waitcnt lgkmcnt(3)
	v_mfma_f32_16x16x32_bf16 v[60:63], v[178:181], v[198:201], v[60:63]
	v_mfma_f32_16x16x32_bf16 v[56:59], v[186:189], v[198:201], v[56:59]
	v_mfma_f32_16x16x32_bf16 v[52:55], v[190:193], v[198:201], v[52:55]
	v_mfma_f32_16x16x32_bf16 v[48:51], v[194:197], v[198:201], v[48:51]
	ds_read_b128 v[246:249], v182 offset:16192
	s_waitcnt lgkmcnt(3)
	v_mfma_f32_16x16x32_bf16 v[44:47], v[178:181], v[202:205], v[44:47]
	v_mfma_f32_16x16x32_bf16 v[40:43], v[186:189], v[202:205], v[40:43]
	v_mfma_f32_16x16x32_bf16 v[36:39], v[190:193], v[202:205], v[36:39]
	v_mfma_f32_16x16x32_bf16 v[32:35], v[194:197], v[202:205], v[32:35]
	s_add_i32 s16, s16, 1
	s_and_b32 s98, s16, 1
	s_mul_i32 s98, s98, 0x12000
	v_add3_u32 v183, s98, v160, v177
	v_add3_u32 v182, s98, v172, v177
	s_cmp_lg_u32 s16, 6
	s_waitcnt lgkmcnt(0)
	s_barrier
	s_cbranch_scc0 .Lgm2_exit
	ds_read_b128 v[198:201], v182
	ds_read_b128 v[202:205], v182 offset:2304
	v_mfma_f32_16x16x32_bf16 v[28:31], v[178:181], v[242:245], v[28:31]
	v_mfma_f32_16x16x32_bf16 v[8:11], v[178:181], v[246:249], v[8:11]
	ds_read_b128 v[178:181], v183 offset:36864
	v_mfma_f32_16x16x32_bf16 v[24:27], v[186:189], v[242:245], v[24:27]
	v_mfma_f32_16x16x32_bf16 v[4:7], v[186:189], v[246:249], v[4:7]
	ds_read_b128 v[186:189], v183 offset:39168
	v_mfma_f32_16x16x32_bf16 v[20:23], v[190:193], v[242:245], v[20:23]
	v_mfma_f32_16x16x32_bf16 v[0:3], v[190:193], v[246:249], v[0:3]
	ds_read_b128 v[190:193], v183 offset:41472
	v_mfma_f32_16x16x32_bf16 v[16:19], v[194:197], v[242:245], v[16:19]
	v_mfma_f32_16x16x32_bf16 v[12:15], v[194:197], v[246:249], v[12:15]
	ds_read_b128 v[194:197], v183 offset:43776
	s_branch .Lgm2_main

; DI f32x4 mfma16(bf16x8 a, bf16x8 b, f32x4 c) { return __builtin_amdgcn_mfma_f32_16x16x32_bf16(a, b, c, 0, 0, 0); }
; template <int MI, int NJ, bool SWAP, class AP, class BP>
; DI void gemm_main(f32x4 (&acc)[MI][NJ], const AP& ap, int a_kstep, const BP& bp, int b_kstep, int nk, bf16_t* smem) {
;     ...
;   for (int kt = 0; kt < nk; ++kt) {
;     const int buf = kt & 1;
;     sstore(buf ^ 1);
;     gload(kt + 2 < nk ? kt + 2 : nk - 1);
;     __builtin_amdgcn_sched_barrier(0);
;     const bf16_t* As = smem + buf * L::STAGE + (wm * 16 * MI + l15) * LDT + quad * 8;
;     const bf16_t* Bs = smem + buf * L::STAGE + L::A_ELEMS + (wn * 16 * NJ + l15) * LDT + quad * 8;
; #pragma unroll
;     for (int ks = 0; ks < 2; ++ks) {
;       if (MI * NJ >= 32 && ks == 1) asm volatile("" ::: "memory");
;       bf16x8 b[NJ];
; #pragma unroll
;       for (int j = 0; j < NJ; ++j) b[j] = *(const bf16x8*)(Bs + j * 16 * LDT + ks * 32);
; #pragma unroll
;       for (int i = 0; i < MI; ++i) {
;         const bf16x8 a = *(const bf16x8*)(As + i * 16 * LDT + ks * 32);
; #pragma unroll
;         for (int j = 0; j < NJ; ++j) acc[i][j] = SWAP ? mfma16(b[j], a, acc[i][j]) : mfma16(a, b[j], acc[i][j]);
;       }
;     }
;     __syncthreads();
;   }
.Lgm3_main:
	ds_read_b128 v[242:245], v182 offset:4608
	s_waitcnt lgkmcnt(4)
	v_mfma_f32_16x16x32_bf16 v[156:159], v[178:181], v[198:201], v[156:159]
	s_waitcnt lgkmcnt(3)
	v_mfma_f32_16x16x32_bf16 v[152:155], v[186:189], v[198:201], v[152:155]
	s_waitcnt lgkmcnt(2)
	v_mfma_f32_16x16x32_bf16 v[148:151], v[190:193], v[198:201], v[148:151]
	v_lshlrev_b32_e32 v250, 1, v160
	s_and_b32 s54, s33, 1
	s_xor_b32 s52, s54, 1
	s_mul_i32 s52, s52, 0x12000
	v_add3_u32 v250, s52, v250, v172
	s_waitcnt vmcnt(7)
	ds_write_b128 v250, v[112:115]
	s_waitcnt lgkmcnt(2)
	v_mfma_f32_16x16x32_bf16 v[144:147], v[194:197], v[198:201], v[144:147]
	ds_read_b128 v[246:249], v182 offset:6912
	v_mfma_f32_16x16x32_bf16 v[108:111], v[178:181], v[202:205], v[108:111]
	s_cmp_eq_u32 s33, 0
	s_cselect_b32 s55, s48, 0x180
	v_lshlrev_b32_e32 v251, 1, v173
	v_add3_u32 v251, s52, v251, v172
	v_lshlrev_b32_e32 v252, 1, v174
	v_add3_u32 v252, s52, v252, v172
	v_lshlrev_b32_e32 v253, 1, v175
	v_add3_u32 v253, s52, v253, v172
	s_add_u32 s52, s0, s55
	s_addc_u32 s53, s1, 0
	v_lshl_add_u64 v[112:113], s[52:53], 0, v[162:163]
	s_nop 0
	global_load_dwordx4 v[112:115], v[112:113], off
	v_mfma_f32_16x16x32_bf16 v[104:107], v[186:189], v[202:205], v[104:107]
	v_mfma_f32_16x16x32_bf16 v[100:103], v[190:193], v[202:205], v[100:103]
	v_mfma_f32_16x16x32_bf16 v[96:99], v[194:197], v[202:205], v[96:99]
	ds_read_b128 v[198:201], v182 offset:9216
	s_waitcnt lgkmcnt(3)
	v_mfma_f32_16x16x32_bf16 v[92:95], v[178:181], v[242:245], v[92:95]
	s_waitcnt vmcnt(7)
	ds_write_b128 v251, v[116:119]
	v_mfma_f32_16x16x32_bf16 v[88:91], v[186:189], v[242:245], v[88:91]
	v_mfma_f32_16x16x32_bf16 v[84:87], v[190:193], v[242:245], v[84:87]
	v_lshl_add_u64 v[116:117], s[52:53], 0, v[164:165]
	s_nop 0
	global_load_dwordx4 v[116:119], v[116:117], off
	v_mfma_f32_16x16x32_bf16 v[80:83], v[194:197], v[242:245], v[80:83]
	ds_read_b128 v[202:205], v182 offset:11520
	s_waitcnt lgkmcnt(3)
	v_mfma_f32_16x16x32_bf16 v[76:79], v[178:181], v[246:249], v[76:79]
	v_mfma_f32_16x16x32_bf16 v[72:75], v[186:189], v[246:249], v[72:75]
	v_mfma_f32_16x16x32_bf16 v[68:71], v[190:193], v[246:249], v[68:71]
	s_waitcnt vmcnt(7)
	ds_write_b128 v252, v[120:123]
	v_mfma_f32_16x16x32_bf16 v[64:67], v[194:197], v[246:249], v[64:67]
	ds_read_b128 v[242:245], v182 offset:13824
	s_waitcnt lgkmcnt(4)
	v_mfma_f32_16x16x32_bf16 v[60:63], v[178:181], v[198:201], v[60:63]
	v_lshl_add_u64 v[120:121], s[52:53], 0, v[166:167]
	s_nop 0
	global_load_dwordx4 v[120:123], v[120:121], off
	v_mfma_f32_16x16x32_bf16 v[56:59], v[186:189], v[198:201], v[56:59]
	v_mfma_f32_16x16x32_bf16 v[52:55], v[190:193], v[198:201], v[52:55]
	v_mfma_f32_16x16x32_bf16 v[48:51], v[194:197], v[198:201], v[48:51]
	ds_read_b128 v[246:249], v182 offset:16128
	s_waitcnt lgkmcnt(3)
	v_mfma_f32_16x16x32_bf16 v[44:47], v[178:181], v[202:205], v[44:47]
	s_waitcnt vmcnt(7)
	ds_write_b128 v253, v[124:127]
	v_mfma_f32_16x16x32_bf16 v[40:43], v[186:189], v[202:205], v[40:43]
	v_mfma_f32_16x16x32_bf16 v[36:39], v[190:193], v[202:205], v[36:39]
	v_lshl_add_u64 v[124:125], s[52:53], 0, v[168:169]
	s_nop 0
	global_load_dwordx4 v[124:127], v[124:125], off
	v_mfma_f32_16x16x32_bf16 v[32:35], v[194:197], v[202:205], v[32:35]
	ds_read_b128 v[198:201], v182 offset:64
	s_waitcnt lgkmcnt(3)
	v_mfma_f32_16x16x32_bf16 v[28:31], v[178:181], v[242:245], v[28:31]
	v_mfma_f32_16x16x32_bf16 v[24:27], v[186:189], v[242:245], v[24:27]
	v_mfma_f32_16x16x32_bf16 v[20:23], v[190:193], v[242:245], v[20:23]
	s_waitcnt vmcnt(7)
	ds_write_b128 v250, v[128:131] offset:36864
	v_mfma_f32_16x16x32_bf16 v[16:19], v[194:197], v[242:245], v[16:19]
	ds_read_b128 v[202:205], v182 offset:2368
	s_waitcnt lgkmcnt(4)
; DI f32x4 mfma16(bf16x8 a, bf16x8 b, f32x4 c) { return __builtin_amdgcn_mfma_f32_16x16x32_bf16(a, b, c, 0, 0, 0); }
; template <int MI, int NJ, bool SWAP, class AP, class BP>
; DI void gemm_main(f32x4 (&acc)[MI][NJ], const AP& ap, int a_kstep, const BP& bp, int b_kstep, int nk, bf16_t* smem) {
;     ...
;   for (int kt = 0; kt < nk; ++kt) {
;     const int buf = kt & 1;
;     sstore(buf ^ 1);
;     gload(kt + 2 < nk ? kt + 2 : nk - 1);
;     __builtin_amdgcn_sched_barrier(0);
;     const bf16_t* As = smem + buf * L::STAGE + (wm * 16 * MI + l15) * LDT + quad * 8;
;     const bf16_t* Bs = smem + buf * L::STAGE + L::A_ELEMS + (wn * 16 * NJ + l15) * LDT + quad * 8;
; #pragma unroll
;     for (int ks = 0; ks < 2; ++ks) {
;       if (MI * NJ >= 32 && ks == 1) asm volatile("" ::: "memory");
;       bf16x8 b[NJ];
; #pragma unroll
;       for (int j = 0; j < NJ; ++j) b[j] = *(const bf16x8*)(Bs + j * 16 * LDT + ks * 32);
; #pragma unroll
;       for (int i = 0; i < MI; ++i) {
;         const bf16x8 a = *(const bf16x8*)(As + i * 16 * LDT + ks * 32);
; #pragma unroll
;         for (int j = 0; j < NJ; ++j) acc[i][j] = SWAP ? mfma16(b[j], a, acc[i][j]) : mfma16(a, b[j], acc[i][j]);
;       }
;     }
;     __syncthreads();
;   }
	v_mfma_f32_16x16x32_bf16 v[8:11], v[178:181], v[246:249], v[8:11]
	ds_read_b128 v[178:181], v183 offset:36928
	s_add_u32 s52, s2, s55
	s_addc_u32 s53, s3, 0
	v_lshl_add_u64 v[128:129], s[52:53], 0, v[162:163]
	s_nop 0
	global_load_dwordx4 v[128:131], v[128:129], off
	v_mfma_f32_16x16x32_bf16 v[4:7], v[186:189], v[246:249], v[4:7]
	ds_read_b128 v[186:189], v183 offset:39232
	v_mfma_f32_16x16x32_bf16 v[0:3], v[190:193], v[246:249], v[0:3]
	ds_read_b128 v[190:193], v183 offset:41536
	v_mfma_f32_16x16x32_bf16 v[12:15], v[194:197], v[246:249], v[12:15]
	ds_read_b128 v[194:197], v183 offset:43840
	ds_read_b128 v[242:245], v182 offset:4672
	s_waitcnt lgkmcnt(4)
	v_mfma_f32_16x16x32_bf16 v[156:159], v[178:181], v[198:201], v[156:159]
	s_waitcnt vmcnt(7)
	ds_write_b128 v251, v[132:135] offset:36864
	s_waitcnt lgkmcnt(4)
	v_mfma_f32_16x16x32_bf16 v[152:155], v[186:189], v[198:201], v[152:155]
	s_waitcnt lgkmcnt(3)
	v_mfma_f32_16x16x32_bf16 v[148:151], v[190:193], v[198:201], v[148:151]
	v_lshl_add_u64 v[132:133], s[52:53], 0, v[164:165]
	s_nop 0
	global_load_dwordx4 v[132:135], v[132:133], off
	s_waitcnt lgkmcnt(2)
	v_mfma_f32_16x16x32_bf16 v[144:147], v[194:197], v[198:201], v[144:147]
	ds_read_b128 v[246:249], v182 offset:6976
	v_mfma_f32_16x16x32_bf16 v[108:111], v[178:181], v[202:205], v[108:111]
	v_mfma_f32_16x16x32_bf16 v[104:107], v[186:189], v[202:205], v[104:107]
	v_mfma_f32_16x16x32_bf16 v[100:103], v[190:193], v[202:205], v[100:103]
	s_waitcnt vmcnt(7)
	ds_write_b128 v252, v[136:139] offset:36864
	v_mfma_f32_16x16x32_bf16 v[96:99], v[194:197], v[202:205], v[96:99]
	ds_read_b128 v[198:201], v182 offset:9280
	s_waitcnt lgkmcnt(4)
	v_mfma_f32_16x16x32_bf16 v[92:95], v[178:181], v[242:245], v[92:95]
	v_lshl_add_u64 v[136:137], s[52:53], 0, v[166:167]
	s_nop 0
	global_load_dwordx4 v[136:139], v[136:137], off
	v_mfma_f32_16x16x32_bf16 v[88:91], v[186:189], v[242:245], v[88:91]
	v_mfma_f32_16x16x32_bf16 v[84:87], v[190:193], v[242:245], v[84:87]
	v_mfma_f32_16x16x32_bf16 v[80:83], v[194:197], v[242:245], v[80:83]
	ds_read_b128 v[202:205], v182 offset:11584
	s_waitcnt lgkmcnt(3)
	v_mfma_f32_16x16x32_bf16 v[76:79], v[178:181], v[246:249], v[76:79]
	s_waitcnt vmcnt(7)
	ds_write_b128 v253, v[140:143] offset:36864
	v_mfma_f32_16x16x32_bf16 v[72:75], v[186:189], v[246:249], v[72:75]
	v_mfma_f32_16x16x32_bf16 v[68:71], v[190:193], v[246:249], v[68:71]
	v_lshl_add_u64 v[140:141], s[52:53], 0, v[168:169]
	s_nop 0
	global_load_dwordx4 v[140:143], v[140:141], off
	v_mfma_f32_16x16x32_bf16 v[64:67], v[194:197], v[246:249], v[64:67]
	ds_read_b128 v[242:245], v182 offset:13888
	s_waitcnt lgkmcnt(3)
	v_mfma_f32_16x16x32_bf16 v[60:63], v[178:181], v[198:201], v[60:63]
	v_mfma_f32_16x16x32_bf16 v[56:59], v[186:189], v[198:201], v[56:59]
	v_mfma_f32_16x16x32_bf16 v[52:55], v[190:193], v[198:201], v[52:55]
	v_mfma_f32_16x16x32_bf16 v[48:51], v[194:197], v[198:201], v[48:51]
	ds_read_b128 v[246:249], v182 offset:16192
	s_waitcnt lgkmcnt(3)
	v_mfma_f32_16x16x32_bf16 v[44:47], v[178:181], v[202:205], v[44:47]
	v_mfma_f32_16x16x32_bf16 v[40:43], v[186:189], v[202:205], v[40:43]
	v_mfma_f32_16x16x32_bf16 v[36:39], v[190:193], v[202:205], v[36:39]
	v_mfma_f32_16x16x32_bf16 v[32:35], v[194:197], v[202:205], v[32:35]
	s_add_i32 s33, s33, 1
	s_and_b32 s98, s33, 1
	s_mul_i32 s98, s98, 0x12000
	v_add3_u32 v183, s98, v171, v177
	v_add3_u32 v182, s98, v176, v177
	s_cmp_lg_u32 s33, 4
	s_waitcnt lgkmcnt(0)
	s_barrier
	s_cbranch_scc0 .Lgm3_exit
	ds_read_b128 v[198:201], v182
	ds_read_b128 v[202:205], v182 offset:2304
	v_mfma_f32_16x16x32_bf16 v[28:31], v[178:181], v[242:245], v[28:31]
	v_mfma_f32_16x16x32_bf16 v[8:11], v[178:181], v[246:249], v[8:11]
	ds_read_b128 v[178:181], v183 offset:36864
	v_mfma_f32_16x16x32_bf16 v[24:27], v[186:189], v[242:245], v[24:27]
	v_mfma_f32_16x16x32_bf16 v[4:7], v[186:189], v[246:249], v[4:7]
	ds_read_b128 v[186:189], v183 offset:39168
	v_mfma_f32_16x16x32_bf16 v[20:23], v[190:193], v[242:245], v[20:23]
	v_mfma_f32_16x16x32_bf16 v[0:3], v[190:193], v[246:249], v[0:3]
	ds_read_b128 v[190:193], v183 offset:41472
	v_mfma_f32_16x16x32_bf16 v[16:19], v[194:197], v[242:245], v[16:19]
	v_mfma_f32_16x16x32_bf16 v[12:15], v[194:197], v[246:249], v[12:15]
	ds_read_b128 v[194:197], v183 offset:43776
	s_branch .Lgm3_main

; DI f32x4 mfma16(bf16x8 a, bf16x8 b, f32x4 c) { return __builtin_amdgcn_mfma_f32_16x16x32_bf16(a, b, c, 0, 0, 0); }
; template <int MI, int NJ, bool SWAP, class AP, class BP>
; DI void gemm_main(f32x4 (&acc)[MI][NJ], const AP& ap, int a_kstep, const BP& bp, int b_kstep, int nk, bf16_t* smem) {
;     ...
;   for (int kt = 0; kt < nk; ++kt) {
;     const int buf = kt & 1;
;     sstore(buf ^ 1);
;     gload(kt + 2 < nk ? kt + 2 : nk - 1);
;     __builtin_amdgcn_sched_barrier(0);
;     const bf16_t* As = smem + buf * L::STAGE + (wm * 16 * MI + l15) * LDT + quad * 8;
;     const bf16_t* Bs = smem + buf * L::STAGE + L::A_ELEMS + (wn * 16 * NJ + l15) * LDT + quad * 8;
; #pragma unroll
;     for (int ks = 0; ks < 2; ++ks) {
;       if (MI * NJ >= 32 && ks == 1) asm volatile("" ::: "memory");
;       bf16x8 b[NJ];
; #pragma unroll
;       for (int j = 0; j < NJ; ++j) b[j] = *(const bf16x8*)(Bs + j * 16 * LDT + ks * 32);
; #pragma unroll
;       for (int i = 0; i < MI; ++i) {
;         const bf16x8 a = *(const bf16x8*)(As + i * 16 * LDT + ks * 32);
; #pragma unroll
;         for (int j = 0; j < NJ; ++j) acc[i][j] = SWAP ? mfma16(b[j], a, acc[i][j]) : mfma16(a, b[j], acc[i][j]);
;       }
;     }
;     __syncthreads();
;   }
.Lgm4_main:
	ds_read_b128 v[242:245], v182 offset:4608
	s_waitcnt lgkmcnt(4)
	v_mfma_f32_16x16x32_bf16 v[140:143], v[198:201], v[178:181], v[140:143]
	s_waitcnt lgkmcnt(3)
	v_mfma_f32_16x16x32_bf16 v[120:123], v[198:201], v[186:189], v[120:123]
	s_waitcnt lgkmcnt(2)
	v_mfma_f32_16x16x32_bf16 v[116:119], v[198:201], v[190:193], v[116:119]
	v_lshlrev_b32_e32 v250, 1, v160
	s_and_b32 s16, s5, 1
	s_xor_b32 s33, s16, 1
	s_mul_i32 s33, s33, 0x12000
	v_add3_u32 v250, s33, v250, v172
	s_waitcnt vmcnt(7)
	ds_write_b128 v250, v[124:127]
	s_waitcnt lgkmcnt(2)
	v_mfma_f32_16x16x32_bf16 v[112:115], v[198:201], v[194:197], v[112:115]
	ds_read_b128 v[246:249], v182 offset:6912
	v_mfma_f32_16x16x32_bf16 v[108:111], v[202:205], v[178:181], v[108:111]
	s_cmp_eq_u32 s5, 0
	v_lshlrev_b32_e32 v251, 1, v173
	v_add3_u32 v251, s33, v251, v172
	v_lshlrev_b32_e32 v252, 1, v174
	v_add3_u32 v252, s33, v252, v172
	v_lshlrev_b32_e32 v253, 1, v175
	v_add3_u32 v253, s33, v253, v172
	s_cselect_b32 s33, s48, 0x180
	s_add_u32 s52, s0, s33
	s_addc_u32 s53, s1, 0
	v_lshl_add_u64 v[124:125], s[52:53], 0, v[162:163]
	s_nop 0
	global_load_dwordx4 v[124:127], v[124:125], off
	v_mfma_f32_16x16x32_bf16 v[104:107], v[202:205], v[186:189], v[104:107]
	v_mfma_f32_16x16x32_bf16 v[100:103], v[202:205], v[190:193], v[100:103]
	v_mfma_f32_16x16x32_bf16 v[96:99], v[202:205], v[194:197], v[96:99]
	ds_read_b128 v[198:201], v182 offset:9216
	s_waitcnt lgkmcnt(3)
	v_mfma_f32_16x16x32_bf16 v[92:95], v[242:245], v[178:181], v[92:95]
	s_waitcnt vmcnt(7)
	ds_write_b128 v251, v[128:131]
	v_mfma_f32_16x16x32_bf16 v[88:91], v[242:245], v[186:189], v[88:91]
	v_mfma_f32_16x16x32_bf16 v[84:87], v[242:245], v[190:193], v[84:87]
	v_lshl_add_u64 v[128:129], s[52:53], 0, v[164:165]
	s_nop 0
	global_load_dwordx4 v[128:131], v[128:129], off
	v_mfma_f32_16x16x32_bf16 v[80:83], v[242:245], v[194:197], v[80:83]
	ds_read_b128 v[202:205], v182 offset:11520
	s_waitcnt lgkmcnt(3)
	v_mfma_f32_16x16x32_bf16 v[76:79], v[246:249], v[178:181], v[76:79]
	v_mfma_f32_16x16x32_bf16 v[72:75], v[246:249], v[186:189], v[72:75]
	v_mfma_f32_16x16x32_bf16 v[68:71], v[246:249], v[190:193], v[68:71]
	s_waitcnt vmcnt(7)
	ds_write_b128 v252, v[132:135]
	v_mfma_f32_16x16x32_bf16 v[64:67], v[246:249], v[194:197], v[64:67]
	ds_read_b128 v[242:245], v182 offset:13824
	s_waitcnt lgkmcnt(4)
	v_mfma_f32_16x16x32_bf16 v[60:63], v[198:201], v[178:181], v[60:63]
	v_lshl_add_u64 v[132:133], s[52:53], 0, v[166:167]
	s_nop 0
	global_load_dwordx4 v[132:135], v[132:133], off
	v_mfma_f32_16x16x32_bf16 v[56:59], v[198:201], v[186:189], v[56:59]
	v_mfma_f32_16x16x32_bf16 v[52:55], v[198:201], v[190:193], v[52:55]
	v_mfma_f32_16x16x32_bf16 v[48:51], v[198:201], v[194:197], v[48:51]
	ds_read_b128 v[246:249], v182 offset:16128
	s_waitcnt lgkmcnt(3)
	v_mfma_f32_16x16x32_bf16 v[44:47], v[202:205], v[178:181], v[44:47]
	s_waitcnt vmcnt(7)
	ds_write_b128 v253, v[136:139]
	v_mfma_f32_16x16x32_bf16 v[40:43], v[202:205], v[186:189], v[40:43]
	v_mfma_f32_16x16x32_bf16 v[36:39], v[202:205], v[190:193], v[36:39]
	v_lshl_add_u64 v[136:137], s[52:53], 0, v[168:169]
	s_nop 0
	global_load_dwordx4 v[136:139], v[136:137], off
	v_mfma_f32_16x16x32_bf16 v[32:35], v[202:205], v[194:197], v[32:35]
	ds_read_b128 v[198:201], v182 offset:64
	s_waitcnt lgkmcnt(3)
	v_mfma_f32_16x16x32_bf16 v[28:31], v[242:245], v[178:181], v[28:31]
	v_mfma_f32_16x16x32_bf16 v[24:27], v[242:245], v[186:189], v[24:27]
	v_mfma_f32_16x16x32_bf16 v[20:23], v[242:245], v[190:193], v[20:23]
	s_waitcnt vmcnt(7)
	ds_write_b128 v250, v[144:147] offset:36864
	v_mfma_f32_16x16x32_bf16 v[16:19], v[242:245], v[194:197], v[16:19]
	ds_read_b128 v[202:205], v182 offset:2368
	s_waitcnt lgkmcnt(4)
; DI f32x4 mfma16(bf16x8 a, bf16x8 b, f32x4 c) { return __builtin_amdgcn_mfma_f32_16x16x32_bf16(a, b, c, 0, 0, 0); }
; template <int MI, int NJ, bool SWAP, class AP, class BP>
; DI void gemm_main(f32x4 (&acc)[MI][NJ], const AP& ap, int a_kstep, const BP& bp, int b_kstep, int nk, bf16_t* smem) {
;     ...
;   for (int kt = 0; kt < nk; ++kt) {
;     const int buf = kt & 1;
;     sstore(buf ^ 1);
;     gload(kt + 2 < nk ? kt + 2 : nk - 1);
;     __builtin_amdgcn_sched_barrier(0);
;     const bf16_t* As = smem + buf * L::STAGE + (wm * 16 * MI + l15) * LDT + quad * 8;
;     const bf16_t* Bs = smem + buf * L::STAGE + L::A_ELEMS + (wn * 16 * NJ + l15) * LDT + quad * 8;
; #pragma unroll
;     for (int ks = 0; ks < 2; ++ks) {
;       if (MI * NJ >= 32 && ks == 1) asm volatile("" ::: "memory");
;       bf16x8 b[NJ];
; #pragma unroll
;       for (int j = 0; j < NJ; ++j) b[j] = *(const bf16x8*)(Bs + j * 16 * LDT + ks * 32);
; #pragma unroll
;       for (int i = 0; i < MI; ++i) {
;         const bf16x8 a = *(const bf16x8*)(As + i * 16 * LDT + ks * 32);
; #pragma unroll
;         for (int j = 0; j < NJ; ++j) acc[i][j] = SWAP ? mfma16(b[j], a, acc[i][j]) : mfma16(a, b[j], acc[i][j]);
;       }
;     }
;     __syncthreads();
;   }
	v_mfma_f32_16x16x32_bf16 v[8:11], v[246:249], v[178:181], v[8:11]
	ds_read_b128 v[178:181], v183 offset:36928
	s_add_u32 s52, s2, s33
	s_addc_u32 s53, s3, 0
	v_lshl_add_u64 v[144:145], s[52:53], 0, v[162:163]
	s_nop 0
	global_load_dwordx4 v[144:147], v[144:145], off
	v_mfma_f32_16x16x32_bf16 v[4:7], v[246:249], v[186:189], v[4:7]
	ds_read_b128 v[186:189], v183 offset:39232
	v_mfma_f32_16x16x32_bf16 v[0:3], v[246:249], v[190:193], v[0:3]
	ds_read_b128 v[190:193], v183 offset:41536
	v_mfma_f32_16x16x32_bf16 v[12:15], v[246:249], v[194:197], v[12:15]
	ds_read_b128 v[194:197], v183 offset:43840
	ds_read_b128 v[242:245], v182 offset:4672
	s_waitcnt lgkmcnt(4)
	v_mfma_f32_16x16x32_bf16 v[140:143], v[198:201], v[178:181], v[140:143]
	s_waitcnt vmcnt(7)
	ds_write_b128 v251, v[148:151] offset:36864
	s_waitcnt lgkmcnt(4)
	v_mfma_f32_16x16x32_bf16 v[120:123], v[198:201], v[186:189], v[120:123]
	s_waitcnt lgkmcnt(3)
	v_mfma_f32_16x16x32_bf16 v[116:119], v[198:201], v[190:193], v[116:119]
	v_lshl_add_u64 v[148:149], s[52:53], 0, v[164:165]
	s_nop 0
	global_load_dwordx4 v[148:151], v[148:149], off
	s_waitcnt lgkmcnt(2)
	v_mfma_f32_16x16x32_bf16 v[112:115], v[198:201], v[194:197], v[112:115]
	ds_read_b128 v[246:249], v182 offset:6976
	v_mfma_f32_16x16x32_bf16 v[108:111], v[202:205], v[178:181], v[108:111]
	v_mfma_f32_16x16x32_bf16 v[104:107], v[202:205], v[186:189], v[104:107]
	v_mfma_f32_16x16x32_bf16 v[100:103], v[202:205], v[190:193], v[100:103]
	s_waitcnt vmcnt(7)
	ds_write_b128 v252, v[152:155] offset:36864
	v_mfma_f32_16x16x32_bf16 v[96:99], v[202:205], v[194:197], v[96:99]
	ds_read_b128 v[198:201], v182 offset:9280
	s_waitcnt lgkmcnt(4)
	v_mfma_f32_16x16x32_bf16 v[92:95], v[242:245], v[178:181], v[92:95]
	v_lshl_add_u64 v[152:153], s[52:53], 0, v[166:167]
	s_nop 0
	global_load_dwordx4 v[152:155], v[152:153], off
	v_mfma_f32_16x16x32_bf16 v[88:91], v[242:245], v[186:189], v[88:91]
	v_mfma_f32_16x16x32_bf16 v[84:87], v[242:245], v[190:193], v[84:87]
	v_mfma_f32_16x16x32_bf16 v[80:83], v[242:245], v[194:197], v[80:83]
	ds_read_b128 v[202:205], v182 offset:11584
	s_waitcnt lgkmcnt(3)
	v_mfma_f32_16x16x32_bf16 v[76:79], v[246:249], v[178:181], v[76:79]
	s_waitcnt vmcnt(7)
	ds_write_b128 v253, v[156:159] offset:36864
	v_mfma_f32_16x16x32_bf16 v[72:75], v[246:249], v[186:189], v[72:75]
	v_mfma_f32_16x16x32_bf16 v[68:71], v[246:249], v[190:193], v[68:71]
	v_lshl_add_u64 v[156:157], s[52:53], 0, v[168:169]
	s_nop 0
	global_load_dwordx4 v[156:159], v[156:157], off
	v_mfma_f32_16x16x32_bf16 v[64:67], v[246:249], v[194:197], v[64:67]
	ds_read_b128 v[242:245], v182 offset:13888
	s_waitcnt lgkmcnt(3)
	v_mfma_f32_16x16x32_bf16 v[60:63], v[198:201], v[178:181], v[60:63]
	v_mfma_f32_16x16x32_bf16 v[56:59], v[198:201], v[186:189], v[56:59]
	v_mfma_f32_16x16x32_bf16 v[52:55], v[198:201], v[190:193], v[52:55]
	v_mfma_f32_16x16x32_bf16 v[48:51], v[198:201], v[194:197], v[48:51]
	ds_read_b128 v[246:249], v182 offset:16192
	s_waitcnt lgkmcnt(3)
	v_mfma_f32_16x16x32_bf16 v[44:47], v[202:205], v[178:181], v[44:47]
	v_mfma_f32_16x16x32_bf16 v[40:43], v[202:205], v[186:189], v[40:43]
	v_mfma_f32_16x16x32_bf16 v[36:39], v[202:205], v[190:193], v[36:39]
	v_mfma_f32_16x16x32_bf16 v[32:35], v[202:205], v[194:197], v[32:35]
	s_add_i32 s5, s5, 1
	s_and_b32 s98, s5, 1
	s_mul_i32 s98, s98, 0x12000
	v_add3_u32 v182, s98, v176, v177
	v_add3_u32 v183, s98, v171, v177
	s_cmp_lg_u32 s5, 4
	s_waitcnt lgkmcnt(0)
	s_barrier
	s_cbranch_scc0 .Lgm4_exit
	ds_read_b128 v[198:201], v182
	ds_read_b128 v[202:205], v182 offset:2304
	v_mfma_f32_16x16x32_bf16 v[28:31], v[242:245], v[178:181], v[28:31]
	v_mfma_f32_16x16x32_bf16 v[8:11], v[246:249], v[178:181], v[8:11]
	ds_read_b128 v[178:181], v183 offset:36864
	v_mfma_f32_16x16x32_bf16 v[24:27], v[242:245], v[186:189], v[24:27]
	v_mfma_f32_16x16x32_bf16 v[4:7], v[246:249], v[186:189], v[4:7]
	ds_read_b128 v[186:189], v183 offset:39168
	v_mfma_f32_16x16x32_bf16 v[20:23], v[242:245], v[190:193], v[20:23]
	v_mfma_f32_16x16x32_bf16 v[0:3], v[246:249], v[190:193], v[0:3]
	ds_read_b128 v[190:193], v183 offset:41472
	v_mfma_f32_16x16x32_bf16 v[16:19], v[242:245], v[194:197], v[16:19]
	v_mfma_f32_16x16x32_bf16 v[12:15], v[246:249], v[194:197], v[12:15]
	ds_read_b128 v[194:197], v183 offset:43776
	s_branch .Lgm4_main

; DI f32x4 mfma16(bf16x8 a, bf16x8 b, f32x4 c) { return __builtin_amdgcn_mfma_f32_16x16x32_bf16(a, b, c, 0, 0, 0); }
; template <int MI, int NJ, bool SWAP, class AP, class BP>
; DI void gemm_main(f32x4 (&acc)[MI][NJ], const AP& ap, int a_kstep, const BP& bp, int b_kstep, int nk, bf16_t* smem) {
;     ...
;   for (int kt = 0; kt < nk; ++kt) {
;     const int buf = kt & 1;
;     sstore(buf ^ 1);
;     gload(kt + 2 < nk ? kt + 2 : nk - 1);
;     __builtin_amdgcn_sched_barrier(0);
;     const bf16_t* As = smem + buf * L::STAGE + (wm * 16 * MI + l15) * LDT + quad * 8;
;     const bf16_t* Bs = smem + buf * L::STAGE + L::A_ELEMS + (wn * 16 * NJ + l15) * LDT + quad * 8;
; #pragma unroll
;     for (int ks = 0; ks < 2; ++ks) {
;       if (MI * NJ >= 32 && ks == 1) asm volatile("" ::: "memory");
;       bf16x8 b[NJ];
; #pragma unroll
;       for (int j = 0; j < NJ; ++j) b[j] = *(const bf16x8*)(Bs + j * 16 * LDT + ks * 32);
; #pragma unroll
;       for (int i = 0; i < MI; ++i) {
;         const bf16x8 a = *(const bf16x8*)(As + i * 16 * LDT + ks * 32);
; #pragma unroll
;         for (int j = 0; j < NJ; ++j) acc[i][j] = SWAP ? mfma16(b[j], a, acc[i][j]) : mfma16(a, b[j], acc[i][j]);
;       }
;     }
;     __syncthreads();
;   }
.Lgm5_main:
	ds_read_b128 v[242:245], v177 offset:4608
	s_waitcnt lgkmcnt(4)
	v_mfma_f32_16x16x32_bf16 v[156:159], v[178:181], v[194:197], v[156:159]
	s_waitcnt lgkmcnt(3)
	v_mfma_f32_16x16x32_bf16 v[152:155], v[182:185], v[194:197], v[152:155]
	s_waitcnt lgkmcnt(2)
	v_mfma_f32_16x16x32_bf16 v[148:151], v[186:189], v[194:197], v[148:151]
	s_and_b32 s15, s1, 1
	s_min_u32 s16, s1, 13
	s_xor_b32 s17, s15, 1
	s_mul_i32 s17, s17, 0x12000
	v_add3_u32 v250, s17, v172, v170
	s_waitcnt vmcnt(7)
	ds_write_b128 v250, v[112:115]
	s_waitcnt lgkmcnt(2)
	v_mfma_f32_16x16x32_bf16 v[128:131], v[190:193], v[194:197], v[128:131]
	ds_read_b128 v[246:249], v177 offset:6912
	v_mfma_f32_16x16x32_bf16 v[108:111], v[178:181], v[198:201], v[108:111]
	s_lshl_b32 s26, s16, 7
	s_add_u32 s16, s2, s26
	v_add3_u32 v251, s17, v174, v170
	v_add3_u32 v252, s17, v175, v170
	v_add3_u32 v253, s17, v176, v170
	s_addc_u32 s17, s3, 0
	v_lshl_add_u64 v[112:113], s[16:17], 0, v[162:163]
	s_nop 0
	global_load_dwordx4 v[112:115], v[112:113], off offset:256
	v_mfma_f32_16x16x32_bf16 v[104:107], v[182:185], v[198:201], v[104:107]
	v_mfma_f32_16x16x32_bf16 v[100:103], v[186:189], v[198:201], v[100:103]
	v_mfma_f32_16x16x32_bf16 v[96:99], v[190:193], v[198:201], v[96:99]
	ds_read_b128 v[194:197], v177 offset:9216
	s_waitcnt lgkmcnt(3)
	v_mfma_f32_16x16x32_bf16 v[92:95], v[178:181], v[242:245], v[92:95]
	s_waitcnt vmcnt(7)
	ds_write_b128 v251, v[116:119]
	v_mfma_f32_16x16x32_bf16 v[88:91], v[182:185], v[242:245], v[88:91]
	v_mfma_f32_16x16x32_bf16 v[84:87], v[186:189], v[242:245], v[84:87]
	v_lshl_add_u64 v[116:117], s[16:17], 0, v[164:165]
	s_nop 0
	global_load_dwordx4 v[116:119], v[116:117], off offset:256
	v_mfma_f32_16x16x32_bf16 v[80:83], v[190:193], v[242:245], v[80:83]
	ds_read_b128 v[198:201], v177 offset:11520
	s_waitcnt lgkmcnt(3)
	v_mfma_f32_16x16x32_bf16 v[76:79], v[178:181], v[246:249], v[76:79]
	v_mfma_f32_16x16x32_bf16 v[72:75], v[182:185], v[246:249], v[72:75]
	v_mfma_f32_16x16x32_bf16 v[68:71], v[186:189], v[246:249], v[68:71]
	s_waitcnt vmcnt(7)
	ds_write_b128 v252, v[120:123]
	v_mfma_f32_16x16x32_bf16 v[64:67], v[190:193], v[246:249], v[64:67]
	ds_read_b128 v[242:245], v177 offset:13824
	s_waitcnt lgkmcnt(4)
	v_mfma_f32_16x16x32_bf16 v[60:63], v[178:181], v[194:197], v[60:63]
	v_lshl_add_u64 v[120:121], s[16:17], 0, v[166:167]
	s_nop 0
	global_load_dwordx4 v[120:123], v[120:121], off offset:256
	v_mfma_f32_16x16x32_bf16 v[56:59], v[182:185], v[194:197], v[56:59]
	v_mfma_f32_16x16x32_bf16 v[52:55], v[186:189], v[194:197], v[52:55]
	v_mfma_f32_16x16x32_bf16 v[48:51], v[190:193], v[194:197], v[48:51]
	ds_read_b128 v[246:249], v177 offset:16128
	s_waitcnt lgkmcnt(3)
	v_mfma_f32_16x16x32_bf16 v[44:47], v[178:181], v[198:201], v[44:47]
	s_waitcnt vmcnt(7)
	ds_write_b128 v253, v[124:127]
	v_mfma_f32_16x16x32_bf16 v[40:43], v[182:185], v[198:201], v[40:43]
	v_mfma_f32_16x16x32_bf16 v[36:39], v[186:189], v[198:201], v[36:39]
	v_lshl_add_u64 v[124:125], s[16:17], 0, v[168:169]
	s_nop 0
	global_load_dwordx4 v[124:127], v[124:125], off offset:256
	v_mfma_f32_16x16x32_bf16 v[32:35], v[190:193], v[198:201], v[32:35]
	ds_read_b128 v[194:197], v177 offset:64
	s_waitcnt lgkmcnt(3)
	v_mfma_f32_16x16x32_bf16 v[28:31], v[178:181], v[242:245], v[28:31]
	v_mfma_f32_16x16x32_bf16 v[24:27], v[182:185], v[242:245], v[24:27]
	v_mfma_f32_16x16x32_bf16 v[20:23], v[186:189], v[242:245], v[20:23]
	s_waitcnt vmcnt(7)
	ds_write_b128 v250, v[132:135] offset:36864
	v_mfma_f32_16x16x32_bf16 v[16:19], v[190:193], v[242:245], v[16:19]
	ds_read_b128 v[198:201], v177 offset:2368
	s_waitcnt lgkmcnt(4)
	v_mfma_f32_16x16x32_bf16 v[8:11], v[178:181], v[246:249], v[8:11]
	ds_read_b128 v[178:181], v202 offset:36928
	s_add_u32 s16, s12, s26
	s_addc_u32 s17, s13, 0
	v_lshl_add_u64 v[132:133], s[16:17], 0, v[162:163]
	s_nop 0
	global_load_dwordx4 v[132:135], v[132:133], off offset:256
	v_mfma_f32_16x16x32_bf16 v[4:7], v[182:185], v[246:249], v[4:7]
	ds_read_b128 v[182:185], v202 offset:39232
	v_mfma_f32_16x16x32_bf16 v[0:3], v[186:189], v[246:249], v[0:3]
	ds_read_b128 v[186:189], v202 offset:41536
	v_mfma_f32_16x16x32_bf16 v[12:15], v[190:193], v[246:249], v[12:15]
	ds_read_b128 v[190:193], v202 offset:43840
	ds_read_b128 v[242:245], v177 offset:4672
	s_waitcnt lgkmcnt(4)
; DI f32x4 mfma16(bf16x8 a, bf16x8 b, f32x4 c) { return __builtin_amdgcn_mfma_f32_16x16x32_bf16(a, b, c, 0, 0, 0); }
; template <int MI, int NJ, bool SWAP, class AP, class BP>
; DI void gemm_main(f32x4 (&acc)[MI][NJ], const AP& ap, int a_kstep, const BP& bp, int b_kstep, int nk, bf16_t* smem) {
;     ...
;   for (int kt = 0; kt < nk; ++kt) {
;     const int buf = kt & 1;
;     sstore(buf ^ 1);
;     gload(kt + 2 < nk ? kt + 2 : nk - 1);
;     __builtin_amdgcn_sched_barrier(0);
;     const bf16_t* As = smem + buf * L::STAGE + (wm * 16 * MI + l15) * LDT + quad * 8;
;     const bf16_t* Bs = smem + buf * L::STAGE + L::A_ELEMS + (wn * 16 * NJ + l15) * LDT + quad * 8;
; #pragma unroll
;     for (int ks = 0; ks < 2; ++ks) {
;       if (MI * NJ >= 32 && ks == 1) asm volatile("" ::: "memory");
;       bf16x8 b[NJ];
; #pragma unroll
;       for (int j = 0; j < NJ; ++j) b[j] = *(const bf16x8*)(Bs + j * 16 * LDT + ks * 32);
; #pragma unroll
;       for (int i = 0; i < MI; ++i) {
;         const bf16x8 a = *(const bf16x8*)(As + i * 16 * LDT + ks * 32);
; #pragma unroll
;         for (int j = 0; j < NJ; ++j) acc[i][j] = SWAP ? mfma16(b[j], a, acc[i][j]) : mfma16(a, b[j], acc[i][j]);
;       }
;     }
;     __syncthreads();
;   }
	v_mfma_f32_16x16x32_bf16 v[156:159], v[178:181], v[194:197], v[156:159]
	s_waitcnt vmcnt(7)
	ds_write_b128 v251, v[136:139] offset:36864
	s_waitcnt lgkmcnt(4)
	v_mfma_f32_16x16x32_bf16 v[152:155], v[182:185], v[194:197], v[152:155]
	s_waitcnt lgkmcnt(3)
	v_mfma_f32_16x16x32_bf16 v[148:151], v[186:189], v[194:197], v[148:151]
	v_lshl_add_u64 v[136:137], s[16:17], 0, v[164:165]
	s_nop 0
	global_load_dwordx4 v[136:139], v[136:137], off offset:256
	s_waitcnt lgkmcnt(2)
	v_mfma_f32_16x16x32_bf16 v[128:131], v[190:193], v[194:197], v[128:131]
	ds_read_b128 v[246:249], v177 offset:6976
	v_mfma_f32_16x16x32_bf16 v[108:111], v[178:181], v[198:201], v[108:111]
	v_mfma_f32_16x16x32_bf16 v[104:107], v[182:185], v[198:201], v[104:107]
	v_mfma_f32_16x16x32_bf16 v[100:103], v[186:189], v[198:201], v[100:103]
	s_waitcnt vmcnt(7)
	ds_write_b128 v252, v[140:143] offset:36864
	v_mfma_f32_16x16x32_bf16 v[96:99], v[190:193], v[198:201], v[96:99]
	ds_read_b128 v[194:197], v177 offset:9280
	s_waitcnt lgkmcnt(4)
	v_mfma_f32_16x16x32_bf16 v[92:95], v[178:181], v[242:245], v[92:95]
	v_lshl_add_u64 v[140:141], s[16:17], 0, v[166:167]
	s_nop 0
	global_load_dwordx4 v[140:143], v[140:141], off offset:256
	v_mfma_f32_16x16x32_bf16 v[88:91], v[182:185], v[242:245], v[88:91]
	v_mfma_f32_16x16x32_bf16 v[84:87], v[186:189], v[242:245], v[84:87]
	v_mfma_f32_16x16x32_bf16 v[80:83], v[190:193], v[242:245], v[80:83]
	ds_read_b128 v[198:201], v177 offset:11584
	s_waitcnt lgkmcnt(3)
	v_mfma_f32_16x16x32_bf16 v[76:79], v[178:181], v[246:249], v[76:79]
	s_waitcnt vmcnt(7)
	ds_write_b128 v253, v[144:147] offset:36864
	v_mfma_f32_16x16x32_bf16 v[72:75], v[182:185], v[246:249], v[72:75]
	v_mfma_f32_16x16x32_bf16 v[68:71], v[186:189], v[246:249], v[68:71]
	v_lshl_add_u64 v[144:145], s[16:17], 0, v[168:169]
	s_nop 0
	global_load_dwordx4 v[144:147], v[144:145], off offset:256
	v_mfma_f32_16x16x32_bf16 v[64:67], v[190:193], v[246:249], v[64:67]
	ds_read_b128 v[242:245], v177 offset:13888
	s_waitcnt lgkmcnt(3)
	v_mfma_f32_16x16x32_bf16 v[60:63], v[178:181], v[194:197], v[60:63]
	v_mfma_f32_16x16x32_bf16 v[56:59], v[182:185], v[194:197], v[56:59]
	v_mfma_f32_16x16x32_bf16 v[52:55], v[186:189], v[194:197], v[52:55]
	v_mfma_f32_16x16x32_bf16 v[48:51], v[190:193], v[194:197], v[48:51]
	ds_read_b128 v[246:249], v177 offset:16192
	s_waitcnt lgkmcnt(3)
	v_mfma_f32_16x16x32_bf16 v[44:47], v[178:181], v[198:201], v[44:47]
	v_mfma_f32_16x16x32_bf16 v[40:43], v[182:185], v[198:201], v[40:43]
	v_mfma_f32_16x16x32_bf16 v[36:39], v[186:189], v[198:201], v[36:39]
	v_mfma_f32_16x16x32_bf16 v[32:35], v[190:193], v[198:201], v[32:35]
	s_add_i32 s1, s1, 1
	s_and_b32 s98, s1, 1
	s_mul_i32 s98, s98, 0x12000
	v_add3_u32 v202, s98, v160, v173
	v_add3_u32 v177, s98, v171, v173
	s_cmp_lg_u32 s1, 16
	s_waitcnt lgkmcnt(0)
	s_barrier
	s_cbranch_scc0 .Lgm5_exit
	ds_read_b128 v[194:197], v177
	ds_read_b128 v[198:201], v177 offset:2304
	v_mfma_f32_16x16x32_bf16 v[28:31], v[178:181], v[242:245], v[28:31]
	v_mfma_f32_16x16x32_bf16 v[8:11], v[178:181], v[246:249], v[8:11]
	ds_read_b128 v[178:181], v202 offset:36864
	v_mfma_f32_16x16x32_bf16 v[24:27], v[182:185], v[242:245], v[24:27]
	v_mfma_f32_16x16x32_bf16 v[4:7], v[182:185], v[246:249], v[4:7]
	ds_read_b128 v[182:185], v202 offset:39168
	v_mfma_f32_16x16x32_bf16 v[20:23], v[186:189], v[242:245], v[20:23]
	v_mfma_f32_16x16x32_bf16 v[0:3], v[186:189], v[246:249], v[0:3]
	ds_read_b128 v[186:189], v202 offset:41472
	v_mfma_f32_16x16x32_bf16 v[16:19], v[190:193], v[242:245], v[16:19]
	v_mfma_f32_16x16x32_bf16 v[12:15], v[190:193], v[246:249], v[12:15]
	ds_read_b128 v[190:193], v202 offset:43776
	s_branch .Lgm5_main

; DI f32x4 mfma16(bf16x8 a, bf16x8 b, f32x4 c) { return __builtin_amdgcn_mfma_f32_16x16x32_bf16(a, b, c, 0, 0, 0); }
; template <int MI, int NJ, bool SWAP, class AP, class BP>
; DI void gemm_main(f32x4 (&acc)[MI][NJ], const AP& ap, int a_kstep, const BP& bp, int b_kstep, int nk, bf16_t* smem) {
;     ...
;   auto gload = [&](int kt) {
;     const bf16_t* ab = ap.base + (size_t)kt * a_kstep; const bf16_t* bb = bp.base + (size_t)kt * b_kstep;
; #pragma unroll
;     for (int i = 0; i < CA; ++i) ra[i] = *(const u32x4*)(ab + pa[i]);
; #pragma unroll
;     for (int i = 0; i < CB; ++i) rb[i] = *(const u32x4*)(bb + pb[i]);
;   };
;   auto sstore = [&](int buf) {
;     bf16_t* As = smem + buf * L::STAGE; bf16_t* Bs = As + L::A_ELEMS;
; #pragma unroll
;     for (int i = 0; i < CA; ++i) { const int c = tid + NTHR * i; *(u32x4*)(As + (c >> 3) * LDT + (c & 7) * 8) = oka[i] ? ra[i] : (u32x4){0u, 0u, 0u, 0u}; }
; #pragma unroll
;     for (int i = 0; i < CB; ++i) { const int c = tid + NTHR * i; *(u32x4*)(Bs + (c >> 3) * LDT + (c & 7) * 8) = rb[i]; }
;   };
;   gload(0); sstore(0); gload(nk > 1 ? 1 : 0); __syncthreads();
; #pragma unroll 1
;   for (int kt = 0; kt < nk; ++kt) {
;     const int buf = kt & 1;
;     sstore(buf ^ 1);
;     gload(kt + 2 < nk ? kt + 2 : nk - 1);
;     __builtin_amdgcn_sched_barrier(0);
;     const bf16_t* As = smem + buf * L::STAGE + (wm * 16 * MI + l15) * LDT + quad * 8;
;     const bf16_t* Bs = smem + buf * L::STAGE + L::A_ELEMS + (wn * 16 * NJ + l15) * LDT + quad * 8;
; #pragma unroll
;     for (int ks = 0; ks < 2; ++ks) {
;       if (MI * NJ >= 32 && ks == 1) asm volatile("" ::: "memory");
;       bf16x8 b[NJ];
; #pragma unroll
;       for (int j = 0; j < NJ; ++j) b[j] = *(const bf16x8*)(Bs + j * 16 * LDT + ks * 32);
; #pragma unroll
;       for (int i = 0; i < MI; ++i) {
;         const bf16x8 a = *(const bf16x8*)(As + i * 16 * LDT + ks * 32);
; #pragma unroll
;         for (int j = 0; j < NJ; ++j) acc[i][j] = SWAP ? mfma16(b[j], a, acc[i][j]) : mfma16(a, b[j], acc[i][j]);
;       }
;     }
;     __syncthreads();
;   }
.Lgm6_main:
	ds_read_b128 v[246:249], v181 offset:4608
	s_waitcnt lgkmcnt(4)
	v_mfma_f32_16x16x32_bf16 v[156:159], v[182:185], v[198:201], v[156:159]
	s_waitcnt lgkmcnt(3)
	v_mfma_f32_16x16x32_bf16 v[152:155], v[186:189], v[198:201], v[152:155]
	s_waitcnt lgkmcnt(2)
	v_mfma_f32_16x16x32_bf16 v[148:151], v[190:193], v[198:201], v[148:151]
	s_waitcnt vmcnt(7)
	v_cndmask_b32_e32 v139, 0, v139, vcc
	v_cndmask_b32_e32 v138, 0, v138, vcc
	v_cndmask_b32_e32 v137, 0, v137, vcc
	v_cndmask_b32_e32 v136, 0, v136, vcc
	s_and_b32 s31, s30, 1
	s_xor_b32 s33, s31, 1
	s_mul_i32 s33, s33, 0x12000
	v_add3_u32 v254, s33, v172, v169
	ds_write_b128 v254, v[136:139]
	s_waitcnt lgkmcnt(2)
	v_mfma_f32_16x16x32_bf16 v[144:147], v[194:197], v[198:201], v[144:147]
	ds_read_b128 v[250:253], v181 offset:6912
	v_mfma_f32_16x16x32_bf16 v[108:111], v[182:185], v[242:245], v[108:111]
	v_add3_u32 v238, s33, v173, v169
	v_add3_u32 v239, s33, v174, v169
	v_add3_u32 v255, s33, v175, v169
	s_min_u32 s33, s30, 13
	s_lshl_b32 s33, s33, 7
	s_add_u32 s34, s12, s33
	s_addc_u32 s35, s13, 0
	s_nop 0
	global_load_dwordx4 v[136:139], v176, s[34:35] offset:256
	v_mfma_f32_16x16x32_bf16 v[104:107], v[186:189], v[242:245], v[104:107]
	v_mfma_f32_16x16x32_bf16 v[100:103], v[190:193], v[242:245], v[100:103]
	v_mfma_f32_16x16x32_bf16 v[96:99], v[194:197], v[242:245], v[96:99]
	ds_read_b128 v[198:201], v181 offset:9216
	s_waitcnt lgkmcnt(3)
	v_mfma_f32_16x16x32_bf16 v[92:95], v[182:185], v[246:249], v[92:95]
	s_waitcnt vmcnt(7)
	v_cndmask_b32_e64 v127, 0, v127, s[0:1]
	v_cndmask_b32_e64 v126, 0, v126, s[0:1]
	v_cndmask_b32_e64 v125, 0, v125, s[0:1]
	v_cndmask_b32_e64 v124, 0, v124, s[0:1]
	ds_write_b128 v238, v[124:127]
	v_mfma_f32_16x16x32_bf16 v[88:91], v[186:189], v[246:249], v[88:91]
	v_mfma_f32_16x16x32_bf16 v[84:87], v[190:193], v[246:249], v[84:87]
	s_nop 0
	global_load_dwordx4 v[124:127], v177, s[34:35] offset:256
	v_mfma_f32_16x16x32_bf16 v[80:83], v[194:197], v[246:249], v[80:83]
	ds_read_b128 v[242:245], v181 offset:11520
	s_waitcnt lgkmcnt(3)
	v_mfma_f32_16x16x32_bf16 v[76:79], v[182:185], v[250:253], v[76:79]
	v_mfma_f32_16x16x32_bf16 v[72:75], v[186:189], v[250:253], v[72:75]
	v_mfma_f32_16x16x32_bf16 v[68:71], v[190:193], v[250:253], v[68:71]
	s_waitcnt vmcnt(7)
	v_cndmask_b32_e64 v115, 0, v115, s[2:3]
	v_cndmask_b32_e64 v114, 0, v114, s[2:3]
	v_cndmask_b32_e64 v113, 0, v113, s[2:3]
	v_cndmask_b32_e64 v112, 0, v112, s[2:3]
	ds_write_b128 v239, v[112:115]
	v_mfma_f32_16x16x32_bf16 v[64:67], v[194:197], v[250:253], v[64:67]
	ds_read_b128 v[246:249], v181 offset:13824
	s_waitcnt lgkmcnt(4)
	v_mfma_f32_16x16x32_bf16 v[60:63], v[182:185], v[198:201], v[60:63]
	v_mfma_f32_16x16x32_bf16 v[56:59], v[186:189], v[198:201], v[56:59]
	v_mfma_f32_16x16x32_bf16 v[52:55], v[190:193], v[198:201], v[52:55]
	v_mfma_f32_16x16x32_bf16 v[48:51], v[194:197], v[198:201], v[48:51]
	ds_read_b128 v[250:253], v181 offset:16128
	s_waitcnt lgkmcnt(3)
	v_mfma_f32_16x16x32_bf16 v[44:47], v[182:185], v[242:245], v[44:47]
	s_waitcnt vmcnt(6)
	v_cndmask_b32_e64 v112, 0, v116, s[4:5]
	v_cndmask_b32_e64 v115, 0, v119, s[4:5]
	v_cndmask_b32_e64 v114, 0, v118, s[4:5]
	v_cndmask_b32_e64 v113, 0, v117, s[4:5]
	ds_write_b128 v255, v[112:115]
	v_mfma_f32_16x16x32_bf16 v[40:43], v[186:189], v[242:245], v[40:43]
	v_mfma_f32_16x16x32_bf16 v[36:39], v[190:193], v[242:245], v[36:39]
	s_nop 0
	global_load_dwordx4 v[112:115], v178, s[34:35] offset:256
	s_nop 0
	global_load_dwordx4 v[116:119], v179, s[34:35] offset:256
	v_mfma_f32_16x16x32_bf16 v[32:35], v[194:197], v[242:245], v[32:35]
	ds_read_b128 v[198:201], v181 offset:64
	s_waitcnt lgkmcnt(3)
	v_mfma_f32_16x16x32_bf16 v[28:31], v[182:185], v[246:249], v[28:31]
	v_mfma_f32_16x16x32_bf16 v[24:27], v[186:189], v[246:249], v[24:27]
	v_mfma_f32_16x16x32_bf16 v[20:23], v[190:193], v[246:249], v[20:23]
	s_waitcnt vmcnt(7)
	ds_write_b128 v254, v[120:123] offset:36864
	v_mfma_f32_16x16x32_bf16 v[16:19], v[194:197], v[246:249], v[16:19]
	ds_read_b128 v[242:245], v181 offset:2368
	s_waitcnt lgkmcnt(4)
; DI f32x4 mfma16(bf16x8 a, bf16x8 b, f32x4 c) { return __builtin_amdgcn_mfma_f32_16x16x32_bf16(a, b, c, 0, 0, 0); }
; template <int MI, int NJ, bool SWAP, class AP, class BP>
; DI void gemm_main(f32x4 (&acc)[MI][NJ], const AP& ap, int a_kstep, const BP& bp, int b_kstep, int nk, bf16_t* smem) {
;     ...
;   auto gload = [&](int kt) {
;     const bf16_t* ab = ap.base + (size_t)kt * a_kstep; const bf16_t* bb = bp.base + (size_t)kt * b_kstep;
; #pragma unroll
;     for (int i = 0; i < CA; ++i) ra[i] = *(const u32x4*)(ab + pa[i]);
; #pragma unroll
;     for (int i = 0; i < CB; ++i) rb[i] = *(const u32x4*)(bb + pb[i]);
;   };
;   auto sstore = [&](int buf) {
;     bf16_t* As = smem + buf * L::STAGE; bf16_t* Bs = As + L::A_ELEMS;
; #pragma unroll
;     for (int i = 0; i < CA; ++i) { const int c = tid + NTHR * i; *(u32x4*)(As + (c >> 3) * LDT + (c & 7) * 8) = oka[i] ? ra[i] : (u32x4){0u, 0u, 0u, 0u}; }
; #pragma unroll
;     for (int i = 0; i < CB; ++i) { const int c = tid + NTHR * i; *(u32x4*)(Bs + (c >> 3) * LDT + (c & 7) * 8) = rb[i]; }
;   };
;   gload(0); sstore(0); gload(nk > 1 ? 1 : 0); __syncthreads();
; #pragma unroll 1
;   for (int kt = 0; kt < nk; ++kt) {
;     const int buf = kt & 1;
;     sstore(buf ^ 1);
;     gload(kt + 2 < nk ? kt + 2 : nk - 1);
;     __builtin_amdgcn_sched_barrier(0);
;     const bf16_t* As = smem + buf * L::STAGE + (wm * 16 * MI + l15) * LDT + quad * 8;
;     const bf16_t* Bs = smem + buf * L::STAGE + L::A_ELEMS + (wn * 16 * NJ + l15) * LDT + quad * 8;
; #pragma unroll
;     for (int ks = 0; ks < 2; ++ks) {
;       if (MI * NJ >= 32 && ks == 1) asm volatile("" ::: "memory");
;       bf16x8 b[NJ];
; #pragma unroll
;       for (int j = 0; j < NJ; ++j) b[j] = *(const bf16x8*)(Bs + j * 16 * LDT + ks * 32);
; #pragma unroll
;       for (int i = 0; i < MI; ++i) {
;         const bf16x8 a = *(const bf16x8*)(As + i * 16 * LDT + ks * 32);
; #pragma unroll
;         for (int j = 0; j < NJ; ++j) acc[i][j] = SWAP ? mfma16(b[j], a, acc[i][j]) : mfma16(a, b[j], acc[i][j]);
;       }
;     }
;     __syncthreads();
;   }
	v_mfma_f32_16x16x32_bf16 v[12:15], v[182:185], v[250:253], v[12:15]
	ds_read_b128 v[182:185], v202 offset:36928
	s_add_u32 s34, s14, s33
	s_addc_u32 s35, s15, 0
	v_lshl_add_u64 v[120:121], v[160:161], 1, s[34:35]
	s_nop 0
	global_load_dwordx4 v[120:123], v[120:121], off offset:256
	v_mfma_f32_16x16x32_bf16 v[8:11], v[186:189], v[250:253], v[8:11]
	ds_read_b128 v[186:189], v202 offset:39232
	v_mfma_f32_16x16x32_bf16 v[4:7], v[190:193], v[250:253], v[4:7]
	ds_read_b128 v[190:193], v202 offset:41536
	v_mfma_f32_16x16x32_bf16 v[0:3], v[194:197], v[250:253], v[0:3]
	ds_read_b128 v[194:197], v202 offset:43840
	ds_read_b128 v[246:249], v181 offset:4672
	s_waitcnt lgkmcnt(4)
	v_mfma_f32_16x16x32_bf16 v[156:159], v[182:185], v[198:201], v[156:159]
	s_waitcnt vmcnt(7)
	ds_write_b128 v238, v[128:131] offset:36864
	s_waitcnt lgkmcnt(4)
	v_mfma_f32_16x16x32_bf16 v[152:155], v[186:189], v[198:201], v[152:155]
	s_waitcnt lgkmcnt(3)
	v_mfma_f32_16x16x32_bf16 v[148:151], v[190:193], v[198:201], v[148:151]
	v_lshl_add_u64 v[128:129], v[162:163], 1, s[34:35]
	s_nop 0
	global_load_dwordx4 v[128:131], v[128:129], off offset:256
	s_waitcnt lgkmcnt(2)
	v_mfma_f32_16x16x32_bf16 v[144:147], v[194:197], v[198:201], v[144:147]
	ds_read_b128 v[250:253], v181 offset:6976
	v_mfma_f32_16x16x32_bf16 v[108:111], v[182:185], v[242:245], v[108:111]
	v_mfma_f32_16x16x32_bf16 v[104:107], v[186:189], v[242:245], v[104:107]
	v_mfma_f32_16x16x32_bf16 v[100:103], v[190:193], v[242:245], v[100:103]
	s_waitcnt vmcnt(7)
	ds_write_b128 v239, v[132:135] offset:36864
	v_mfma_f32_16x16x32_bf16 v[96:99], v[194:197], v[242:245], v[96:99]
	ds_read_b128 v[198:201], v181 offset:9280
	s_waitcnt lgkmcnt(4)
	v_mfma_f32_16x16x32_bf16 v[92:95], v[182:185], v[246:249], v[92:95]
	v_lshl_add_u64 v[132:133], v[164:165], 1, s[34:35]
	s_nop 0
	global_load_dwordx4 v[132:135], v[132:133], off offset:256
	v_mfma_f32_16x16x32_bf16 v[88:91], v[186:189], v[246:249], v[88:91]
	v_mfma_f32_16x16x32_bf16 v[84:87], v[190:193], v[246:249], v[84:87]
	v_mfma_f32_16x16x32_bf16 v[80:83], v[194:197], v[246:249], v[80:83]
	ds_read_b128 v[242:245], v181 offset:11584
	s_waitcnt lgkmcnt(3)
	v_mfma_f32_16x16x32_bf16 v[76:79], v[182:185], v[250:253], v[76:79]
	s_waitcnt vmcnt(7)
	ds_write_b128 v255, v[140:143] offset:36864
	v_mfma_f32_16x16x32_bf16 v[72:75], v[186:189], v[250:253], v[72:75]
	v_mfma_f32_16x16x32_bf16 v[68:71], v[190:193], v[250:253], v[68:71]
	v_lshl_add_u64 v[140:141], v[166:167], 1, s[34:35]
	s_nop 0
	global_load_dwordx4 v[140:143], v[140:141], off offset:256
	v_mfma_f32_16x16x32_bf16 v[64:67], v[194:197], v[250:253], v[64:67]
	ds_read_b128 v[246:249], v181 offset:13888
	s_waitcnt lgkmcnt(3)
	v_mfma_f32_16x16x32_bf16 v[60:63], v[182:185], v[198:201], v[60:63]
	v_mfma_f32_16x16x32_bf16 v[56:59], v[186:189], v[198:201], v[56:59]
	v_mfma_f32_16x16x32_bf16 v[52:55], v[190:193], v[198:201], v[52:55]
	v_mfma_f32_16x16x32_bf16 v[48:51], v[194:197], v[198:201], v[48:51]
	ds_read_b128 v[250:253], v181 offset:16192
	s_waitcnt lgkmcnt(3)
	v_mfma_f32_16x16x32_bf16 v[44:47], v[182:185], v[242:245], v[44:47]
	v_mfma_f32_16x16x32_bf16 v[40:43], v[186:189], v[242:245], v[40:43]
	v_mfma_f32_16x16x32_bf16 v[36:39], v[190:193], v[242:245], v[36:39]
	v_mfma_f32_16x16x32_bf16 v[32:35], v[194:197], v[242:245], v[32:35]
	s_add_i32 s30, s30, 1
	s_and_b32 s98, s30, 1
	s_mul_i32 s98, s98, 0x12000
	v_add3_u32 v181, s98, v170, v180
	v_add3_u32 v202, s98, v171, v180
	s_cmp_lg_u32 s30, 16
	s_waitcnt lgkmcnt(0)
	s_barrier
	s_cbranch_scc0 .Lgm6_exit
	ds_read_b128 v[198:201], v181
	ds_read_b128 v[242:245], v181 offset:2304
	v_mfma_f32_16x16x32_bf16 v[28:31], v[182:185], v[246:249], v[28:31]
	v_mfma_f32_16x16x32_bf16 v[12:15], v[182:185], v[250:253], v[12:15]
	ds_read_b128 v[182:185], v202 offset:36864
	v_mfma_f32_16x16x32_bf16 v[24:27], v[186:189], v[246:249], v[24:27]
	v_mfma_f32_16x16x32_bf16 v[8:11], v[186:189], v[250:253], v[8:11]
	ds_read_b128 v[186:189], v202 offset:39168
	v_mfma_f32_16x16x32_bf16 v[20:23], v[190:193], v[246:249], v[20:23]
	v_mfma_f32_16x16x32_bf16 v[4:7], v[190:193], v[250:253], v[4:7]
	ds_read_b128 v[190:193], v202 offset:41472
	v_mfma_f32_16x16x32_bf16 v[16:19], v[194:197], v[246:249], v[16:19]
	v_mfma_f32_16x16x32_bf16 v[0:3], v[194:197], v[250:253], v[0:3]
	ds_read_b128 v[194:197], v202 offset:43776
	s_branch .Lgm6_main

; DI f32x4 mfma16(bf16x8 a, bf16x8 b, f32x4 c) { return __builtin_amdgcn_mfma_f32_16x16x32_bf16(a, b, c, 0, 0, 0); }
; template <int MI, int NJ, bool SWAP, class AP, class BP>
; DI void gemm_main(f32x4 (&acc)[MI][NJ], const AP& ap, int a_kstep, const BP& bp, int b_kstep, int nk, bf16_t* smem) {
;     ...
;   for (int kt = 0; kt < nk; ++kt) {
;     const int buf = kt & 1;
;     sstore(buf ^ 1);
;     gload(kt + 2 < nk ? kt + 2 : nk - 1);
;     __builtin_amdgcn_sched_barrier(0);
;     const bf16_t* As = smem + buf * L::STAGE + (wm * 16 * MI + l15) * LDT + quad * 8;
;     const bf16_t* Bs = smem + buf * L::STAGE + L::A_ELEMS + (wn * 16 * NJ + l15) * LDT + quad * 8;
; #pragma unroll
;     for (int ks = 0; ks < 2; ++ks) {
;       if (MI * NJ >= 32 && ks == 1) asm volatile("" ::: "memory");
;       bf16x8 b[NJ];
; #pragma unroll
;       for (int j = 0; j < NJ; ++j) b[j] = *(const bf16x8*)(Bs + j * 16 * LDT + ks * 32);
; #pragma unroll
;       for (int i = 0; i < MI; ++i) {
;         const bf16x8 a = *(const bf16x8*)(As + i * 16 * LDT + ks * 32);
; #pragma unroll
;         for (int j = 0; j < NJ; ++j) acc[i][j] = SWAP ? mfma16(b[j], a, acc[i][j]) : mfma16(a, b[j], acc[i][j]);
;       }
;     }
;     __syncthreads();
;   }
.Lgm7_main:
	ds_read_b128 v[242:245], v177 offset:4608
	s_waitcnt lgkmcnt(4)
	v_mfma_f32_16x16x32_bf16 v[156:159], v[178:181], v[194:197], v[156:159]
	s_waitcnt lgkmcnt(3)
	v_mfma_f32_16x16x32_bf16 v[152:155], v[182:185], v[194:197], v[152:155]
	s_waitcnt lgkmcnt(2)
	v_mfma_f32_16x16x32_bf16 v[148:151], v[186:189], v[194:197], v[148:151]
	s_and_b32 s24, s21, 1
	s_min_u32 s22, s21, 41
	s_xor_b32 s23, s24, 1
	s_mul_i32 s23, s23, 0x12000
	v_add3_u32 v250, s23, v172, v170
	s_waitcnt vmcnt(7)
	ds_write_b128 v250, v[112:115]
	s_waitcnt lgkmcnt(2)
	v_mfma_f32_16x16x32_bf16 v[144:147], v[190:193], v[194:197], v[144:147]
	ds_read_b128 v[246:249], v177 offset:6912
	v_mfma_f32_16x16x32_bf16 v[108:111], v[178:181], v[198:201], v[108:111]
	s_lshl_b32 s25, s22, 7
	s_add_u32 s22, s6, s25
	v_add3_u32 v251, s23, v173, v170
	v_add3_u32 v252, s23, v174, v170
	v_add3_u32 v253, s23, v175, v170
	s_addc_u32 s23, s7, 0
	v_lshl_add_u64 v[112:113], s[22:23], 0, v[162:163]
	s_nop 0
	global_load_dwordx4 v[112:115], v[112:113], off offset:256
	v_mfma_f32_16x16x32_bf16 v[104:107], v[182:185], v[198:201], v[104:107]
	v_mfma_f32_16x16x32_bf16 v[100:103], v[186:189], v[198:201], v[100:103]
	v_mfma_f32_16x16x32_bf16 v[96:99], v[190:193], v[198:201], v[96:99]
	ds_read_b128 v[194:197], v177 offset:9216
	s_waitcnt lgkmcnt(3)
	v_mfma_f32_16x16x32_bf16 v[92:95], v[178:181], v[242:245], v[92:95]
	s_waitcnt vmcnt(7)
	ds_write_b128 v251, v[116:119]
	v_mfma_f32_16x16x32_bf16 v[88:91], v[182:185], v[242:245], v[88:91]
	v_mfma_f32_16x16x32_bf16 v[84:87], v[186:189], v[242:245], v[84:87]
	v_lshl_add_u64 v[116:117], s[22:23], 0, v[164:165]
	s_nop 0
	global_load_dwordx4 v[116:119], v[116:117], off offset:256
	v_mfma_f32_16x16x32_bf16 v[80:83], v[190:193], v[242:245], v[80:83]
	ds_read_b128 v[198:201], v177 offset:11520
	s_waitcnt lgkmcnt(3)
	v_mfma_f32_16x16x32_bf16 v[76:79], v[178:181], v[246:249], v[76:79]
	v_mfma_f32_16x16x32_bf16 v[72:75], v[182:185], v[246:249], v[72:75]
	v_mfma_f32_16x16x32_bf16 v[68:71], v[186:189], v[246:249], v[68:71]
	s_waitcnt vmcnt(7)
	ds_write_b128 v252, v[120:123]
	v_mfma_f32_16x16x32_bf16 v[64:67], v[190:193], v[246:249], v[64:67]
	ds_read_b128 v[242:245], v177 offset:13824
	s_waitcnt lgkmcnt(4)
	v_mfma_f32_16x16x32_bf16 v[60:63], v[178:181], v[194:197], v[60:63]
	v_lshl_add_u64 v[120:121], s[22:23], 0, v[166:167]
	s_nop 0
	global_load_dwordx4 v[120:123], v[120:121], off offset:256
	v_mfma_f32_16x16x32_bf16 v[56:59], v[182:185], v[194:197], v[56:59]
	v_mfma_f32_16x16x32_bf16 v[52:55], v[186:189], v[194:197], v[52:55]
	v_mfma_f32_16x16x32_bf16 v[48:51], v[190:193], v[194:197], v[48:51]
	ds_read_b128 v[246:249], v177 offset:16128
	s_waitcnt lgkmcnt(3)
	v_mfma_f32_16x16x32_bf16 v[44:47], v[178:181], v[198:201], v[44:47]
	s_waitcnt vmcnt(7)
	ds_write_b128 v253, v[124:127]
	v_mfma_f32_16x16x32_bf16 v[40:43], v[182:185], v[198:201], v[40:43]
	v_mfma_f32_16x16x32_bf16 v[36:39], v[186:189], v[198:201], v[36:39]
	v_lshl_add_u64 v[124:125], s[22:23], 0, v[168:169]
	s_nop 0
	global_load_dwordx4 v[124:127], v[124:125], off offset:256
	v_mfma_f32_16x16x32_bf16 v[32:35], v[190:193], v[198:201], v[32:35]
	ds_read_b128 v[194:197], v177 offset:64
	s_waitcnt lgkmcnt(3)
	v_mfma_f32_16x16x32_bf16 v[28:31], v[178:181], v[242:245], v[28:31]
	v_mfma_f32_16x16x32_bf16 v[24:27], v[182:185], v[242:245], v[24:27]
	v_mfma_f32_16x16x32_bf16 v[20:23], v[186:189], v[242:245], v[20:23]
	s_waitcnt vmcnt(7)
	ds_write_b128 v250, v[128:131] offset:36864
	v_mfma_f32_16x16x32_bf16 v[16:19], v[190:193], v[242:245], v[16:19]
	ds_read_b128 v[198:201], v177 offset:2368
	s_waitcnt lgkmcnt(4)
	v_mfma_f32_16x16x32_bf16 v[8:11], v[178:181], v[246:249], v[8:11]
	ds_read_b128 v[178:181], v202 offset:36928
	s_add_u32 s22, s8, s25
	s_addc_u32 s23, s9, 0
	v_lshl_add_u64 v[128:129], s[22:23], 0, v[162:163]
	s_nop 0
	global_load_dwordx4 v[128:131], v[128:129], off offset:256
	v_mfma_f32_16x16x32_bf16 v[4:7], v[182:185], v[246:249], v[4:7]
	ds_read_b128 v[182:185], v202 offset:39232
	v_mfma_f32_16x16x32_bf16 v[0:3], v[186:189], v[246:249], v[0:3]
	ds_read_b128 v[186:189], v202 offset:41536
	v_mfma_f32_16x16x32_bf16 v[12:15], v[190:193], v[246:249], v[12:15]
	ds_read_b128 v[190:193], v202 offset:43840
	ds_read_b128 v[242:245], v177 offset:4672
	s_waitcnt lgkmcnt(4)
; DI f32x4 mfma16(bf16x8 a, bf16x8 b, f32x4 c) { return __builtin_amdgcn_mfma_f32_16x16x32_bf16(a, b, c, 0, 0, 0); }
; template <int MI, int NJ, bool SWAP, class AP, class BP>
; DI void gemm_main(f32x4 (&acc)[MI][NJ], const AP& ap, int a_kstep, const BP& bp, int b_kstep, int nk, bf16_t* smem) {
;     ...
;   for (int kt = 0; kt < nk; ++kt) {
;     const int buf = kt & 1;
;     sstore(buf ^ 1);
;     gload(kt + 2 < nk ? kt + 2 : nk - 1);
;     __builtin_amdgcn_sched_barrier(0);
;     const bf16_t* As = smem + buf * L::STAGE + (wm * 16 * MI + l15) * LDT + quad * 8;
;     const bf16_t* Bs = smem + buf * L::STAGE + L::A_ELEMS + (wn * 16 * NJ + l15) * LDT + quad * 8;
; #pragma unroll
;     for (int ks = 0; ks < 2; ++ks) {
;       if (MI * NJ >= 32 && ks == 1) asm volatile("" ::: "memory");
;       bf16x8 b[NJ];
; #pragma unroll
;       for (int j = 0; j < NJ; ++j) b[j] = *(const bf16x8*)(Bs + j * 16 * LDT + ks * 32);
; #pragma unroll
;       for (int i = 0; i < MI; ++i) {
;         const bf16x8 a = *(const bf16x8*)(As + i * 16 * LDT + ks * 32);
; #pragma unroll
;         for (int j = 0; j < NJ; ++j) acc[i][j] = SWAP ? mfma16(b[j], a, acc[i][j]) : mfma16(a, b[j], acc[i][j]);
;       }
;     }
;     __syncthreads();
;   }
	v_mfma_f32_16x16x32_bf16 v[156:159], v[178:181], v[194:197], v[156:159]
	s_waitcnt vmcnt(7)
	ds_write_b128 v251, v[132:135] offset:36864
	s_waitcnt lgkmcnt(4)
	v_mfma_f32_16x16x32_bf16 v[152:155], v[182:185], v[194:197], v[152:155]
	s_waitcnt lgkmcnt(3)
	v_mfma_f32_16x16x32_bf16 v[148:151], v[186:189], v[194:197], v[148:151]
	v_lshl_add_u64 v[132:133], s[22:23], 0, v[164:165]
	s_nop 0
	global_load_dwordx4 v[132:135], v[132:133], off offset:256
	s_waitcnt lgkmcnt(2)
	v_mfma_f32_16x16x32_bf16 v[144:147], v[190:193], v[194:197], v[144:147]
	ds_read_b128 v[246:249], v177 offset:6976
	v_mfma_f32_16x16x32_bf16 v[108:111], v[178:181], v[198:201], v[108:111]
	v_mfma_f32_16x16x32_bf16 v[104:107], v[182:185], v[198:201], v[104:107]
	v_mfma_f32_16x16x32_bf16 v[100:103], v[186:189], v[198:201], v[100:103]
	s_waitcnt vmcnt(7)
	ds_write_b128 v252, v[136:139] offset:36864
	v_mfma_f32_16x16x32_bf16 v[96:99], v[190:193], v[198:201], v[96:99]
	ds_read_b128 v[194:197], v177 offset:9280
	s_waitcnt lgkmcnt(4)
	v_mfma_f32_16x16x32_bf16 v[92:95], v[178:181], v[242:245], v[92:95]
	v_lshl_add_u64 v[136:137], s[22:23], 0, v[166:167]
	s_nop 0
	global_load_dwordx4 v[136:139], v[136:137], off offset:256
	v_mfma_f32_16x16x32_bf16 v[88:91], v[182:185], v[242:245], v[88:91]
	v_mfma_f32_16x16x32_bf16 v[84:87], v[186:189], v[242:245], v[84:87]
	v_mfma_f32_16x16x32_bf16 v[80:83], v[190:193], v[242:245], v[80:83]
	ds_read_b128 v[198:201], v177 offset:11584
	s_waitcnt lgkmcnt(3)
	v_mfma_f32_16x16x32_bf16 v[76:79], v[178:181], v[246:249], v[76:79]
	s_waitcnt vmcnt(7)
	ds_write_b128 v253, v[140:143] offset:36864
	v_mfma_f32_16x16x32_bf16 v[72:75], v[182:185], v[246:249], v[72:75]
	v_mfma_f32_16x16x32_bf16 v[68:71], v[186:189], v[246:249], v[68:71]
	v_lshl_add_u64 v[140:141], s[22:23], 0, v[168:169]
	s_nop 0
	global_load_dwordx4 v[140:143], v[140:141], off offset:256
	v_mfma_f32_16x16x32_bf16 v[64:67], v[190:193], v[246:249], v[64:67]
	ds_read_b128 v[242:245], v177 offset:13888
	s_waitcnt lgkmcnt(3)
	v_mfma_f32_16x16x32_bf16 v[60:63], v[178:181], v[194:197], v[60:63]
	v_mfma_f32_16x16x32_bf16 v[56:59], v[182:185], v[194:197], v[56:59]
	v_mfma_f32_16x16x32_bf16 v[52:55], v[186:189], v[194:197], v[52:55]
	v_mfma_f32_16x16x32_bf16 v[48:51], v[190:193], v[194:197], v[48:51]
	ds_read_b128 v[246:249], v177 offset:16192
	s_waitcnt lgkmcnt(3)
	v_mfma_f32_16x16x32_bf16 v[44:47], v[178:181], v[198:201], v[44:47]
	v_mfma_f32_16x16x32_bf16 v[40:43], v[182:185], v[198:201], v[40:43]
	v_mfma_f32_16x16x32_bf16 v[36:39], v[186:189], v[198:201], v[36:39]
	v_mfma_f32_16x16x32_bf16 v[32:35], v[190:193], v[198:201], v[32:35]
	s_add_i32 s21, s21, 1
	s_and_b32 s98, s21, 1
	s_mul_i32 s98, s98, 0x12000
	v_add3_u32 v202, s98, v160, v176
	v_add3_u32 v177, s98, v171, v176
	s_cmp_lg_u32 s21, 44
	s_waitcnt lgkmcnt(0)
	s_barrier
	s_cbranch_scc0 .Lgm7_exit
	ds_read_b128 v[194:197], v177
	ds_read_b128 v[198:201], v177 offset:2304
	v_mfma_f32_16x16x32_bf16 v[28:31], v[178:181], v[242:245], v[28:31]
	v_mfma_f32_16x16x32_bf16 v[8:11], v[178:181], v[246:249], v[8:11]
	ds_read_b128 v[178:181], v202 offset:36864
	v_mfma_f32_16x16x32_bf16 v[24:27], v[182:185], v[242:245], v[24:27]
	v_mfma_f32_16x16x32_bf16 v[4:7], v[182:185], v[246:249], v[4:7]
	ds_read_b128 v[182:185], v202 offset:39168
	v_mfma_f32_16x16x32_bf16 v[20:23], v[186:189], v[242:245], v[20:23]
	v_mfma_f32_16x16x32_bf16 v[0:3], v[186:189], v[246:249], v[0:3]
	ds_read_b128 v[186:189], v202 offset:41472
	v_mfma_f32_16x16x32_bf16 v[16:19], v[190:193], v[242:245], v[16:19]
	v_mfma_f32_16x16x32_bf16 v[12:15], v[190:193], v[246:249], v[12:15]
	ds_read_b128 v[190:193], v202 offset:43776
	s_branch .Lgm7_main

; DI f32x4 mfma16(bf16x8 a, bf16x8 b, f32x4 c) { return __builtin_amdgcn_mfma_f32_16x16x32_bf16(a, b, c, 0, 0, 0); }
; template <int MI, int NJ, bool SWAP, class AP, class BP>
; DI void gemm_main(f32x4 (&acc)[MI][NJ], const AP& ap, int a_kstep, const BP& bp, int b_kstep, int nk, bf16_t* smem) {
;     ...
;   for (int kt = 0; kt < nk; ++kt) {
;     const int buf = kt & 1;
;     sstore(buf ^ 1);
;     gload(kt + 2 < nk ? kt + 2 : nk - 1);
;     __builtin_amdgcn_sched_barrier(0);
;     const bf16_t* As = smem + buf * L::STAGE + (wm * 16 * MI + l15) * LDT + quad * 8;
;     const bf16_t* Bs = smem + buf * L::STAGE + L::A_ELEMS + (wn * 16 * NJ + l15) * LDT + quad * 8;
; #pragma unroll
;     for (int ks = 0; ks < 2; ++ks) {
;       if (MI * NJ >= 32 && ks == 1) asm volatile("" ::: "memory");
;       bf16x8 b[NJ];
; #pragma unroll
;       for (int j = 0; j < NJ; ++j) b[j] = *(const bf16x8*)(Bs + j * 16 * LDT + ks * 32);
; #pragma unroll
;       for (int i = 0; i < MI; ++i) {
;         const bf16x8 a = *(const bf16x8*)(As + i * 16 * LDT + ks * 32);
; #pragma unroll
;         for (int j = 0; j < NJ; ++j) acc[i][j] = SWAP ? mfma16(b[j], a, acc[i][j]) : mfma16(a, b[j], acc[i][j]);
;       }
;     }
;     __syncthreads();
;   }
.Lgm8_main:
	ds_read_b128 v[246:249], v210 offset:4608
	s_waitcnt lgkmcnt(4)
	v_mfma_f32_16x16x32_bf16 v[124:127], v[190:193], v[206:209], v[124:127]
	s_waitcnt lgkmcnt(3)
	v_mfma_f32_16x16x32_bf16 v[120:123], v[194:197], v[206:209], v[120:123]
	s_waitcnt lgkmcnt(2)
	v_mfma_f32_16x16x32_bf16 v[116:119], v[198:201], v[206:209], v[116:119]
	s_and_b32 s5, s4, 1
	s_xor_b32 s23, s5, 1
	s_mul_i32 s23, s23, 0x12000
	v_add3_u32 v254, s23, v185, v183
	s_waitcnt vmcnt(7)
	ds_write_b128 v254, v[128:131]
	s_waitcnt lgkmcnt(2)
	v_mfma_f32_16x16x32_bf16 v[112:115], v[202:205], v[206:209], v[112:115]
	ds_read_b128 v[250:253], v210 offset:6912
	v_mfma_f32_16x16x32_bf16 v[108:111], v[190:193], v[242:245], v[108:111]
	s_min_u32 s99, s4, 13
	s_lshl_b32 s99, s99, 7
	s_add_u32 s26, s0, s99
	s_addc_u32 s27, s1, 0
	v_lshl_add_u64 v[128:129], s[26:27], 0, v[162:163]
	s_nop 0
	global_load_dwordx4 v[128:131], v[128:129], off offset:256
	v_mfma_f32_16x16x32_bf16 v[104:107], v[194:197], v[242:245], v[104:107]
	v_mfma_f32_16x16x32_bf16 v[100:103], v[198:201], v[242:245], v[100:103]
	v_mfma_f32_16x16x32_bf16 v[96:99], v[202:205], v[242:245], v[96:99]
	ds_read_b128 v[206:209], v210 offset:9216
	s_waitcnt lgkmcnt(3)
	v_mfma_f32_16x16x32_bf16 v[92:95], v[190:193], v[246:249], v[92:95]
	v_add3_u32 v238, s23, v187, v183
	s_waitcnt vmcnt(7)
	ds_write_b128 v238, v[132:135]
	v_mfma_f32_16x16x32_bf16 v[88:91], v[194:197], v[246:249], v[88:91]
	v_mfma_f32_16x16x32_bf16 v[84:87], v[198:201], v[246:249], v[84:87]
	v_lshl_add_u64 v[132:133], s[26:27], 0, v[164:165]
	s_nop 0
	global_load_dwordx4 v[132:135], v[132:133], off offset:256
	v_mfma_f32_16x16x32_bf16 v[80:83], v[202:205], v[246:249], v[80:83]
	ds_read_b128 v[242:245], v210 offset:11520
	s_waitcnt lgkmcnt(3)
	v_mfma_f32_16x16x32_bf16 v[76:79], v[190:193], v[250:253], v[76:79]
	v_mfma_f32_16x16x32_bf16 v[72:75], v[194:197], v[250:253], v[72:75]
	v_mfma_f32_16x16x32_bf16 v[68:71], v[198:201], v[250:253], v[68:71]
	v_add3_u32 v239, s23, v188, v183
	s_waitcnt vmcnt(7)
	ds_write_b128 v239, v[136:139]
	v_mfma_f32_16x16x32_bf16 v[64:67], v[202:205], v[250:253], v[64:67]
	ds_read_b128 v[246:249], v210 offset:13824
	s_waitcnt lgkmcnt(4)
	v_mfma_f32_16x16x32_bf16 v[60:63], v[190:193], v[206:209], v[60:63]
	v_lshl_add_u64 v[136:137], s[26:27], 0, v[166:167]
	s_nop 0
	global_load_dwordx4 v[136:139], v[136:137], off offset:256
	v_mfma_f32_16x16x32_bf16 v[56:59], v[194:197], v[206:209], v[56:59]
	v_mfma_f32_16x16x32_bf16 v[52:55], v[198:201], v[206:209], v[52:55]
	v_mfma_f32_16x16x32_bf16 v[48:51], v[202:205], v[206:209], v[48:51]
	ds_read_b128 v[250:253], v210 offset:16128
	s_waitcnt lgkmcnt(3)
	v_mfma_f32_16x16x32_bf16 v[44:47], v[190:193], v[242:245], v[44:47]
	v_add3_u32 v255, s23, v189, v183
	s_waitcnt vmcnt(7)
	ds_write_b128 v255, v[140:143]
	v_mfma_f32_16x16x32_bf16 v[40:43], v[194:197], v[242:245], v[40:43]
	v_mfma_f32_16x16x32_bf16 v[36:39], v[198:201], v[242:245], v[36:39]
	v_lshl_add_u64 v[140:141], s[26:27], 0, v[168:169]
	s_nop 0
	global_load_dwordx4 v[140:143], v[140:141], off offset:256
	v_mfma_f32_16x16x32_bf16 v[32:35], v[202:205], v[242:245], v[32:35]
	ds_read_b128 v[206:209], v210 offset:64
	s_waitcnt lgkmcnt(3)
	v_mfma_f32_16x16x32_bf16 v[28:31], v[190:193], v[246:249], v[28:31]
	v_mfma_f32_16x16x32_bf16 v[24:27], v[194:197], v[246:249], v[24:27]
	v_mfma_f32_16x16x32_bf16 v[20:23], v[198:201], v[246:249], v[20:23]
	s_waitcnt vmcnt(7)
	ds_write_b128 v254, v[144:147] offset:36864
	v_mfma_f32_16x16x32_bf16 v[16:19], v[202:205], v[246:249], v[16:19]
	ds_read_b128 v[242:245], v210 offset:2368
	s_waitcnt lgkmcnt(4)
	v_mfma_f32_16x16x32_bf16 v[12:15], v[190:193], v[250:253], v[12:15]
	ds_read_b128 v[190:193], v211 offset:36928
	s_add_u32 s26, s2, s99
	s_addc_u32 s27, s3, 0
	v_lshl_add_u64 v[144:145], s[26:27], 0, v[162:163]
	s_nop 0
	global_load_dwordx4 v[144:147], v[144:145], off offset:256
	v_mfma_f32_16x16x32_bf16 v[8:11], v[194:197], v[250:253], v[8:11]
	ds_read_b128 v[194:197], v211 offset:39232
	v_mfma_f32_16x16x32_bf16 v[4:7], v[198:201], v[250:253], v[4:7]
	ds_read_b128 v[198:201], v211 offset:41536
	v_mfma_f32_16x16x32_bf16 v[0:3], v[202:205], v[250:253], v[0:3]
	ds_read_b128 v[202:205], v211 offset:43840
	ds_read_b128 v[246:249], v210 offset:4672
	s_waitcnt lgkmcnt(4)
; DI f32x4 mfma16(bf16x8 a, bf16x8 b, f32x4 c) { return __builtin_amdgcn_mfma_f32_16x16x32_bf16(a, b, c, 0, 0, 0); }
; template <int MI, int NJ, bool SWAP, class AP, class BP>
; DI void gemm_main(f32x4 (&acc)[MI][NJ], const AP& ap, int a_kstep, const BP& bp, int b_kstep, int nk, bf16_t* smem) {
;     ...
;   for (int kt = 0; kt < nk; ++kt) {
;     const int buf = kt & 1;
;     sstore(buf ^ 1);
;     gload(kt + 2 < nk ? kt + 2 : nk - 1);
;     __builtin_amdgcn_sched_barrier(0);
;     const bf16_t* As = smem + buf * L::STAGE + (wm * 16 * MI + l15) * LDT + quad * 8;
;     const bf16_t* Bs = smem + buf * L::STAGE + L::A_ELEMS + (wn * 16 * NJ + l15) * LDT + quad * 8;
; #pragma unroll
;     for (int ks = 0; ks < 2; ++ks) {
;       if (MI * NJ >= 32 && ks == 1) asm volatile("" ::: "memory");
;       bf16x8 b[NJ];
; #pragma unroll
;       for (int j = 0; j < NJ; ++j) b[j] = *(const bf16x8*)(Bs + j * 16 * LDT + ks * 32);
; #pragma unroll
;       for (int i = 0; i < MI; ++i) {
;         const bf16x8 a = *(const bf16x8*)(As + i * 16 * LDT + ks * 32);
; #pragma unroll
;         for (int j = 0; j < NJ; ++j) acc[i][j] = SWAP ? mfma16(b[j], a, acc[i][j]) : mfma16(a, b[j], acc[i][j]);
;       }
;     }
;     __syncthreads();
;   }
	v_mfma_f32_16x16x32_bf16 v[124:127], v[190:193], v[206:209], v[124:127]
	s_waitcnt vmcnt(7)
	ds_write_b128 v238, v[148:151] offset:36864
	s_waitcnt lgkmcnt(4)
	v_mfma_f32_16x16x32_bf16 v[120:123], v[194:197], v[206:209], v[120:123]
	s_waitcnt lgkmcnt(3)
	v_mfma_f32_16x16x32_bf16 v[116:119], v[198:201], v[206:209], v[116:119]
	v_lshl_add_u64 v[148:149], s[26:27], 0, v[164:165]
	s_nop 0
	global_load_dwordx4 v[148:151], v[148:149], off offset:256
	s_waitcnt lgkmcnt(2)
	v_mfma_f32_16x16x32_bf16 v[112:115], v[202:205], v[206:209], v[112:115]
	ds_read_b128 v[250:253], v210 offset:6976
	v_mfma_f32_16x16x32_bf16 v[108:111], v[190:193], v[242:245], v[108:111]
	v_mfma_f32_16x16x32_bf16 v[104:107], v[194:197], v[242:245], v[104:107]
	v_mfma_f32_16x16x32_bf16 v[100:103], v[198:201], v[242:245], v[100:103]
	s_waitcnt vmcnt(7)
	ds_write_b128 v239, v[152:155] offset:36864
	v_mfma_f32_16x16x32_bf16 v[96:99], v[202:205], v[242:245], v[96:99]
	ds_read_b128 v[206:209], v210 offset:9280
	s_waitcnt lgkmcnt(4)
	v_mfma_f32_16x16x32_bf16 v[92:95], v[190:193], v[246:249], v[92:95]
	v_lshl_add_u64 v[152:153], s[26:27], 0, v[166:167]
	s_nop 0
	global_load_dwordx4 v[152:155], v[152:153], off offset:256
	v_mfma_f32_16x16x32_bf16 v[88:91], v[194:197], v[246:249], v[88:91]
	v_mfma_f32_16x16x32_bf16 v[84:87], v[198:201], v[246:249], v[84:87]
	v_mfma_f32_16x16x32_bf16 v[80:83], v[202:205], v[246:249], v[80:83]
	ds_read_b128 v[242:245], v210 offset:11584
	s_waitcnt lgkmcnt(3)
	v_mfma_f32_16x16x32_bf16 v[76:79], v[190:193], v[250:253], v[76:79]
	s_waitcnt vmcnt(7)
	ds_write_b128 v255, v[156:159] offset:36864
	v_mfma_f32_16x16x32_bf16 v[72:75], v[194:197], v[250:253], v[72:75]
	v_mfma_f32_16x16x32_bf16 v[68:71], v[198:201], v[250:253], v[68:71]
	v_lshl_add_u64 v[156:157], s[26:27], 0, v[168:169]
	s_nop 0
	global_load_dwordx4 v[156:159], v[156:157], off offset:256
	v_mfma_f32_16x16x32_bf16 v[64:67], v[202:205], v[250:253], v[64:67]
	ds_read_b128 v[246:249], v210 offset:13888
	s_waitcnt lgkmcnt(3)
	v_mfma_f32_16x16x32_bf16 v[60:63], v[190:193], v[206:209], v[60:63]
	v_mfma_f32_16x16x32_bf16 v[56:59], v[194:197], v[206:209], v[56:59]
	v_mfma_f32_16x16x32_bf16 v[52:55], v[198:201], v[206:209], v[52:55]
	v_mfma_f32_16x16x32_bf16 v[48:51], v[202:205], v[206:209], v[48:51]
	ds_read_b128 v[250:253], v210 offset:16192
	s_waitcnt lgkmcnt(3)
	v_mfma_f32_16x16x32_bf16 v[44:47], v[190:193], v[242:245], v[44:47]
	v_mfma_f32_16x16x32_bf16 v[40:43], v[194:197], v[242:245], v[40:43]
	v_mfma_f32_16x16x32_bf16 v[36:39], v[198:201], v[242:245], v[36:39]
	v_mfma_f32_16x16x32_bf16 v[32:35], v[202:205], v[242:245], v[32:35]
	s_add_i32 s4, s4, 1
	s_and_b32 s98, s4, 1
	s_mul_i32 s98, s98, 0x12000
	v_add3_u32 v210, s98, v184, v186
	v_add3_u32 v211, s98, v160, v186
	s_cmp_lg_u32 s4, 16
	s_waitcnt lgkmcnt(0)
	s_barrier
	s_cbranch_scc0 .Lgm8_exit
	ds_read_b128 v[206:209], v210
	ds_read_b128 v[242:245], v210 offset:2304
	v_mfma_f32_16x16x32_bf16 v[28:31], v[190:193], v[246:249], v[28:31]
	v_mfma_f32_16x16x32_bf16 v[12:15], v[190:193], v[250:253], v[12:15]
	ds_read_b128 v[190:193], v211 offset:36864
	v_mfma_f32_16x16x32_bf16 v[24:27], v[194:197], v[246:249], v[24:27]
	v_mfma_f32_16x16x32_bf16 v[8:11], v[194:197], v[250:253], v[8:11]
	ds_read_b128 v[194:197], v211 offset:39168
	v_mfma_f32_16x16x32_bf16 v[20:23], v[198:201], v[246:249], v[20:23]
	v_mfma_f32_16x16x32_bf16 v[4:7], v[198:201], v[250:253], v[4:7]
	ds_read_b128 v[198:201], v211 offset:41472
	v_mfma_f32_16x16x32_bf16 v[16:19], v[202:205], v[246:249], v[16:19]
	v_mfma_f32_16x16x32_bf16 v[0:3], v[202:205], v[250:253], v[0:3]
	ds_read_b128 v[202:205], v211 offset:43776
	s_branch .Lgm8_main

; DI f32x4 mfma16(bf16x8 a, bf16x8 b, f32x4 c) { return __builtin_amdgcn_mfma_f32_16x16x32_bf16(a, b, c, 0, 0, 0); }
; template <int MI, int NJ, bool SWAP, class AP, class BP>
; DI void gemm_main(f32x4 (&acc)[MI][NJ], const AP& ap, int a_kstep, const BP& bp, int b_kstep, int nk, bf16_t* smem) {
;     ...
;   for (int kt = 0; kt < nk; ++kt) {
;     const int buf = kt & 1;
;     sstore(buf ^ 1);
;     gload(kt + 2 < nk ? kt + 2 : nk - 1);
;     __builtin_amdgcn_sched_barrier(0);
;     const bf16_t* As = smem + buf * L::STAGE + (wm * 16 * MI + l15) * LDT + quad * 8;
;     const bf16_t* Bs = smem + buf * L::STAGE + L::A_ELEMS + (wn * 16 * NJ + l15) * LDT + quad * 8;
; #pragma unroll
;     for (int ks = 0; ks < 2; ++ks) {
;       if (MI * NJ >= 32 && ks == 1) asm volatile("" ::: "memory");
;       bf16x8 b[NJ];
; #pragma unroll
;       for (int j = 0; j < NJ; ++j) b[j] = *(const bf16x8*)(Bs + j * 16 * LDT + ks * 32);
; #pragma unroll
;       for (int i = 0; i < MI; ++i) {
;         const bf16x8 a = *(const bf16x8*)(As + i * 16 * LDT + ks * 32);
; #pragma unroll
;         for (int j = 0; j < NJ; ++j) acc[i][j] = SWAP ? mfma16(b[j], a, acc[i][j]) : mfma16(a, b[j], acc[i][j]);
;       }
;     }
;     __syncthreads();
;   }
.Lgm9_main:
	ds_read_b128 v[246:249], v210 offset:4608
	s_waitcnt lgkmcnt(4)
	v_mfma_f32_16x16x32_bf16 v[124:127], v[206:209], v[190:193], v[124:127]
	s_waitcnt lgkmcnt(3)
	v_mfma_f32_16x16x32_bf16 v[120:123], v[206:209], v[194:197], v[120:123]
	s_waitcnt lgkmcnt(2)
	v_mfma_f32_16x16x32_bf16 v[116:119], v[206:209], v[198:201], v[116:119]
	s_waitcnt lgkmcnt(1)
	v_mfma_f32_16x16x32_bf16 v[112:115], v[206:209], v[202:205], v[112:115]
	s_and_b32 s5, s4, 1
	s_xor_b32 s23, s5, 1
	s_mul_i32 s23, s23, 0x12000
	v_lshlrev_b32_e32 v254, 1, v160
	v_add3_u32 v254, s23, v254, v184
	s_waitcnt vmcnt(7)
	ds_write_b128 v254, v[140:143]
	ds_read_b128 v[250:253], v210 offset:6912
	v_mfma_f32_16x16x32_bf16 v[108:111], v[242:245], v[190:193], v[108:111]
	v_mfma_f32_16x16x32_bf16 v[104:107], v[242:245], v[194:197], v[104:107]
	v_mfma_f32_16x16x32_bf16 v[100:103], v[242:245], v[198:201], v[100:103]
	v_mfma_f32_16x16x32_bf16 v[96:99], v[242:245], v[202:205], v[96:99]
	v_lshlrev_b32_e32 v140, 1, v185
	v_add3_u32 v140, s23, v140, v184
	s_waitcnt vmcnt(6)
	ds_write_b128 v140, v[136:139]
	ds_read_b128 v[206:209], v210 offset:9216
	s_waitcnt lgkmcnt(4)
	v_mfma_f32_16x16x32_bf16 v[92:95], v[246:249], v[190:193], v[92:95]
	v_mfma_f32_16x16x32_bf16 v[88:91], v[246:249], v[194:197], v[88:91]
	v_mfma_f32_16x16x32_bf16 v[84:87], v[246:249], v[198:201], v[84:87]
	v_mfma_f32_16x16x32_bf16 v[80:83], v[246:249], v[202:205], v[80:83]
	ds_read_b128 v[242:245], v210 offset:11520
	s_waitcnt lgkmcnt(3)
	v_mfma_f32_16x16x32_bf16 v[76:79], v[250:253], v[190:193], v[76:79]
	v_lshlrev_b32_e32 v136, 1, v186
	v_add3_u32 v136, s23, v136, v184
	s_waitcnt vmcnt(5)
	ds_write_b128 v136, v[132:135]
	v_mfma_f32_16x16x32_bf16 v[72:75], v[250:253], v[194:197], v[72:75]
	v_mfma_f32_16x16x32_bf16 v[68:71], v[250:253], v[198:201], v[68:71]
	v_mfma_f32_16x16x32_bf16 v[64:67], v[250:253], v[202:205], v[64:67]
	ds_read_b128 v[246:249], v210 offset:13824
	s_waitcnt lgkmcnt(3)
	v_mfma_f32_16x16x32_bf16 v[60:63], v[206:209], v[190:193], v[60:63]
	v_lshlrev_b32_e32 v132, 1, v187
	v_add3_u32 v132, s23, v132, v184
	s_min_u32 s23, s4, 13
	s_lshl_b32 s23, s23, 7
	s_add_u32 s26, s0, s23
	s_addc_u32 s27, s1, 0
	s_waitcnt vmcnt(4)
	ds_write_b128 v132, v[128:131]
	v_mfma_f32_16x16x32_bf16 v[56:59], v[206:209], v[194:197], v[56:59]
	v_mfma_f32_16x16x32_bf16 v[52:55], v[206:209], v[198:201], v[52:55]
	v_mfma_f32_16x16x32_bf16 v[48:51], v[206:209], v[202:205], v[48:51]
	ds_read_b128 v[250:253], v210 offset:16128
	s_waitcnt lgkmcnt(4)
	v_mfma_f32_16x16x32_bf16 v[44:47], v[242:245], v[190:193], v[44:47]
	s_waitcnt vmcnt(3)
	ds_write_b128 v254, v[144:147] offset:36864
	v_mfma_f32_16x16x32_bf16 v[40:43], v[242:245], v[194:197], v[40:43]
	v_mfma_f32_16x16x32_bf16 v[36:39], v[242:245], v[198:201], v[36:39]
	v_mfma_f32_16x16x32_bf16 v[32:35], v[242:245], v[202:205], v[32:35]
	ds_read_b128 v[206:209], v210 offset:64
	s_waitcnt lgkmcnt(4)
	v_mfma_f32_16x16x32_bf16 v[28:31], v[246:249], v[190:193], v[28:31]
	s_waitcnt vmcnt(2)
	ds_write_b128 v140, v[148:151] offset:36864
	v_mfma_f32_16x16x32_bf16 v[24:27], v[246:249], v[194:197], v[24:27]
	v_mfma_f32_16x16x32_bf16 v[20:23], v[246:249], v[198:201], v[20:23]
	v_mfma_f32_16x16x32_bf16 v[16:19], v[246:249], v[202:205], v[16:19]
	ds_read_b128 v[242:245], v210 offset:2368
	s_waitcnt lgkmcnt(4)
	v_mfma_f32_16x16x32_bf16 v[12:15], v[250:253], v[190:193], v[12:15]
	ds_read_b128 v[190:193], v211 offset:36928
	s_waitcnt vmcnt(1)
	ds_write_b128 v136, v[152:155] offset:36864
	v_mfma_f32_16x16x32_bf16 v[8:11], v[250:253], v[194:197], v[8:11]
	ds_read_b128 v[194:197], v211 offset:39232
	v_mfma_f32_16x16x32_bf16 v[4:7], v[250:253], v[198:201], v[4:7]
	ds_read_b128 v[198:201], v211 offset:41536
	v_mfma_f32_16x16x32_bf16 v[0:3], v[250:253], v[202:205], v[0:3]
	ds_read_b128 v[202:205], v211 offset:43840
	ds_read_b128 v[246:249], v210 offset:4672
	s_waitcnt lgkmcnt(5)
	v_mfma_f32_16x16x32_bf16 v[124:127], v[206:209], v[190:193], v[124:127]
	s_waitcnt lgkmcnt(3)
; DI f32x4 mfma16(bf16x8 a, bf16x8 b, f32x4 c) { return __builtin_amdgcn_mfma_f32_16x16x32_bf16(a, b, c, 0, 0, 0); }
; template <int MI, int NJ, bool SWAP, class AP, class BP>
; DI void gemm_main(f32x4 (&acc)[MI][NJ], const AP& ap, int a_kstep, const BP& bp, int b_kstep, int nk, bf16_t* smem) {
;     ...
;   for (int kt = 0; kt < nk; ++kt) {
;     const int buf = kt & 1;
;     sstore(buf ^ 1);
;     gload(kt + 2 < nk ? kt + 2 : nk - 1);
;     __builtin_amdgcn_sched_barrier(0);
;     const bf16_t* As = smem + buf * L::STAGE + (wm * 16 * MI + l15) * LDT + quad * 8;
;     const bf16_t* Bs = smem + buf * L::STAGE + L::A_ELEMS + (wn * 16 * NJ + l15) * LDT + quad * 8;
; #pragma unroll
;     for (int ks = 0; ks < 2; ++ks) {
;       if (MI * NJ >= 32 && ks == 1) asm volatile("" ::: "memory");
;       bf16x8 b[NJ];
; #pragma unroll
;       for (int j = 0; j < NJ; ++j) b[j] = *(const bf16x8*)(Bs + j * 16 * LDT + ks * 32);
; #pragma unroll
;       for (int i = 0; i < MI; ++i) {
;         const bf16x8 a = *(const bf16x8*)(As + i * 16 * LDT + ks * 32);
; #pragma unroll
;         for (int j = 0; j < NJ; ++j) acc[i][j] = SWAP ? mfma16(b[j], a, acc[i][j]) : mfma16(a, b[j], acc[i][j]);
;       }
;     }
;     __syncthreads();
;   }
	v_mfma_f32_16x16x32_bf16 v[120:123], v[206:209], v[194:197], v[120:123]
	s_waitcnt vmcnt(0)
	ds_write_b128 v132, v[156:159] offset:36864
	s_waitcnt lgkmcnt(3)
	v_mfma_f32_16x16x32_bf16 v[116:119], v[206:209], v[198:201], v[116:119]
	s_waitcnt lgkmcnt(2)
	v_mfma_f32_16x16x32_bf16 v[112:115], v[206:209], v[202:205], v[112:115]
	v_lshl_add_u64 v[128:129], s[26:27], 0, v[162:163]
	global_load_dwordx4 v[140:143], v[128:129], off offset:256
	ds_read_b128 v[250:253], v210 offset:6976
	v_mfma_f32_16x16x32_bf16 v[108:111], v[242:245], v[190:193], v[108:111]
	v_mfma_f32_16x16x32_bf16 v[104:107], v[242:245], v[194:197], v[104:107]
	v_lshl_add_u64 v[128:129], s[26:27], 0, v[164:165]
	global_load_dwordx4 v[136:139], v[128:129], off offset:256
	v_mfma_f32_16x16x32_bf16 v[100:103], v[242:245], v[198:201], v[100:103]
	v_mfma_f32_16x16x32_bf16 v[96:99], v[242:245], v[202:205], v[96:99]
	ds_read_b128 v[206:209], v210 offset:9280
	s_waitcnt lgkmcnt(3)
	v_mfma_f32_16x16x32_bf16 v[92:95], v[246:249], v[190:193], v[92:95]
	v_lshl_add_u64 v[128:129], s[26:27], 0, v[166:167]
	global_load_dwordx4 v[132:135], v[128:129], off offset:256
	v_mfma_f32_16x16x32_bf16 v[88:91], v[246:249], v[194:197], v[88:91]
	v_mfma_f32_16x16x32_bf16 v[84:87], v[246:249], v[198:201], v[84:87]
	v_lshl_add_u64 v[128:129], s[26:27], 0, v[168:169]
	s_add_u32 s26, s2, s23
	s_addc_u32 s27, s3, 0
	v_lshl_add_u64 v[144:145], s[26:27], 0, v[162:163]
	v_lshl_add_u64 v[148:149], s[26:27], 0, v[164:165]
	v_lshl_add_u64 v[152:153], s[26:27], 0, v[166:167]
	v_lshl_add_u64 v[156:157], s[26:27], 0, v[168:169]
	global_load_dwordx4 v[128:131], v[128:129], off offset:256
	v_mfma_f32_16x16x32_bf16 v[80:83], v[246:249], v[202:205], v[80:83]
	ds_read_b128 v[242:245], v210 offset:11584
	s_waitcnt lgkmcnt(2)
	v_mfma_f32_16x16x32_bf16 v[76:79], v[250:253], v[190:193], v[76:79]
	v_mfma_f32_16x16x32_bf16 v[72:75], v[250:253], v[194:197], v[72:75]
	s_nop 0
	global_load_dwordx4 v[144:147], v[144:145], off offset:256
	v_mfma_f32_16x16x32_bf16 v[68:71], v[250:253], v[198:201], v[68:71]
	v_mfma_f32_16x16x32_bf16 v[64:67], v[250:253], v[202:205], v[64:67]
	s_nop 0
	global_load_dwordx4 v[148:151], v[148:149], off offset:256
	ds_read_b128 v[246:249], v210 offset:13888
	s_waitcnt lgkmcnt(2)
	v_mfma_f32_16x16x32_bf16 v[60:63], v[206:209], v[190:193], v[60:63]
	v_mfma_f32_16x16x32_bf16 v[56:59], v[206:209], v[194:197], v[56:59]
	v_mfma_f32_16x16x32_bf16 v[52:55], v[206:209], v[198:201], v[52:55]
	s_nop 0
	global_load_dwordx4 v[152:155], v[152:153], off offset:256
	v_mfma_f32_16x16x32_bf16 v[48:51], v[206:209], v[202:205], v[48:51]
	ds_read_b128 v[250:253], v210 offset:16192
	s_waitcnt lgkmcnt(2)
	v_mfma_f32_16x16x32_bf16 v[44:47], v[242:245], v[190:193], v[44:47]
	s_nop 0
	global_load_dwordx4 v[156:159], v[156:157], off offset:256
	v_mfma_f32_16x16x32_bf16 v[40:43], v[242:245], v[194:197], v[40:43]
	v_mfma_f32_16x16x32_bf16 v[36:39], v[242:245], v[198:201], v[36:39]
	v_mfma_f32_16x16x32_bf16 v[32:35], v[242:245], v[202:205], v[32:35]
	s_add_i32 s4, s4, 1
	s_and_b32 s98, s4, 1
	s_mul_i32 s98, s98, 0x12000
	v_add3_u32 v210, s98, v188, v189
	v_add3_u32 v211, s98, v183, v189
	s_cmp_lg_u32 s4, 16
	s_waitcnt lgkmcnt(0)
	s_barrier
	s_cbranch_scc0 .Lgm9_exit
	ds_read_b128 v[206:209], v210
	ds_read_b128 v[242:245], v210 offset:2304
	v_mfma_f32_16x16x32_bf16 v[28:31], v[246:249], v[190:193], v[28:31]
	v_mfma_f32_16x16x32_bf16 v[12:15], v[250:253], v[190:193], v[12:15]
	ds_read_b128 v[190:193], v211 offset:36864
	v_mfma_f32_16x16x32_bf16 v[24:27], v[246:249], v[194:197], v[24:27]
	v_mfma_f32_16x16x32_bf16 v[8:11], v[250:253], v[194:197], v[8:11]
	ds_read_b128 v[194:197], v211 offset:39168
	v_mfma_f32_16x16x32_bf16 v[20:23], v[246:249], v[198:201], v[20:23]
	v_mfma_f32_16x16x32_bf16 v[4:7], v[250:253], v[198:201], v[4:7]
	ds_read_b128 v[198:201], v211 offset:41472
	v_mfma_f32_16x16x32_bf16 v[16:19], v[246:249], v[202:205], v[16:19]
	v_mfma_f32_16x16x32_bf16 v[0:3], v[250:253], v[202:205], v[0:3]
	ds_read_b128 v[202:205], v211 offset:43776
	s_branch .Lgm9_main

; DI f32x4 mfma16(bf16x8 a, bf16x8 b, f32x4 c) { return __builtin_amdgcn_mfma_f32_16x16x32_bf16(a, b, c, 0, 0, 0); }
; template <int MI, int NJ, bool SWAP, class AP, class BP>
; DI void gemm_main(f32x4 (&acc)[MI][NJ], const AP& ap, int a_kstep, const BP& bp, int b_kstep, int nk, bf16_t* smem) {
;     ...
;   for (int kt = 0; kt < nk; ++kt) {
;     const int buf = kt & 1;
;     sstore(buf ^ 1);
;     gload(kt + 2 < nk ? kt + 2 : nk - 1);
;     __builtin_amdgcn_sched_barrier(0);
;     const bf16_t* As = smem + buf * L::STAGE + (wm * 16 * MI + l15) * LDT + quad * 8;
;     const bf16_t* Bs = smem + buf * L::STAGE + L::A_ELEMS + (wn * 16 * NJ + l15) * LDT + quad * 8;
; #pragma unroll
;     for (int ks = 0; ks < 2; ++ks) {
;       if (MI * NJ >= 32 && ks == 1) asm volatile("" ::: "memory");
;       bf16x8 b[NJ];
; #pragma unroll
;       for (int j = 0; j < NJ; ++j) b[j] = *(const bf16x8*)(Bs + j * 16 * LDT + ks * 32);
; #pragma unroll
;       for (int i = 0; i < MI; ++i) {
;         const bf16x8 a = *(const bf16x8*)(As + i * 16 * LDT + ks * 32);
; #pragma unroll
;         for (int j = 0; j < NJ; ++j) acc[i][j] = SWAP ? mfma16(b[j], a, acc[i][j]) : mfma16(a, b[j], acc[i][j]);
;       }
;     }
;     __syncthreads();
;   }
.Lgm10_main:
	ds_read_b128 v[246:249], v198 offset:4608
	s_waitcnt lgkmcnt(4)
	v_mfma_f32_16x16x32_bf16 v[156:159], v[178:181], v[194:197], v[156:159]
	s_waitcnt lgkmcnt(3)
	v_mfma_f32_16x16x32_bf16 v[152:155], v[182:185], v[194:197], v[152:155]
	s_waitcnt lgkmcnt(2)
	v_mfma_f32_16x16x32_bf16 v[148:151], v[186:189], v[194:197], v[148:151]
	s_and_b32 s33, s8, 1
	s_xor_b32 s37, s33, 1
	s_mul_i32 s37, s37, 0x12000
	v_add3_u32 v254, s37, v173, v171
	s_waitcnt vmcnt(7)
	ds_write_b128 v254, v[112:115]
	s_waitcnt lgkmcnt(2)
	v_mfma_f32_16x16x32_bf16 v[144:147], v[190:193], v[194:197], v[144:147]
	ds_read_b128 v[250:253], v198 offset:6912
	v_mfma_f32_16x16x32_bf16 v[108:111], v[178:181], v[242:245], v[108:111]
	s_min_u32 s99, s8, 3
	s_lshl_b32 s99, s99, 7
	s_add_u32 s38, s0, s99
	s_addc_u32 s39, s1, 0
	v_lshl_add_u64 v[112:113], s[38:39], 0, v[162:163]
	s_nop 0
	global_load_dwordx4 v[112:115], v[112:113], off offset:256
	v_mfma_f32_16x16x32_bf16 v[104:107], v[182:185], v[242:245], v[104:107]
	v_mfma_f32_16x16x32_bf16 v[100:103], v[186:189], v[242:245], v[100:103]
	v_mfma_f32_16x16x32_bf16 v[96:99], v[190:193], v[242:245], v[96:99]
	ds_read_b128 v[194:197], v198 offset:9216
	s_waitcnt lgkmcnt(3)
	v_mfma_f32_16x16x32_bf16 v[92:95], v[178:181], v[246:249], v[92:95]
	v_add3_u32 v238, s37, v174, v171
	s_waitcnt vmcnt(6)
	ds_write_b128 v238, v[116:119]
	v_mfma_f32_16x16x32_bf16 v[88:91], v[182:185], v[246:249], v[88:91]
	v_mfma_f32_16x16x32_bf16 v[84:87], v[186:189], v[246:249], v[84:87]
	v_lshl_add_u64 v[116:117], s[38:39], 0, v[164:165]
	s_nop 0
	global_load_dwordx4 v[116:119], v[116:117], off offset:256
	v_mfma_f32_16x16x32_bf16 v[80:83], v[190:193], v[246:249], v[80:83]
	ds_read_b128 v[242:245], v198 offset:11520
	s_waitcnt lgkmcnt(3)
	v_mfma_f32_16x16x32_bf16 v[76:79], v[178:181], v[250:253], v[76:79]
	v_mfma_f32_16x16x32_bf16 v[72:75], v[182:185], v[250:253], v[72:75]
	v_mfma_f32_16x16x32_bf16 v[68:71], v[186:189], v[250:253], v[68:71]
	v_add3_u32 v239, s37, v175, v171
	s_waitcnt vmcnt(6)
	ds_write_b128 v239, v[120:123]
	v_mfma_f32_16x16x32_bf16 v[64:67], v[190:193], v[250:253], v[64:67]
	ds_read_b128 v[246:249], v198 offset:13824
	s_waitcnt lgkmcnt(4)
	v_mfma_f32_16x16x32_bf16 v[60:63], v[178:181], v[194:197], v[60:63]
	v_lshl_add_u64 v[120:121], s[38:39], 0, v[166:167]
	s_nop 0
	global_load_dwordx4 v[120:123], v[120:121], off offset:256
	v_mfma_f32_16x16x32_bf16 v[56:59], v[182:185], v[194:197], v[56:59]
	v_mfma_f32_16x16x32_bf16 v[52:55], v[186:189], v[194:197], v[52:55]
	v_mfma_f32_16x16x32_bf16 v[48:51], v[190:193], v[194:197], v[48:51]
	ds_read_b128 v[250:253], v198 offset:16128
	s_waitcnt lgkmcnt(3)
	v_mfma_f32_16x16x32_bf16 v[44:47], v[178:181], v[242:245], v[44:47]
	v_add3_u32 v255, s37, v176, v171
	s_waitcnt vmcnt(6)
	ds_write_b128 v255, v[124:127]
	v_mfma_f32_16x16x32_bf16 v[40:43], v[182:185], v[242:245], v[40:43]
	v_mfma_f32_16x16x32_bf16 v[36:39], v[186:189], v[242:245], v[36:39]
	v_lshl_add_u64 v[124:125], s[38:39], 0, v[168:169]
	s_nop 0
	global_load_dwordx4 v[124:127], v[124:125], off offset:256
	v_mfma_f32_16x16x32_bf16 v[32:35], v[190:193], v[242:245], v[32:35]
	ds_read_b128 v[194:197], v198 offset:64
	s_waitcnt lgkmcnt(3)
	v_mfma_f32_16x16x32_bf16 v[28:31], v[178:181], v[246:249], v[28:31]
	v_mfma_f32_16x16x32_bf16 v[24:27], v[182:185], v[246:249], v[24:27]
	v_mfma_f32_16x16x32_bf16 v[20:23], v[186:189], v[246:249], v[20:23]
	ds_write_b128 v254, v[128:131] offset:36864
	v_mfma_f32_16x16x32_bf16 v[16:19], v[190:193], v[246:249], v[16:19]
	ds_read_b128 v[242:245], v198 offset:2368
	s_waitcnt lgkmcnt(4)
	v_mfma_f32_16x16x32_bf16 v[12:15], v[178:181], v[250:253], v[12:15]
	ds_read_b128 v[178:181], v199 offset:36928
	s_add_u32 s38, s2, s99
	s_addc_u32 s39, s3, 0
	v_lshl_add_u64 v[128:129], s[38:39], 0, v[162:163]
	s_nop 0
	global_load_dwordx4 v[128:131], v[128:129], off offset:256
	v_mfma_f32_16x16x32_bf16 v[8:11], v[182:185], v[250:253], v[8:11]
	ds_read_b128 v[182:185], v199 offset:39232
	v_mfma_f32_16x16x32_bf16 v[4:7], v[186:189], v[250:253], v[4:7]
	ds_read_b128 v[186:189], v199 offset:41536
	v_mfma_f32_16x16x32_bf16 v[0:3], v[190:193], v[250:253], v[0:3]
	ds_read_b128 v[190:193], v199 offset:43840
	ds_read_b128 v[246:249], v198 offset:4672
	s_waitcnt lgkmcnt(4)
; DI f32x4 mfma16(bf16x8 a, bf16x8 b, f32x4 c) { return __builtin_amdgcn_mfma_f32_16x16x32_bf16(a, b, c, 0, 0, 0); }
; template <int MI, int NJ, bool SWAP, class AP, class BP>
; DI void gemm_main(f32x4 (&acc)[MI][NJ], const AP& ap, int a_kstep, const BP& bp, int b_kstep, int nk, bf16_t* smem) {
;     ...
;   for (int kt = 0; kt < nk; ++kt) {
;     const int buf = kt & 1;
;     sstore(buf ^ 1);
;     gload(kt + 2 < nk ? kt + 2 : nk - 1);
;     __builtin_amdgcn_sched_barrier(0);
;     const bf16_t* As = smem + buf * L::STAGE + (wm * 16 * MI + l15) * LDT + quad * 8;
;     const bf16_t* Bs = smem + buf * L::STAGE + L::A_ELEMS + (wn * 16 * NJ + l15) * LDT + quad * 8;
; #pragma unroll
;     for (int ks = 0; ks < 2; ++ks) {
;       if (MI * NJ >= 32 && ks == 1) asm volatile("" ::: "memory");
;       bf16x8 b[NJ];
; #pragma unroll
;       for (int j = 0; j < NJ; ++j) b[j] = *(const bf16x8*)(Bs + j * 16 * LDT + ks * 32);
; #pragma unroll
;       for (int i = 0; i < MI; ++i) {
;         const bf16x8 a = *(const bf16x8*)(As + i * 16 * LDT + ks * 32);
; #pragma unroll
;         for (int j = 0; j < NJ; ++j) acc[i][j] = SWAP ? mfma16(b[j], a, acc[i][j]) : mfma16(a, b[j], acc[i][j]);
;       }
;     }
;     __syncthreads();
;   }
	v_mfma_f32_16x16x32_bf16 v[156:159], v[178:181], v[194:197], v[156:159]
	s_waitcnt vmcnt(7)
	ds_write_b128 v238, v[132:135] offset:36864
	s_waitcnt lgkmcnt(4)
	v_mfma_f32_16x16x32_bf16 v[152:155], v[182:185], v[194:197], v[152:155]
	s_waitcnt lgkmcnt(3)
	v_mfma_f32_16x16x32_bf16 v[148:151], v[186:189], v[194:197], v[148:151]
	v_lshl_add_u64 v[132:133], s[38:39], 0, v[164:165]
	s_nop 0
	global_load_dwordx4 v[132:135], v[132:133], off offset:256
	s_waitcnt lgkmcnt(2)
	v_mfma_f32_16x16x32_bf16 v[144:147], v[190:193], v[194:197], v[144:147]
	ds_read_b128 v[250:253], v198 offset:6976
	v_mfma_f32_16x16x32_bf16 v[108:111], v[178:181], v[242:245], v[108:111]
	v_mfma_f32_16x16x32_bf16 v[104:107], v[182:185], v[242:245], v[104:107]
	v_mfma_f32_16x16x32_bf16 v[100:103], v[186:189], v[242:245], v[100:103]
	s_waitcnt vmcnt(7)
	ds_write_b128 v239, v[136:139] offset:36864
	v_mfma_f32_16x16x32_bf16 v[96:99], v[190:193], v[242:245], v[96:99]
	ds_read_b128 v[194:197], v198 offset:9280
	s_waitcnt lgkmcnt(4)
	v_mfma_f32_16x16x32_bf16 v[92:95], v[178:181], v[246:249], v[92:95]
	v_lshl_add_u64 v[136:137], s[38:39], 0, v[166:167]
	s_nop 0
	global_load_dwordx4 v[136:139], v[136:137], off offset:256
	v_mfma_f32_16x16x32_bf16 v[88:91], v[182:185], v[246:249], v[88:91]
	v_mfma_f32_16x16x32_bf16 v[84:87], v[186:189], v[246:249], v[84:87]
	v_mfma_f32_16x16x32_bf16 v[80:83], v[190:193], v[246:249], v[80:83]
	ds_read_b128 v[242:245], v198 offset:11584
	s_waitcnt lgkmcnt(3)
	v_mfma_f32_16x16x32_bf16 v[76:79], v[178:181], v[250:253], v[76:79]
	s_waitcnt vmcnt(7)
	ds_write_b128 v255, v[140:143] offset:36864
	v_mfma_f32_16x16x32_bf16 v[72:75], v[182:185], v[250:253], v[72:75]
	v_mfma_f32_16x16x32_bf16 v[68:71], v[186:189], v[250:253], v[68:71]
	v_lshl_add_u64 v[140:141], s[38:39], 0, v[168:169]
	s_nop 0
	global_load_dwordx4 v[140:143], v[140:141], off offset:256
	v_mfma_f32_16x16x32_bf16 v[64:67], v[190:193], v[250:253], v[64:67]
	ds_read_b128 v[246:249], v198 offset:13888
	s_waitcnt lgkmcnt(3)
	v_mfma_f32_16x16x32_bf16 v[60:63], v[178:181], v[194:197], v[60:63]
	v_mfma_f32_16x16x32_bf16 v[56:59], v[182:185], v[194:197], v[56:59]
	v_mfma_f32_16x16x32_bf16 v[52:55], v[186:189], v[194:197], v[52:55]
	v_mfma_f32_16x16x32_bf16 v[48:51], v[190:193], v[194:197], v[48:51]
	ds_read_b128 v[250:253], v198 offset:16192
	s_waitcnt lgkmcnt(3)
	v_mfma_f32_16x16x32_bf16 v[44:47], v[178:181], v[242:245], v[44:47]
	v_mfma_f32_16x16x32_bf16 v[40:43], v[182:185], v[242:245], v[40:43]
	v_mfma_f32_16x16x32_bf16 v[36:39], v[186:189], v[242:245], v[36:39]
	v_mfma_f32_16x16x32_bf16 v[32:35], v[190:193], v[242:245], v[32:35]
	s_add_i32 s8, s8, 1
	s_and_b32 s98, s8, 1
	s_mul_i32 s98, s98, 0x12000
	v_add3_u32 v198, s98, v172, v177
	v_add3_u32 v199, s98, v160, v177
	s_cmp_lg_u32 s8, 6
	s_waitcnt lgkmcnt(0)
	s_barrier
	s_cbranch_scc0 .Lgm10_exit
	ds_read_b128 v[194:197], v198
	ds_read_b128 v[242:245], v198 offset:2304
	v_mfma_f32_16x16x32_bf16 v[28:31], v[178:181], v[246:249], v[28:31]
	v_mfma_f32_16x16x32_bf16 v[12:15], v[178:181], v[250:253], v[12:15]
	ds_read_b128 v[178:181], v199 offset:36864
	v_mfma_f32_16x16x32_bf16 v[24:27], v[182:185], v[246:249], v[24:27]
	v_mfma_f32_16x16x32_bf16 v[8:11], v[182:185], v[250:253], v[8:11]
	ds_read_b128 v[182:185], v199 offset:39168
	v_mfma_f32_16x16x32_bf16 v[20:23], v[186:189], v[246:249], v[20:23]
	v_mfma_f32_16x16x32_bf16 v[4:7], v[186:189], v[250:253], v[4:7]
	ds_read_b128 v[186:189], v199 offset:41472
	v_mfma_f32_16x16x32_bf16 v[16:19], v[190:193], v[246:249], v[16:19]
	v_mfma_f32_16x16x32_bf16 v[0:3], v[190:193], v[250:253], v[0:3]
	ds_read_b128 v[190:193], v199 offset:43776
	s_branch .Lgm10_main

; DI f32x4 mfma16(bf16x8 a, bf16x8 b, f32x4 c) { return __builtin_amdgcn_mfma_f32_16x16x32_bf16(a, b, c, 0, 0, 0); }
; template <int MI, int NJ, bool SWAP, class AP, class BP>
; DI void gemm_main(f32x4 (&acc)[MI][NJ], const AP& ap, int a_kstep, const BP& bp, int b_kstep, int nk, bf16_t* smem) {
;     ...
;   auto sstore = [&](int buf) {
;     bf16_t* As = smem + buf * L::STAGE; bf16_t* Bs = As + L::A_ELEMS;
; #pragma unroll
;     for (int i = 0; i < CA; ++i) { const int c = tid + NTHR * i; *(u32x4*)(As + (c >> 3) * LDT + (c & 7) * 8) = oka[i] ? ra[i] : (u32x4){0u, 0u, 0u, 0u}; }
; #pragma unroll
;     for (int i = 0; i < CB; ++i) { const int c = tid + NTHR * i; *(u32x4*)(Bs + (c >> 3) * LDT + (c & 7) * 8) = rb[i]; }
;   };
;   gload(0); sstore(0); gload(nk > 1 ? 1 : 0); __syncthreads();
; #pragma unroll 1
;   for (int kt = 0; kt < nk; ++kt) {
;     const int buf = kt & 1;
;     sstore(buf ^ 1);
;     gload(kt + 2 < nk ? kt + 2 : nk - 1);
;     __builtin_amdgcn_sched_barrier(0);
;     const bf16_t* As = smem + buf * L::STAGE + (wm * 16 * MI + l15) * LDT + quad * 8;
;     const bf16_t* Bs = smem + buf * L::STAGE + L::A_ELEMS + (wn * 16 * NJ + l15) * LDT + quad * 8;
; #pragma unroll
;     for (int ks = 0; ks < 2; ++ks) {
;       if (MI * NJ >= 32 && ks == 1) asm volatile("" ::: "memory");
;       bf16x8 b[NJ];
; #pragma unroll
;       for (int j = 0; j < NJ; ++j) b[j] = *(const bf16x8*)(Bs + j * 16 * LDT + ks * 32);
; #pragma unroll
;       for (int i = 0; i < MI; ++i) {
;         const bf16x8 a = *(const bf16x8*)(As + i * 16 * LDT + ks * 32);
; #pragma unroll
;         for (int j = 0; j < NJ; ++j) acc[i][j] = SWAP ? mfma16(b[j], a, acc[i][j]) : mfma16(a, b[j], acc[i][j]);
;       }
.Lgm11_main:
	ds_read_b128 v[246:249], v198 offset:4608
	s_waitcnt lgkmcnt(4)
	v_mfma_f32_16x16x32_bf16 v[156:159], v[178:181], v[194:197], v[156:159]
	s_waitcnt lgkmcnt(3)
	v_mfma_f32_16x16x32_bf16 v[152:155], v[182:185], v[194:197], v[152:155]
	s_waitcnt lgkmcnt(2)
	v_mfma_f32_16x16x32_bf16 v[148:151], v[186:189], v[194:197], v[148:151]
	s_waitcnt lgkmcnt(1)
	v_mfma_f32_16x16x32_bf16 v[144:147], v[190:193], v[194:197], v[144:147]
	s_and_b32 s37, s33, 1
	s_xor_b32 s38, s37, 1
	s_mul_i32 s38, s38, 0x12000
	v_lshlrev_b32_e32 v254, 1, v160
	v_add3_u32 v254, s38, v254, v172
	s_waitcnt vmcnt(7)
	ds_write_b128 v254, v[124:127]
	ds_read_b128 v[250:253], v198 offset:6912
	v_mfma_f32_16x16x32_bf16 v[108:111], v[178:181], v[242:245], v[108:111]
	v_mfma_f32_16x16x32_bf16 v[104:107], v[182:185], v[242:245], v[104:107]
	v_mfma_f32_16x16x32_bf16 v[100:103], v[186:189], v[242:245], v[100:103]
	v_mfma_f32_16x16x32_bf16 v[96:99], v[190:193], v[242:245], v[96:99]
	v_lshlrev_b32_e32 v124, 1, v173
	v_add3_u32 v124, s38, v124, v172
	s_waitcnt vmcnt(6)
	ds_write_b128 v124, v[120:123]
	ds_read_b128 v[194:197], v198 offset:9216
	s_waitcnt lgkmcnt(4)
	v_mfma_f32_16x16x32_bf16 v[92:95], v[178:181], v[246:249], v[92:95]
	v_mfma_f32_16x16x32_bf16 v[88:91], v[182:185], v[246:249], v[88:91]
	v_mfma_f32_16x16x32_bf16 v[84:87], v[186:189], v[246:249], v[84:87]
	v_mfma_f32_16x16x32_bf16 v[80:83], v[190:193], v[246:249], v[80:83]
	ds_read_b128 v[242:245], v198 offset:11520
	s_waitcnt lgkmcnt(3)
	v_mfma_f32_16x16x32_bf16 v[76:79], v[178:181], v[250:253], v[76:79]
	v_lshlrev_b32_e32 v120, 1, v174
	v_add3_u32 v120, s38, v120, v172
	s_cmp_eq_u32 s33, 0
	s_waitcnt vmcnt(5)
	ds_write_b128 v120, v[116:119]
	v_mfma_f32_16x16x32_bf16 v[72:75], v[182:185], v[250:253], v[72:75]
	v_mfma_f32_16x16x32_bf16 v[68:71], v[186:189], v[250:253], v[68:71]
	v_mfma_f32_16x16x32_bf16 v[64:67], v[190:193], v[250:253], v[64:67]
	ds_read_b128 v[246:249], v198 offset:13824
	s_waitcnt lgkmcnt(3)
	v_mfma_f32_16x16x32_bf16 v[60:63], v[178:181], v[194:197], v[60:63]
	v_lshlrev_b32_e32 v116, 1, v175
	s_cselect_b32 s40, s31, 0x180
	v_add3_u32 v116, s38, v116, v172
	s_add_u32 s38, s0, s40
	s_addc_u32 s39, s1, 0
	s_waitcnt vmcnt(4)
	ds_write_b128 v116, v[112:115]
	v_mfma_f32_16x16x32_bf16 v[56:59], v[182:185], v[194:197], v[56:59]
	v_mfma_f32_16x16x32_bf16 v[52:55], v[186:189], v[194:197], v[52:55]
	v_mfma_f32_16x16x32_bf16 v[48:51], v[190:193], v[194:197], v[48:51]
	ds_read_b128 v[250:253], v198 offset:16128
	s_waitcnt lgkmcnt(4)
	v_mfma_f32_16x16x32_bf16 v[44:47], v[178:181], v[242:245], v[44:47]
	s_waitcnt vmcnt(3)
	ds_write_b128 v254, v[128:131] offset:36864
	v_mfma_f32_16x16x32_bf16 v[40:43], v[182:185], v[242:245], v[40:43]
	v_mfma_f32_16x16x32_bf16 v[36:39], v[186:189], v[242:245], v[36:39]
	v_mfma_f32_16x16x32_bf16 v[32:35], v[190:193], v[242:245], v[32:35]
	ds_read_b128 v[194:197], v198 offset:64
	s_waitcnt lgkmcnt(4)
	v_mfma_f32_16x16x32_bf16 v[28:31], v[178:181], v[246:249], v[28:31]
	s_waitcnt vmcnt(2)
	ds_write_b128 v124, v[132:135] offset:36864
	v_mfma_f32_16x16x32_bf16 v[24:27], v[182:185], v[246:249], v[24:27]
	v_mfma_f32_16x16x32_bf16 v[20:23], v[186:189], v[246:249], v[20:23]
	v_mfma_f32_16x16x32_bf16 v[16:19], v[190:193], v[246:249], v[16:19]
	ds_read_b128 v[242:245], v198 offset:2368
	s_waitcnt lgkmcnt(4)
	v_mfma_f32_16x16x32_bf16 v[12:15], v[178:181], v[250:253], v[12:15]
	ds_read_b128 v[178:181], v199 offset:36928
	s_waitcnt vmcnt(1)
	ds_write_b128 v120, v[136:139] offset:36864
	v_mfma_f32_16x16x32_bf16 v[8:11], v[182:185], v[250:253], v[8:11]
	ds_read_b128 v[182:185], v199 offset:39232
	v_mfma_f32_16x16x32_bf16 v[4:7], v[186:189], v[250:253], v[4:7]
	ds_read_b128 v[186:189], v199 offset:41536
	v_mfma_f32_16x16x32_bf16 v[0:3], v[190:193], v[250:253], v[0:3]
	ds_read_b128 v[190:193], v199 offset:43840
	ds_read_b128 v[246:249], v198 offset:4672
	s_waitcnt lgkmcnt(5)
	v_mfma_f32_16x16x32_bf16 v[156:159], v[178:181], v[194:197], v[156:159]
	s_waitcnt lgkmcnt(3)
; DI f32x4 mfma16(bf16x8 a, bf16x8 b, f32x4 c) { return __builtin_amdgcn_mfma_f32_16x16x32_bf16(a, b, c, 0, 0, 0); }
; template <int MI, int NJ, bool SWAP, class AP, class BP>
; DI void gemm_main(f32x4 (&acc)[MI][NJ], const AP& ap, int a_kstep, const BP& bp, int b_kstep, int nk, bf16_t* smem) {
;     ...
;   auto gload = [&](int kt) {
;     const bf16_t* ab = ap.base + (size_t)kt * a_kstep; const bf16_t* bb = bp.base + (size_t)kt * b_kstep;
; #pragma unroll
;     for (int i = 0; i < CA; ++i) ra[i] = *(const u32x4*)(ab + pa[i]);
; #pragma unroll
;     for (int i = 0; i < CB; ++i) rb[i] = *(const u32x4*)(bb + pb[i]);
;   };
;   auto sstore = [&](int buf) {
;     bf16_t* As = smem + buf * L::STAGE; bf16_t* Bs = As + L::A_ELEMS;
; #pragma unroll
;     for (int i = 0; i < CA; ++i) { const int c = tid + NTHR * i; *(u32x4*)(As + (c >> 3) * LDT + (c & 7) * 8) = oka[i] ? ra[i] : (u32x4){0u, 0u, 0u, 0u}; }
; #pragma unroll
;     for (int i = 0; i < CB; ++i) { const int c = tid + NTHR * i; *(u32x4*)(Bs + (c >> 3) * LDT + (c & 7) * 8) = rb[i]; }
;   };
;   gload(0); sstore(0); gload(nk > 1 ? 1 : 0); __syncthreads();
; #pragma unroll 1
;   for (int kt = 0; kt < nk; ++kt) {
;     const int buf = kt & 1;
;     sstore(buf ^ 1);
;     gload(kt + 2 < nk ? kt + 2 : nk - 1);
;     __builtin_amdgcn_sched_barrier(0);
;     const bf16_t* As = smem + buf * L::STAGE + (wm * 16 * MI + l15) * LDT + quad * 8;
;     const bf16_t* Bs = smem + buf * L::STAGE + L::A_ELEMS + (wn * 16 * NJ + l15) * LDT + quad * 8;
; #pragma unroll
;     for (int ks = 0; ks < 2; ++ks) {
;       if (MI * NJ >= 32 && ks == 1) asm volatile("" ::: "memory");
;       bf16x8 b[NJ];
; #pragma unroll
;       for (int j = 0; j < NJ; ++j) b[j] = *(const bf16x8*)(Bs + j * 16 * LDT + ks * 32);
; #pragma unroll
;       for (int i = 0; i < MI; ++i) {
;         const bf16x8 a = *(const bf16x8*)(As + i * 16 * LDT + ks * 32);
; #pragma unroll
;         for (int j = 0; j < NJ; ++j) acc[i][j] = SWAP ? mfma16(b[j], a, acc[i][j]) : mfma16(a, b[j], acc[i][j]);
;       }
;     }
;     __syncthreads();
;   }
	v_mfma_f32_16x16x32_bf16 v[152:155], v[182:185], v[194:197], v[152:155]
	s_waitcnt vmcnt(0)
	ds_write_b128 v116, v[140:143] offset:36864
	s_waitcnt lgkmcnt(3)
	v_mfma_f32_16x16x32_bf16 v[148:151], v[186:189], v[194:197], v[148:151]
	s_waitcnt lgkmcnt(2)
	v_mfma_f32_16x16x32_bf16 v[144:147], v[190:193], v[194:197], v[144:147]
	v_lshl_add_u64 v[112:113], s[38:39], 0, v[162:163]
	global_load_dwordx4 v[124:127], v[112:113], off
	ds_read_b128 v[250:253], v198 offset:6976
	v_mfma_f32_16x16x32_bf16 v[108:111], v[178:181], v[242:245], v[108:111]
	v_mfma_f32_16x16x32_bf16 v[104:107], v[182:185], v[242:245], v[104:107]
	v_lshl_add_u64 v[112:113], s[38:39], 0, v[164:165]
	global_load_dwordx4 v[120:123], v[112:113], off
	v_mfma_f32_16x16x32_bf16 v[100:103], v[186:189], v[242:245], v[100:103]
	v_mfma_f32_16x16x32_bf16 v[96:99], v[190:193], v[242:245], v[96:99]
	ds_read_b128 v[194:197], v198 offset:9280
	s_waitcnt lgkmcnt(3)
	v_mfma_f32_16x16x32_bf16 v[92:95], v[178:181], v[246:249], v[92:95]
	v_lshl_add_u64 v[112:113], s[38:39], 0, v[166:167]
	global_load_dwordx4 v[116:119], v[112:113], off
	v_mfma_f32_16x16x32_bf16 v[88:91], v[182:185], v[246:249], v[88:91]
	v_mfma_f32_16x16x32_bf16 v[84:87], v[186:189], v[246:249], v[84:87]
	v_lshl_add_u64 v[112:113], s[38:39], 0, v[168:169]
	s_add_u32 s38, s2, s40
	s_addc_u32 s39, s3, 0
	v_lshl_add_u64 v[128:129], s[38:39], 0, v[162:163]
	v_lshl_add_u64 v[132:133], s[38:39], 0, v[164:165]
	v_lshl_add_u64 v[136:137], s[38:39], 0, v[166:167]
	v_lshl_add_u64 v[140:141], s[38:39], 0, v[168:169]
	global_load_dwordx4 v[112:115], v[112:113], off
	v_mfma_f32_16x16x32_bf16 v[80:83], v[190:193], v[246:249], v[80:83]
	ds_read_b128 v[242:245], v198 offset:11584
	s_waitcnt lgkmcnt(2)
	v_mfma_f32_16x16x32_bf16 v[76:79], v[178:181], v[250:253], v[76:79]
	v_mfma_f32_16x16x32_bf16 v[72:75], v[182:185], v[250:253], v[72:75]
	s_nop 0
	global_load_dwordx4 v[128:131], v[128:129], off
	v_mfma_f32_16x16x32_bf16 v[68:71], v[186:189], v[250:253], v[68:71]
	v_mfma_f32_16x16x32_bf16 v[64:67], v[190:193], v[250:253], v[64:67]
	s_nop 0
	global_load_dwordx4 v[132:135], v[132:133], off
	ds_read_b128 v[246:249], v198 offset:13888
	s_waitcnt lgkmcnt(2)
	v_mfma_f32_16x16x32_bf16 v[60:63], v[178:181], v[194:197], v[60:63]
	v_mfma_f32_16x16x32_bf16 v[56:59], v[182:185], v[194:197], v[56:59]
	v_mfma_f32_16x16x32_bf16 v[52:55], v[186:189], v[194:197], v[52:55]
	s_nop 0
	global_load_dwordx4 v[136:139], v[136:137], off
	v_mfma_f32_16x16x32_bf16 v[48:51], v[190:193], v[194:197], v[48:51]
	ds_read_b128 v[250:253], v198 offset:16192
	s_waitcnt lgkmcnt(2)
	v_mfma_f32_16x16x32_bf16 v[44:47], v[178:181], v[242:245], v[44:47]
	s_nop 0
	global_load_dwordx4 v[140:143], v[140:141], off
	v_mfma_f32_16x16x32_bf16 v[40:43], v[182:185], v[242:245], v[40:43]
	v_mfma_f32_16x16x32_bf16 v[36:39], v[186:189], v[242:245], v[36:39]
	v_mfma_f32_16x16x32_bf16 v[32:35], v[190:193], v[242:245], v[32:35]
	s_add_i32 s33, s33, 1
	s_and_b32 s98, s33, 1
	s_mul_i32 s98, s98, 0x12000
	v_add3_u32 v198, s98, v176, v177
	v_add3_u32 v199, s98, v171, v177
	s_cmp_lg_u32 s33, 4
	s_waitcnt lgkmcnt(0)
	s_barrier
	s_cbranch_scc0 .Lgm11_exit
	ds_read_b128 v[194:197], v198
	ds_read_b128 v[242:245], v198 offset:2304
	v_mfma_f32_16x16x32_bf16 v[28:31], v[178:181], v[246:249], v[28:31]
	v_mfma_f32_16x16x32_bf16 v[12:15], v[178:181], v[250:253], v[12:15]
	ds_read_b128 v[178:181], v199 offset:36864
	v_mfma_f32_16x16x32_bf16 v[24:27], v[182:185], v[246:249], v[24:27]
	v_mfma_f32_16x16x32_bf16 v[8:11], v[182:185], v[250:253], v[8:11]
	ds_read_b128 v[182:185], v199 offset:39168
	v_mfma_f32_16x16x32_bf16 v[20:23], v[186:189], v[246:249], v[20:23]
	v_mfma_f32_16x16x32_bf16 v[4:7], v[186:189], v[250:253], v[4:7]
	ds_read_b128 v[186:189], v199 offset:41472
	v_mfma_f32_16x16x32_bf16 v[16:19], v[190:193], v[246:249], v[16:19]
	v_mfma_f32_16x16x32_bf16 v[0:3], v[190:193], v[250:253], v[0:3]
	ds_read_b128 v[190:193], v199 offset:43776
	s_branch .Lgm11_main

; DI f32x4 mfma16(bf16x8 a, bf16x8 b, f32x4 c) { return __builtin_amdgcn_mfma_f32_16x16x32_bf16(a, b, c, 0, 0, 0); }
; template <int MI, int NJ, bool SWAP, class AP, class BP>
; DI void gemm_main(f32x4 (&acc)[MI][NJ], const AP& ap, int a_kstep, const BP& bp, int b_kstep, int nk, bf16_t* smem) {
;     ...
;   auto sstore = [&](int buf) {
;     bf16_t* As = smem + buf * L::STAGE; bf16_t* Bs = As + L::A_ELEMS;
; #pragma unroll
;     for (int i = 0; i < CA; ++i) { const int c = tid + NTHR * i; *(u32x4*)(As + (c >> 3) * LDT + (c & 7) * 8) = oka[i] ? ra[i] : (u32x4){0u, 0u, 0u, 0u}; }
; #pragma unroll
;     for (int i = 0; i < CB; ++i) { const int c = tid + NTHR * i; *(u32x4*)(Bs + (c >> 3) * LDT + (c & 7) * 8) = rb[i]; }
;   };
;   gload(0); sstore(0); gload(nk > 1 ? 1 : 0); __syncthreads();
; #pragma unroll 1
;   for (int kt = 0; kt < nk; ++kt) {
;     const int buf = kt & 1;
;     sstore(buf ^ 1);
;     gload(kt + 2 < nk ? kt + 2 : nk - 1);
;     __builtin_amdgcn_sched_barrier(0);
;     const bf16_t* As = smem + buf * L::STAGE + (wm * 16 * MI + l15) * LDT + quad * 8;
;     const bf16_t* Bs = smem + buf * L::STAGE + L::A_ELEMS + (wn * 16 * NJ + l15) * LDT + quad * 8;
; #pragma unroll
;     for (int ks = 0; ks < 2; ++ks) {
;       if (MI * NJ >= 32 && ks == 1) asm volatile("" ::: "memory");
;       bf16x8 b[NJ];
; #pragma unroll
;       for (int j = 0; j < NJ; ++j) b[j] = *(const bf16x8*)(Bs + j * 16 * LDT + ks * 32);
; #pragma unroll
;       for (int i = 0; i < MI; ++i) {
;         const bf16x8 a = *(const bf16x8*)(As + i * 16 * LDT + ks * 32);
; #pragma unroll
;         for (int j = 0; j < NJ; ++j) acc[i][j] = SWAP ? mfma16(b[j], a, acc[i][j]) : mfma16(a, b[j], acc[i][j]);
;       }
.Lgm12_main:
	ds_read_b128 v[246:249], v198 offset:4608
	s_waitcnt lgkmcnt(4)
	v_mfma_f32_16x16x32_bf16 v[124:127], v[194:197], v[178:181], v[124:127]
	s_waitcnt lgkmcnt(3)
	v_mfma_f32_16x16x32_bf16 v[120:123], v[194:197], v[182:185], v[120:123]
	s_waitcnt lgkmcnt(2)
	v_mfma_f32_16x16x32_bf16 v[116:119], v[194:197], v[186:189], v[116:119]
	s_waitcnt lgkmcnt(1)
	v_mfma_f32_16x16x32_bf16 v[112:115], v[194:197], v[190:193], v[112:115]
	s_and_b32 s17, s8, 1
	s_xor_b32 s33, s17, 1
	s_mul_i32 s33, s33, 0x12000
	v_lshlrev_b32_e32 v254, 1, v160
	v_add3_u32 v254, s33, v254, v172
	s_waitcnt vmcnt(7)
	ds_write_b128 v254, v[140:143]
	ds_read_b128 v[250:253], v198 offset:6912
	v_mfma_f32_16x16x32_bf16 v[108:111], v[242:245], v[178:181], v[108:111]
	v_mfma_f32_16x16x32_bf16 v[104:107], v[242:245], v[182:185], v[104:107]
	v_mfma_f32_16x16x32_bf16 v[100:103], v[242:245], v[186:189], v[100:103]
	v_mfma_f32_16x16x32_bf16 v[96:99], v[242:245], v[190:193], v[96:99]
	v_lshlrev_b32_e32 v140, 1, v173
	v_add3_u32 v140, s33, v140, v172
	s_waitcnt vmcnt(6)
	ds_write_b128 v140, v[136:139]
	ds_read_b128 v[194:197], v198 offset:9216
	s_waitcnt lgkmcnt(4)
	v_mfma_f32_16x16x32_bf16 v[92:95], v[246:249], v[178:181], v[92:95]
	v_mfma_f32_16x16x32_bf16 v[88:91], v[246:249], v[182:185], v[88:91]
	v_mfma_f32_16x16x32_bf16 v[84:87], v[246:249], v[186:189], v[84:87]
	v_mfma_f32_16x16x32_bf16 v[80:83], v[246:249], v[190:193], v[80:83]
	ds_read_b128 v[242:245], v198 offset:11520
	s_waitcnt lgkmcnt(3)
	v_mfma_f32_16x16x32_bf16 v[76:79], v[250:253], v[178:181], v[76:79]
	v_lshlrev_b32_e32 v136, 1, v174
	v_add3_u32 v136, s33, v136, v172
	s_waitcnt vmcnt(5)
	ds_write_b128 v136, v[132:135]
	v_mfma_f32_16x16x32_bf16 v[72:75], v[250:253], v[182:185], v[72:75]
	v_mfma_f32_16x16x32_bf16 v[68:71], v[250:253], v[186:189], v[68:71]
	v_mfma_f32_16x16x32_bf16 v[64:67], v[250:253], v[190:193], v[64:67]
	ds_read_b128 v[246:249], v198 offset:13824
	s_waitcnt lgkmcnt(3)
	v_mfma_f32_16x16x32_bf16 v[60:63], v[194:197], v[178:181], v[60:63]
	v_lshlrev_b32_e32 v132, 1, v175
	s_cmp_eq_u32 s8, 0
	v_add3_u32 v132, s33, v132, v172
	s_cselect_b32 s33, s31, 0x180
	s_add_u32 s38, s0, s33
	s_addc_u32 s39, s1, 0
	s_waitcnt vmcnt(4)
	ds_write_b128 v132, v[128:131]
	v_mfma_f32_16x16x32_bf16 v[56:59], v[194:197], v[182:185], v[56:59]
	v_mfma_f32_16x16x32_bf16 v[52:55], v[194:197], v[186:189], v[52:55]
	v_mfma_f32_16x16x32_bf16 v[48:51], v[194:197], v[190:193], v[48:51]
	ds_read_b128 v[250:253], v198 offset:16128
	s_waitcnt lgkmcnt(4)
	v_mfma_f32_16x16x32_bf16 v[44:47], v[242:245], v[178:181], v[44:47]
	s_waitcnt vmcnt(3)
	ds_write_b128 v254, v[144:147] offset:36864
	v_mfma_f32_16x16x32_bf16 v[40:43], v[242:245], v[182:185], v[40:43]
	v_mfma_f32_16x16x32_bf16 v[36:39], v[242:245], v[186:189], v[36:39]
	v_mfma_f32_16x16x32_bf16 v[32:35], v[242:245], v[190:193], v[32:35]
	ds_read_b128 v[194:197], v198 offset:64
	s_waitcnt lgkmcnt(4)
	v_mfma_f32_16x16x32_bf16 v[28:31], v[246:249], v[178:181], v[28:31]
	s_waitcnt vmcnt(2)
	ds_write_b128 v140, v[148:151] offset:36864
	v_mfma_f32_16x16x32_bf16 v[24:27], v[246:249], v[182:185], v[24:27]
	v_mfma_f32_16x16x32_bf16 v[20:23], v[246:249], v[186:189], v[20:23]
	v_mfma_f32_16x16x32_bf16 v[16:19], v[246:249], v[190:193], v[16:19]
	ds_read_b128 v[242:245], v198 offset:2368
	s_waitcnt lgkmcnt(4)
	v_mfma_f32_16x16x32_bf16 v[12:15], v[250:253], v[178:181], v[12:15]
	ds_read_b128 v[178:181], v199 offset:36928
	s_waitcnt vmcnt(1)
	ds_write_b128 v136, v[152:155] offset:36864
	v_mfma_f32_16x16x32_bf16 v[8:11], v[250:253], v[182:185], v[8:11]
	ds_read_b128 v[182:185], v199 offset:39232
	v_mfma_f32_16x16x32_bf16 v[4:7], v[250:253], v[186:189], v[4:7]
	ds_read_b128 v[186:189], v199 offset:41536
	v_mfma_f32_16x16x32_bf16 v[0:3], v[250:253], v[190:193], v[0:3]
	ds_read_b128 v[190:193], v199 offset:43840
	ds_read_b128 v[246:249], v198 offset:4672
	s_waitcnt lgkmcnt(5)
	v_mfma_f32_16x16x32_bf16 v[124:127], v[194:197], v[178:181], v[124:127]
	s_waitcnt lgkmcnt(3)
; DI f32x4 mfma16(bf16x8 a, bf16x8 b, f32x4 c) { return __builtin_amdgcn_mfma_f32_16x16x32_bf16(a, b, c, 0, 0, 0); }
; template <int MI, int NJ, bool SWAP, class AP, class BP>
; DI void gemm_main(f32x4 (&acc)[MI][NJ], const AP& ap, int a_kstep, const BP& bp, int b_kstep, int nk, bf16_t* smem) {
;     ...
;   auto gload = [&](int kt) {
;     const bf16_t* ab = ap.base + (size_t)kt * a_kstep; const bf16_t* bb = bp.base + (size_t)kt * b_kstep;
; #pragma unroll
;     for (int i = 0; i < CA; ++i) ra[i] = *(const u32x4*)(ab + pa[i]);
; #pragma unroll
;     for (int i = 0; i < CB; ++i) rb[i] = *(const u32x4*)(bb + pb[i]);
;   };
;   auto sstore = [&](int buf) {
;     bf16_t* As = smem + buf * L::STAGE; bf16_t* Bs = As + L::A_ELEMS;
; #pragma unroll
;     for (int i = 0; i < CA; ++i) { const int c = tid + NTHR * i; *(u32x4*)(As + (c >> 3) * LDT + (c & 7) * 8) = oka[i] ? ra[i] : (u32x4){0u, 0u, 0u, 0u}; }
; #pragma unroll
;     for (int i = 0; i < CB; ++i) { const int c = tid + NTHR * i; *(u32x4*)(Bs + (c >> 3) * LDT + (c & 7) * 8) = rb[i]; }
;   };
;   gload(0); sstore(0); gload(nk > 1 ? 1 : 0); __syncthreads();
; #pragma unroll 1
;   for (int kt = 0; kt < nk; ++kt) {
;     const int buf = kt & 1;
;     sstore(buf ^ 1);
;     gload(kt + 2 < nk ? kt + 2 : nk - 1);
;     __builtin_amdgcn_sched_barrier(0);
;     const bf16_t* As = smem + buf * L::STAGE + (wm * 16 * MI + l15) * LDT + quad * 8;
;     const bf16_t* Bs = smem + buf * L::STAGE + L::A_ELEMS + (wn * 16 * NJ + l15) * LDT + quad * 8;
; #pragma unroll
;     for (int ks = 0; ks < 2; ++ks) {
;       if (MI * NJ >= 32 && ks == 1) asm volatile("" ::: "memory");
;       bf16x8 b[NJ];
; #pragma unroll
;       for (int j = 0; j < NJ; ++j) b[j] = *(const bf16x8*)(Bs + j * 16 * LDT + ks * 32);
; #pragma unroll
;       for (int i = 0; i < MI; ++i) {
;         const bf16x8 a = *(const bf16x8*)(As + i * 16 * LDT + ks * 32);
; #pragma unroll
;         for (int j = 0; j < NJ; ++j) acc[i][j] = SWAP ? mfma16(b[j], a, acc[i][j]) : mfma16(a, b[j], acc[i][j]);
;       }
;     }
;     __syncthreads();
;   }
	v_mfma_f32_16x16x32_bf16 v[120:123], v[194:197], v[182:185], v[120:123]
	s_waitcnt vmcnt(0)
	ds_write_b128 v132, v[156:159] offset:36864
	s_waitcnt lgkmcnt(3)
	v_mfma_f32_16x16x32_bf16 v[116:119], v[194:197], v[186:189], v[116:119]
	s_waitcnt lgkmcnt(2)
	v_mfma_f32_16x16x32_bf16 v[112:115], v[194:197], v[190:193], v[112:115]
	v_lshl_add_u64 v[128:129], s[38:39], 0, v[162:163]
	global_load_dwordx4 v[140:143], v[128:129], off
	ds_read_b128 v[250:253], v198 offset:6976
	v_mfma_f32_16x16x32_bf16 v[108:111], v[242:245], v[178:181], v[108:111]
	v_mfma_f32_16x16x32_bf16 v[104:107], v[242:245], v[182:185], v[104:107]
	v_lshl_add_u64 v[128:129], s[38:39], 0, v[164:165]
	global_load_dwordx4 v[136:139], v[128:129], off
	v_mfma_f32_16x16x32_bf16 v[100:103], v[242:245], v[186:189], v[100:103]
	v_mfma_f32_16x16x32_bf16 v[96:99], v[242:245], v[190:193], v[96:99]
	ds_read_b128 v[194:197], v198 offset:9280
	s_waitcnt lgkmcnt(3)
	v_mfma_f32_16x16x32_bf16 v[92:95], v[246:249], v[178:181], v[92:95]
	v_lshl_add_u64 v[128:129], s[38:39], 0, v[166:167]
	global_load_dwordx4 v[132:135], v[128:129], off
	v_mfma_f32_16x16x32_bf16 v[88:91], v[246:249], v[182:185], v[88:91]
	v_mfma_f32_16x16x32_bf16 v[84:87], v[246:249], v[186:189], v[84:87]
	v_lshl_add_u64 v[128:129], s[38:39], 0, v[168:169]
	s_add_u32 s38, s2, s33
	s_addc_u32 s39, s3, 0
	v_lshl_add_u64 v[144:145], s[38:39], 0, v[162:163]
	v_lshl_add_u64 v[148:149], s[38:39], 0, v[164:165]
	v_lshl_add_u64 v[152:153], s[38:39], 0, v[166:167]
	v_lshl_add_u64 v[156:157], s[38:39], 0, v[168:169]
	global_load_dwordx4 v[128:131], v[128:129], off
	v_mfma_f32_16x16x32_bf16 v[80:83], v[246:249], v[190:193], v[80:83]
	ds_read_b128 v[242:245], v198 offset:11584
	s_waitcnt lgkmcnt(2)
	v_mfma_f32_16x16x32_bf16 v[76:79], v[250:253], v[178:181], v[76:79]
	v_mfma_f32_16x16x32_bf16 v[72:75], v[250:253], v[182:185], v[72:75]
	s_nop 0
	global_load_dwordx4 v[144:147], v[144:145], off
	v_mfma_f32_16x16x32_bf16 v[68:71], v[250:253], v[186:189], v[68:71]
	v_mfma_f32_16x16x32_bf16 v[64:67], v[250:253], v[190:193], v[64:67]
	s_nop 0
	global_load_dwordx4 v[148:151], v[148:149], off
	ds_read_b128 v[246:249], v198 offset:13888
	s_waitcnt lgkmcnt(2)
	v_mfma_f32_16x16x32_bf16 v[60:63], v[194:197], v[178:181], v[60:63]
	v_mfma_f32_16x16x32_bf16 v[56:59], v[194:197], v[182:185], v[56:59]
	v_mfma_f32_16x16x32_bf16 v[52:55], v[194:197], v[186:189], v[52:55]
	s_nop 0
	global_load_dwordx4 v[152:155], v[152:153], off
	v_mfma_f32_16x16x32_bf16 v[48:51], v[194:197], v[190:193], v[48:51]
	ds_read_b128 v[250:253], v198 offset:16192
	s_waitcnt lgkmcnt(2)
	v_mfma_f32_16x16x32_bf16 v[44:47], v[242:245], v[178:181], v[44:47]
	s_nop 0
	global_load_dwordx4 v[156:159], v[156:157], off
	v_mfma_f32_16x16x32_bf16 v[40:43], v[242:245], v[182:185], v[40:43]
	v_mfma_f32_16x16x32_bf16 v[36:39], v[242:245], v[186:189], v[36:39]
	v_mfma_f32_16x16x32_bf16 v[32:35], v[242:245], v[190:193], v[32:35]
	s_add_i32 s8, s8, 1
	s_and_b32 s98, s8, 1
	s_mul_i32 s98, s98, 0x12000
	v_add3_u32 v198, s98, v176, v177
	v_add3_u32 v199, s98, v171, v177
	s_cmp_lg_u32 s8, 4
	s_waitcnt lgkmcnt(0)
	s_barrier
	s_cbranch_scc0 .Lgm12_exit
	ds_read_b128 v[194:197], v198
	ds_read_b128 v[242:245], v198 offset:2304
	v_mfma_f32_16x16x32_bf16 v[28:31], v[246:249], v[178:181], v[28:31]
	v_mfma_f32_16x16x32_bf16 v[12:15], v[250:253], v[178:181], v[12:15]
	ds_read_b128 v[178:181], v199 offset:36864
	v_mfma_f32_16x16x32_bf16 v[24:27], v[246:249], v[182:185], v[24:27]
	v_mfma_f32_16x16x32_bf16 v[8:11], v[250:253], v[182:185], v[8:11]
	ds_read_b128 v[182:185], v199 offset:39168
	v_mfma_f32_16x16x32_bf16 v[20:23], v[246:249], v[186:189], v[20:23]
	v_mfma_f32_16x16x32_bf16 v[4:7], v[250:253], v[186:189], v[4:7]
	ds_read_b128 v[186:189], v199 offset:41472
	v_mfma_f32_16x16x32_bf16 v[16:19], v[246:249], v[190:193], v[16:19]
	v_mfma_f32_16x16x32_bf16 v[0:3], v[250:253], v[190:193], v[0:3]
	ds_read_b128 v[190:193], v199 offset:43776
	s_branch .Lgm12_main

; DI f32x4 mfma16(bf16x8 a, bf16x8 b, f32x4 c) { return __builtin_amdgcn_mfma_f32_16x16x32_bf16(a, b, c, 0, 0, 0); }
; template <int MI, int NJ, bool SWAP, class AP, class BP>
; DI void gemm_main(f32x4 (&acc)[MI][NJ], const AP& ap, int a_kstep, const BP& bp, int b_kstep, int nk, bf16_t* smem) {
;     ...
;   auto sstore = [&](int buf) {
;     bf16_t* As = smem + buf * L::STAGE; bf16_t* Bs = As + L::A_ELEMS;
; #pragma unroll
;     for (int i = 0; i < CA; ++i) { const int c = tid + NTHR * i; *(u32x4*)(As + (c >> 3) * LDT + (c & 7) * 8) = oka[i] ? ra[i] : (u32x4){0u, 0u, 0u, 0u}; }
; #pragma unroll
;     for (int i = 0; i < CB; ++i) { const int c = tid + NTHR * i; *(u32x4*)(Bs + (c >> 3) * LDT + (c & 7) * 8) = rb[i]; }
;   };
;   gload(0); sstore(0); gload(nk > 1 ? 1 : 0); __syncthreads();
; #pragma unroll 1
;   for (int kt = 0; kt < nk; ++kt) {
;     const int buf = kt & 1;
;     sstore(buf ^ 1);
;     gload(kt + 2 < nk ? kt + 2 : nk - 1);
;     __builtin_amdgcn_sched_barrier(0);
;     const bf16_t* As = smem + buf * L::STAGE + (wm * 16 * MI + l15) * LDT + quad * 8;
;     const bf16_t* Bs = smem + buf * L::STAGE + L::A_ELEMS + (wn * 16 * NJ + l15) * LDT + quad * 8;
; #pragma unroll
;     for (int ks = 0; ks < 2; ++ks) {
;       if (MI * NJ >= 32 && ks == 1) asm volatile("" ::: "memory");
;       bf16x8 b[NJ];
; #pragma unroll
;       for (int j = 0; j < NJ; ++j) b[j] = *(const bf16x8*)(Bs + j * 16 * LDT + ks * 32);
; #pragma unroll
;       for (int i = 0; i < MI; ++i) {
;         const bf16x8 a = *(const bf16x8*)(As + i * 16 * LDT + ks * 32);
; #pragma unroll
;         for (int j = 0; j < NJ; ++j) acc[i][j] = SWAP ? mfma16(b[j], a, acc[i][j]) : mfma16(a, b[j], acc[i][j]);
;       }
.Lgm13_main:
	ds_read_b128 v[242:245], v177 offset:4608
	s_waitcnt lgkmcnt(4)
	v_mfma_f32_16x16x32_bf16 v[156:159], v[178:181], v[194:197], v[156:159]
	s_waitcnt lgkmcnt(3)
	v_mfma_f32_16x16x32_bf16 v[152:155], v[182:185], v[194:197], v[152:155]
	s_waitcnt lgkmcnt(2)
	v_mfma_f32_16x16x32_bf16 v[148:151], v[186:189], v[194:197], v[148:151]
	s_and_b32 s15, s1, 1
	s_min_u32 s16, s1, 13
	s_xor_b32 s17, s15, 1
	s_mul_i32 s17, s17, 0x12000
	v_add3_u32 v250, s17, v172, v170
	s_waitcnt vmcnt(7)
	ds_write_b128 v250, v[112:115]
	s_waitcnt lgkmcnt(2)
	v_mfma_f32_16x16x32_bf16 v[144:147], v[190:193], v[194:197], v[144:147]
	ds_read_b128 v[246:249], v177 offset:6912
	v_mfma_f32_16x16x32_bf16 v[108:111], v[178:181], v[198:201], v[108:111]
	s_lshl_b32 s26, s16, 7
	s_add_u32 s16, s2, s26
	v_add3_u32 v251, s17, v174, v170
	v_add3_u32 v252, s17, v175, v170
	v_add3_u32 v253, s17, v176, v170
	s_addc_u32 s17, s3, 0
	v_lshl_add_u64 v[112:113], s[16:17], 0, v[162:163]
	s_nop 0
	global_load_dwordx4 v[112:115], v[112:113], off offset:256
	v_mfma_f32_16x16x32_bf16 v[104:107], v[182:185], v[198:201], v[104:107]
	v_mfma_f32_16x16x32_bf16 v[100:103], v[186:189], v[198:201], v[100:103]
	v_mfma_f32_16x16x32_bf16 v[96:99], v[190:193], v[198:201], v[96:99]
	ds_read_b128 v[194:197], v177 offset:9216
	s_waitcnt lgkmcnt(3)
	v_mfma_f32_16x16x32_bf16 v[92:95], v[178:181], v[242:245], v[92:95]
	s_waitcnt vmcnt(7)
	ds_write_b128 v251, v[116:119]
	v_mfma_f32_16x16x32_bf16 v[88:91], v[182:185], v[242:245], v[88:91]
	v_mfma_f32_16x16x32_bf16 v[84:87], v[186:189], v[242:245], v[84:87]
	v_lshl_add_u64 v[116:117], s[16:17], 0, v[164:165]
	s_nop 0
	global_load_dwordx4 v[116:119], v[116:117], off offset:256
	v_mfma_f32_16x16x32_bf16 v[80:83], v[190:193], v[242:245], v[80:83]
	ds_read_b128 v[198:201], v177 offset:11520
	s_waitcnt lgkmcnt(3)
	v_mfma_f32_16x16x32_bf16 v[76:79], v[178:181], v[246:249], v[76:79]
	v_mfma_f32_16x16x32_bf16 v[72:75], v[182:185], v[246:249], v[72:75]
	v_mfma_f32_16x16x32_bf16 v[68:71], v[186:189], v[246:249], v[68:71]
	s_waitcnt vmcnt(7)
	ds_write_b128 v252, v[120:123]
	v_mfma_f32_16x16x32_bf16 v[64:67], v[190:193], v[246:249], v[64:67]
	ds_read_b128 v[242:245], v177 offset:13824
	s_waitcnt lgkmcnt(4)
	v_mfma_f32_16x16x32_bf16 v[60:63], v[178:181], v[194:197], v[60:63]
	v_lshl_add_u64 v[120:121], s[16:17], 0, v[166:167]
	s_nop 0
	global_load_dwordx4 v[120:123], v[120:121], off offset:256
	v_mfma_f32_16x16x32_bf16 v[56:59], v[182:185], v[194:197], v[56:59]
	v_mfma_f32_16x16x32_bf16 v[52:55], v[186:189], v[194:197], v[52:55]
	v_mfma_f32_16x16x32_bf16 v[48:51], v[190:193], v[194:197], v[48:51]
	ds_read_b128 v[246:249], v177 offset:16128
	s_waitcnt lgkmcnt(3)
	v_mfma_f32_16x16x32_bf16 v[44:47], v[178:181], v[198:201], v[44:47]
	s_waitcnt vmcnt(7)
	ds_write_b128 v253, v[124:127]
	v_mfma_f32_16x16x32_bf16 v[40:43], v[182:185], v[198:201], v[40:43]
	v_mfma_f32_16x16x32_bf16 v[36:39], v[186:189], v[198:201], v[36:39]
	v_lshl_add_u64 v[124:125], s[16:17], 0, v[168:169]
	s_nop 0
	global_load_dwordx4 v[124:127], v[124:125], off offset:256
	v_mfma_f32_16x16x32_bf16 v[32:35], v[190:193], v[198:201], v[32:35]
	ds_read_b128 v[194:197], v177 offset:64
	s_waitcnt lgkmcnt(3)
	v_mfma_f32_16x16x32_bf16 v[28:31], v[178:181], v[242:245], v[28:31]
	v_mfma_f32_16x16x32_bf16 v[24:27], v[182:185], v[242:245], v[24:27]
	v_mfma_f32_16x16x32_bf16 v[20:23], v[186:189], v[242:245], v[20:23]
	s_waitcnt vmcnt(7)
	ds_write_b128 v250, v[128:131] offset:36864
	v_mfma_f32_16x16x32_bf16 v[16:19], v[190:193], v[242:245], v[16:19]
	ds_read_b128 v[198:201], v177 offset:2368
	s_waitcnt lgkmcnt(4)
	v_mfma_f32_16x16x32_bf16 v[8:11], v[178:181], v[246:249], v[8:11]
	ds_read_b128 v[178:181], v202 offset:36928
	s_add_u32 s16, s12, s26
	s_addc_u32 s17, s13, 0
	v_lshl_add_u64 v[128:129], s[16:17], 0, v[162:163]
	s_nop 0
	global_load_dwordx4 v[128:131], v[128:129], off offset:256
	v_mfma_f32_16x16x32_bf16 v[4:7], v[182:185], v[246:249], v[4:7]
	ds_read_b128 v[182:185], v202 offset:39232
	v_mfma_f32_16x16x32_bf16 v[0:3], v[186:189], v[246:249], v[0:3]
	ds_read_b128 v[186:189], v202 offset:41536
	v_mfma_f32_16x16x32_bf16 v[12:15], v[190:193], v[246:249], v[12:15]
	ds_read_b128 v[190:193], v202 offset:43840
	ds_read_b128 v[242:245], v177 offset:4672
	s_waitcnt lgkmcnt(4)
; DI f32x4 mfma16(bf16x8 a, bf16x8 b, f32x4 c) { return __builtin_amdgcn_mfma_f32_16x16x32_bf16(a, b, c, 0, 0, 0); }
; template <int MI, int NJ, bool SWAP, class AP, class BP>
; DI void gemm_main(f32x4 (&acc)[MI][NJ], const AP& ap, int a_kstep, const BP& bp, int b_kstep, int nk, bf16_t* smem) {
;     ...
;   auto gload = [&](int kt) {
;     const bf16_t* ab = ap.base + (size_t)kt * a_kstep; const bf16_t* bb = bp.base + (size_t)kt * b_kstep;
; #pragma unroll
;     for (int i = 0; i < CA; ++i) ra[i] = *(const u32x4*)(ab + pa[i]);
; #pragma unroll
;     for (int i = 0; i < CB; ++i) rb[i] = *(const u32x4*)(bb + pb[i]);
;   };
;   auto sstore = [&](int buf) {
;     bf16_t* As = smem + buf * L::STAGE; bf16_t* Bs = As + L::A_ELEMS;
; #pragma unroll
;     for (int i = 0; i < CA; ++i) { const int c = tid + NTHR * i; *(u32x4*)(As + (c >> 3) * LDT + (c & 7) * 8) = oka[i] ? ra[i] : (u32x4){0u, 0u, 0u, 0u}; }
; #pragma unroll
;     for (int i = 0; i < CB; ++i) { const int c = tid + NTHR * i; *(u32x4*)(Bs + (c >> 3) * LDT + (c & 7) * 8) = rb[i]; }
;   };
;   gload(0); sstore(0); gload(nk > 1 ? 1 : 0); __syncthreads();
; #pragma unroll 1
;   for (int kt = 0; kt < nk; ++kt) {
;     const int buf = kt & 1;
;     sstore(buf ^ 1);
;     gload(kt + 2 < nk ? kt + 2 : nk - 1);
;     __builtin_amdgcn_sched_barrier(0);
;     const bf16_t* As = smem + buf * L::STAGE + (wm * 16 * MI + l15) * LDT + quad * 8;
;     const bf16_t* Bs = smem + buf * L::STAGE + L::A_ELEMS + (wn * 16 * NJ + l15) * LDT + quad * 8;
; #pragma unroll
;     for (int ks = 0; ks < 2; ++ks) {
;       if (MI * NJ >= 32 && ks == 1) asm volatile("" ::: "memory");
;       bf16x8 b[NJ];
; #pragma unroll
;       for (int j = 0; j < NJ; ++j) b[j] = *(const bf16x8*)(Bs + j * 16 * LDT + ks * 32);
; #pragma unroll
;       for (int i = 0; i < MI; ++i) {
;         const bf16x8 a = *(const bf16x8*)(As + i * 16 * LDT + ks * 32);
; #pragma unroll
;         for (int j = 0; j < NJ; ++j) acc[i][j] = SWAP ? mfma16(b[j], a, acc[i][j]) : mfma16(a, b[j], acc[i][j]);
;       }
;     }
;     __syncthreads();
;   }
	v_mfma_f32_16x16x32_bf16 v[156:159], v[178:181], v[194:197], v[156:159]
	s_waitcnt vmcnt(7)
	ds_write_b128 v251, v[132:135] offset:36864
	s_waitcnt lgkmcnt(4)
	v_mfma_f32_16x16x32_bf16 v[152:155], v[182:185], v[194:197], v[152:155]
	s_waitcnt lgkmcnt(3)
	v_mfma_f32_16x16x32_bf16 v[148:151], v[186:189], v[194:197], v[148:151]
	v_lshl_add_u64 v[132:133], s[16:17], 0, v[164:165]
	s_nop 0
	global_load_dwordx4 v[132:135], v[132:133], off offset:256
	s_waitcnt lgkmcnt(2)
	v_mfma_f32_16x16x32_bf16 v[144:147], v[190:193], v[194:197], v[144:147]
	ds_read_b128 v[246:249], v177 offset:6976
	v_mfma_f32_16x16x32_bf16 v[108:111], v[178:181], v[198:201], v[108:111]
	v_mfma_f32_16x16x32_bf16 v[104:107], v[182:185], v[198:201], v[104:107]
	v_mfma_f32_16x16x32_bf16 v[100:103], v[186:189], v[198:201], v[100:103]
	s_waitcnt vmcnt(7)
	ds_write_b128 v252, v[136:139] offset:36864
	v_mfma_f32_16x16x32_bf16 v[96:99], v[190:193], v[198:201], v[96:99]
	ds_read_b128 v[194:197], v177 offset:9280
	s_waitcnt lgkmcnt(4)
	v_mfma_f32_16x16x32_bf16 v[92:95], v[178:181], v[242:245], v[92:95]
	v_lshl_add_u64 v[136:137], s[16:17], 0, v[166:167]
	s_nop 0
	global_load_dwordx4 v[136:139], v[136:137], off offset:256
	v_mfma_f32_16x16x32_bf16 v[88:91], v[182:185], v[242:245], v[88:91]
	v_mfma_f32_16x16x32_bf16 v[84:87], v[186:189], v[242:245], v[84:87]
	v_mfma_f32_16x16x32_bf16 v[80:83], v[190:193], v[242:245], v[80:83]
	ds_read_b128 v[198:201], v177 offset:11584
	s_waitcnt lgkmcnt(3)
	v_mfma_f32_16x16x32_bf16 v[76:79], v[178:181], v[246:249], v[76:79]
	s_waitcnt vmcnt(7)
	ds_write_b128 v253, v[140:143] offset:36864
	v_mfma_f32_16x16x32_bf16 v[72:75], v[182:185], v[246:249], v[72:75]
	v_mfma_f32_16x16x32_bf16 v[68:71], v[186:189], v[246:249], v[68:71]
	v_lshl_add_u64 v[140:141], s[16:17], 0, v[168:169]
	s_nop 0
	global_load_dwordx4 v[140:143], v[140:141], off offset:256
	v_mfma_f32_16x16x32_bf16 v[64:67], v[190:193], v[246:249], v[64:67]
	ds_read_b128 v[242:245], v177 offset:13888
	s_waitcnt lgkmcnt(3)
	v_mfma_f32_16x16x32_bf16 v[60:63], v[178:181], v[194:197], v[60:63]
	v_mfma_f32_16x16x32_bf16 v[56:59], v[182:185], v[194:197], v[56:59]
	v_mfma_f32_16x16x32_bf16 v[52:55], v[186:189], v[194:197], v[52:55]
	v_mfma_f32_16x16x32_bf16 v[48:51], v[190:193], v[194:197], v[48:51]
	ds_read_b128 v[246:249], v177 offset:16192
	s_waitcnt lgkmcnt(3)
	v_mfma_f32_16x16x32_bf16 v[44:47], v[178:181], v[198:201], v[44:47]
	v_mfma_f32_16x16x32_bf16 v[40:43], v[182:185], v[198:201], v[40:43]
	v_mfma_f32_16x16x32_bf16 v[36:39], v[186:189], v[198:201], v[36:39]
	v_mfma_f32_16x16x32_bf16 v[32:35], v[190:193], v[198:201], v[32:35]
	s_add_i32 s1, s1, 1
	s_and_b32 s98, s1, 1
	s_mul_i32 s98, s98, 0x12000
	v_add3_u32 v202, s98, v160, v173
	v_add3_u32 v177, s98, v171, v173
	s_cmp_lg_u32 s1, 16
	s_waitcnt lgkmcnt(0)
	s_barrier
	s_cbranch_scc0 .Lgm13_exit
	ds_read_b128 v[194:197], v177
	ds_read_b128 v[198:201], v177 offset:2304
	v_mfma_f32_16x16x32_bf16 v[28:31], v[178:181], v[242:245], v[28:31]
	v_mfma_f32_16x16x32_bf16 v[8:11], v[178:181], v[246:249], v[8:11]
	ds_read_b128 v[178:181], v202 offset:36864
	v_mfma_f32_16x16x32_bf16 v[24:27], v[182:185], v[242:245], v[24:27]
	v_mfma_f32_16x16x32_bf16 v[4:7], v[182:185], v[246:249], v[4:7]
	ds_read_b128 v[182:185], v202 offset:39168
	v_mfma_f32_16x16x32_bf16 v[20:23], v[186:189], v[242:245], v[20:23]
	v_mfma_f32_16x16x32_bf16 v[0:3], v[186:189], v[246:249], v[0:3]
	ds_read_b128 v[186:189], v202 offset:41472
	v_mfma_f32_16x16x32_bf16 v[16:19], v[190:193], v[242:245], v[16:19]
	v_mfma_f32_16x16x32_bf16 v[12:15], v[190:193], v[246:249], v[12:15]
	ds_read_b128 v[190:193], v202 offset:43776
	s_branch .Lgm13_main

; DI f32x4 mfma16(bf16x8 a, bf16x8 b, f32x4 c) { return __builtin_amdgcn_mfma_f32_16x16x32_bf16(a, b, c, 0, 0, 0); }
; template <int MI, int NJ, bool SWAP, class AP, class BP>
; DI void gemm_main(f32x4 (&acc)[MI][NJ], const AP& ap, int a_kstep, const BP& bp, int b_kstep, int nk, bf16_t* smem) {
;     ...
;   auto sstore = [&](int buf) {
;     bf16_t* As = smem + buf * L::STAGE; bf16_t* Bs = As + L::A_ELEMS;
; #pragma unroll
;     for (int i = 0; i < CA; ++i) { const int c = tid + NTHR * i; *(u32x4*)(As + (c >> 3) * LDT + (c & 7) * 8) = oka[i] ? ra[i] : (u32x4){0u, 0u, 0u, 0u}; }
; #pragma unroll
;     for (int i = 0; i < CB; ++i) { const int c = tid + NTHR * i; *(u32x4*)(Bs + (c >> 3) * LDT + (c & 7) * 8) = rb[i]; }
;   };
;   gload(0); sstore(0); gload(nk > 1 ? 1 : 0); __syncthreads();
; #pragma unroll 1
;   for (int kt = 0; kt < nk; ++kt) {
;     const int buf = kt & 1;
;     sstore(buf ^ 1);
;     gload(kt + 2 < nk ? kt + 2 : nk - 1);
;     __builtin_amdgcn_sched_barrier(0);
;     const bf16_t* As = smem + buf * L::STAGE + (wm * 16 * MI + l15) * LDT + quad * 8;
;     const bf16_t* Bs = smem + buf * L::STAGE + L::A_ELEMS + (wn * 16 * NJ + l15) * LDT + quad * 8;
; #pragma unroll
;     for (int ks = 0; ks < 2; ++ks) {
;       if (MI * NJ >= 32 && ks == 1) asm volatile("" ::: "memory");
;       bf16x8 b[NJ];
; #pragma unroll
;       for (int j = 0; j < NJ; ++j) b[j] = *(const bf16x8*)(Bs + j * 16 * LDT + ks * 32);
; #pragma unroll
;       for (int i = 0; i < MI; ++i) {
;         const bf16x8 a = *(const bf16x8*)(As + i * 16 * LDT + ks * 32);
; #pragma unroll
;         for (int j = 0; j < NJ; ++j) acc[i][j] = SWAP ? mfma16(b[j], a, acc[i][j]) : mfma16(a, b[j], acc[i][j]);
;       }
.Lgm14_main:
	ds_read_b128 v[242:245], v181 offset:4608
	s_waitcnt lgkmcnt(4)
	v_mfma_f32_16x16x32_bf16 v[156:159], v[182:185], v[198:201], v[156:159]
	s_waitcnt lgkmcnt(3)
	v_mfma_f32_16x16x32_bf16 v[152:155], v[186:189], v[198:201], v[152:155]
	s_waitcnt lgkmcnt(2)
	v_mfma_f32_16x16x32_bf16 v[148:151], v[190:193], v[198:201], v[148:151]
	s_waitcnt vmcnt(7)
	v_cndmask_b32_e32 v143, 0, v143, vcc
	v_cndmask_b32_e32 v142, 0, v142, vcc
	v_cndmask_b32_e32 v141, 0, v141, vcc
	v_cndmask_b32_e32 v140, 0, v140, vcc
	s_and_b32 s46, s43, 1
	s_min_u32 s44, s43, 13
	s_xor_b32 s45, s46, 1
	s_mul_i32 s45, s45, 0x12000
	v_add3_u32 v250, s45, v172, v169
	ds_write_b128 v250, v[140:143]
	s_waitcnt lgkmcnt(2)
	v_mfma_f32_16x16x32_bf16 v[144:147], v[194:197], v[198:201], v[144:147]
	ds_read_b128 v[246:249], v181 offset:6912
	v_mfma_f32_16x16x32_bf16 v[108:111], v[182:185], v[202:205], v[108:111]
	s_lshl_b32 s47, s44, 7
	s_add_u32 s44, s18, s47
	v_add3_u32 v251, s45, v173, v169
	v_add3_u32 v252, s45, v174, v169
	v_add3_u32 v253, s45, v175, v169
	s_addc_u32 s45, s19, 0
	s_nop 0
	global_load_dwordx4 v[140:143], v176, s[44:45] offset:256
	v_mfma_f32_16x16x32_bf16 v[104:107], v[186:189], v[202:205], v[104:107]
	v_mfma_f32_16x16x32_bf16 v[100:103], v[190:193], v[202:205], v[100:103]
	v_mfma_f32_16x16x32_bf16 v[96:99], v[194:197], v[202:205], v[96:99]
	ds_read_b128 v[198:201], v181 offset:9216
	s_waitcnt lgkmcnt(3)
	v_mfma_f32_16x16x32_bf16 v[92:95], v[182:185], v[242:245], v[92:95]
	s_waitcnt vmcnt(7)
	v_cndmask_b32_e64 v131, 0, v131, s[0:1]
	v_cndmask_b32_e64 v130, 0, v130, s[0:1]
	v_cndmask_b32_e64 v129, 0, v129, s[0:1]
	v_cndmask_b32_e64 v128, 0, v128, s[0:1]
	ds_write_b128 v251, v[128:131]
	v_mfma_f32_16x16x32_bf16 v[88:91], v[186:189], v[242:245], v[88:91]
	v_mfma_f32_16x16x32_bf16 v[84:87], v[190:193], v[242:245], v[84:87]
	s_nop 0
	global_load_dwordx4 v[128:131], v177, s[44:45] offset:256
	v_mfma_f32_16x16x32_bf16 v[80:83], v[194:197], v[242:245], v[80:83]
	ds_read_b128 v[202:205], v181 offset:11520
	s_waitcnt lgkmcnt(3)
	v_mfma_f32_16x16x32_bf16 v[76:79], v[182:185], v[246:249], v[76:79]
	v_mfma_f32_16x16x32_bf16 v[72:75], v[186:189], v[246:249], v[72:75]
	v_mfma_f32_16x16x32_bf16 v[68:71], v[190:193], v[246:249], v[68:71]
	s_waitcnt vmcnt(7)
	v_cndmask_b32_e64 v115, 0, v115, s[2:3]
	v_cndmask_b32_e64 v114, 0, v114, s[2:3]
	v_cndmask_b32_e64 v113, 0, v113, s[2:3]
	v_cndmask_b32_e64 v112, 0, v112, s[2:3]
	ds_write_b128 v252, v[112:115]
	v_mfma_f32_16x16x32_bf16 v[64:67], v[194:197], v[246:249], v[64:67]
	ds_read_b128 v[242:245], v181 offset:13824
	s_waitcnt lgkmcnt(4)
	v_mfma_f32_16x16x32_bf16 v[60:63], v[182:185], v[198:201], v[60:63]
	s_nop 0
	global_load_dwordx4 v[112:115], v178, s[44:45] offset:256
	v_mfma_f32_16x16x32_bf16 v[56:59], v[186:189], v[198:201], v[56:59]
	v_mfma_f32_16x16x32_bf16 v[52:55], v[190:193], v[198:201], v[52:55]
	v_mfma_f32_16x16x32_bf16 v[48:51], v[194:197], v[198:201], v[48:51]
	ds_read_b128 v[246:249], v181 offset:16128
	s_waitcnt lgkmcnt(3)
	v_mfma_f32_16x16x32_bf16 v[44:47], v[182:185], v[202:205], v[44:47]
	s_waitcnt vmcnt(7)
	v_cndmask_b32_e64 v135, 0, v135, s[4:5]
	v_cndmask_b32_e64 v134, 0, v134, s[4:5]
	v_cndmask_b32_e64 v133, 0, v133, s[4:5]
	v_cndmask_b32_e64 v132, 0, v132, s[4:5]
	ds_write_b128 v253, v[132:135]
	v_mfma_f32_16x16x32_bf16 v[40:43], v[186:189], v[202:205], v[40:43]
	v_mfma_f32_16x16x32_bf16 v[36:39], v[190:193], v[202:205], v[36:39]
	s_nop 0
	global_load_dwordx4 v[132:135], v179, s[44:45] offset:256
	v_mfma_f32_16x16x32_bf16 v[32:35], v[194:197], v[202:205], v[32:35]
	ds_read_b128 v[198:201], v181 offset:64
	s_waitcnt lgkmcnt(3)
	v_mfma_f32_16x16x32_bf16 v[28:31], v[182:185], v[242:245], v[28:31]
	v_mfma_f32_16x16x32_bf16 v[24:27], v[186:189], v[242:245], v[24:27]
	v_mfma_f32_16x16x32_bf16 v[20:23], v[190:193], v[242:245], v[20:23]
	s_waitcnt vmcnt(7)
	ds_write_b128 v250, v[116:119] offset:36864
	v_mfma_f32_16x16x32_bf16 v[12:15], v[194:197], v[242:245], v[12:15]
	ds_read_b128 v[202:205], v181 offset:2368
	s_waitcnt lgkmcnt(4)
; DI f32x4 mfma16(bf16x8 a, bf16x8 b, f32x4 c) { return __builtin_amdgcn_mfma_f32_16x16x32_bf16(a, b, c, 0, 0, 0); }
; template <int MI, int NJ, bool SWAP, class AP, class BP>
; DI void gemm_main(f32x4 (&acc)[MI][NJ], const AP& ap, int a_kstep, const BP& bp, int b_kstep, int nk, bf16_t* smem) {
;     ...
;   auto gload = [&](int kt) {
;     const bf16_t* ab = ap.base + (size_t)kt * a_kstep; const bf16_t* bb = bp.base + (size_t)kt * b_kstep;
; #pragma unroll
;     for (int i = 0; i < CA; ++i) ra[i] = *(const u32x4*)(ab + pa[i]);
; #pragma unroll
;     for (int i = 0; i < CB; ++i) rb[i] = *(const u32x4*)(bb + pb[i]);
;   };
;   auto sstore = [&](int buf) {
;     bf16_t* As = smem + buf * L::STAGE; bf16_t* Bs = As + L::A_ELEMS;
; #pragma unroll
;     for (int i = 0; i < CA; ++i) { const int c = tid + NTHR * i; *(u32x4*)(As + (c >> 3) * LDT + (c & 7) * 8) = oka[i] ? ra[i] : (u32x4){0u, 0u, 0u, 0u}; }
; #pragma unroll
;     for (int i = 0; i < CB; ++i) { const int c = tid + NTHR * i; *(u32x4*)(Bs + (c >> 3) * LDT + (c & 7) * 8) = rb[i]; }
;   };
;   gload(0); sstore(0); gload(nk > 1 ? 1 : 0); __syncthreads();
; #pragma unroll 1
;   for (int kt = 0; kt < nk; ++kt) {
;     const int buf = kt & 1;
;     sstore(buf ^ 1);
;     gload(kt + 2 < nk ? kt + 2 : nk - 1);
;     __builtin_amdgcn_sched_barrier(0);
;     const bf16_t* As = smem + buf * L::STAGE + (wm * 16 * MI + l15) * LDT + quad * 8;
;     const bf16_t* Bs = smem + buf * L::STAGE + L::A_ELEMS + (wn * 16 * NJ + l15) * LDT + quad * 8;
; #pragma unroll
;     for (int ks = 0; ks < 2; ++ks) {
;       if (MI * NJ >= 32 && ks == 1) asm volatile("" ::: "memory");
;       bf16x8 b[NJ];
; #pragma unroll
;       for (int j = 0; j < NJ; ++j) b[j] = *(const bf16x8*)(Bs + j * 16 * LDT + ks * 32);
; #pragma unroll
;       for (int i = 0; i < MI; ++i) {
;         const bf16x8 a = *(const bf16x8*)(As + i * 16 * LDT + ks * 32);
; #pragma unroll
;         for (int j = 0; j < NJ; ++j) acc[i][j] = SWAP ? mfma16(b[j], a, acc[i][j]) : mfma16(a, b[j], acc[i][j]);
;       }
;     }
;     __syncthreads();
;   }
	v_mfma_f32_16x16x32_bf16 v[8:11], v[182:185], v[246:249], v[8:11]
	ds_read_b128 v[182:185], v206 offset:36928
	s_add_u32 s44, s20, s47
	s_addc_u32 s45, s21, 0
	v_lshl_add_u64 v[116:117], v[160:161], 1, s[44:45]
	s_nop 0
	global_load_dwordx4 v[116:119], v[116:117], off offset:256
	v_mfma_f32_16x16x32_bf16 v[4:7], v[186:189], v[246:249], v[4:7]
	ds_read_b128 v[186:189], v206 offset:39232
	v_mfma_f32_16x16x32_bf16 v[0:3], v[190:193], v[246:249], v[0:3]
	ds_read_b128 v[190:193], v206 offset:41536
	v_mfma_f32_16x16x32_bf16 v[16:19], v[194:197], v[246:249], v[16:19]
	ds_read_b128 v[194:197], v206 offset:43840
	ds_read_b128 v[242:245], v181 offset:4672
	s_waitcnt lgkmcnt(4)
	v_mfma_f32_16x16x32_bf16 v[156:159], v[182:185], v[198:201], v[156:159]
	s_waitcnt vmcnt(7)
	ds_write_b128 v251, v[120:123] offset:36864
	s_waitcnt lgkmcnt(4)
	v_mfma_f32_16x16x32_bf16 v[152:155], v[186:189], v[198:201], v[152:155]
	s_waitcnt lgkmcnt(3)
	v_mfma_f32_16x16x32_bf16 v[148:151], v[190:193], v[198:201], v[148:151]
	v_lshl_add_u64 v[120:121], v[162:163], 1, s[44:45]
	s_nop 0
	global_load_dwordx4 v[120:123], v[120:121], off offset:256
	s_waitcnt lgkmcnt(2)
	v_mfma_f32_16x16x32_bf16 v[144:147], v[194:197], v[198:201], v[144:147]
	ds_read_b128 v[246:249], v181 offset:6976
	v_mfma_f32_16x16x32_bf16 v[108:111], v[182:185], v[202:205], v[108:111]
	v_mfma_f32_16x16x32_bf16 v[104:107], v[186:189], v[202:205], v[104:107]
	v_mfma_f32_16x16x32_bf16 v[100:103], v[190:193], v[202:205], v[100:103]
	s_waitcnt vmcnt(7)
	ds_write_b128 v252, v[124:127] offset:36864
	v_mfma_f32_16x16x32_bf16 v[96:99], v[194:197], v[202:205], v[96:99]
	ds_read_b128 v[198:201], v181 offset:9280
	s_waitcnt lgkmcnt(4)
	v_mfma_f32_16x16x32_bf16 v[92:95], v[182:185], v[242:245], v[92:95]
	v_lshl_add_u64 v[124:125], v[164:165], 1, s[44:45]
	s_nop 0
	global_load_dwordx4 v[124:127], v[124:125], off offset:256
	v_mfma_f32_16x16x32_bf16 v[88:91], v[186:189], v[242:245], v[88:91]
	v_mfma_f32_16x16x32_bf16 v[84:87], v[190:193], v[242:245], v[84:87]
	v_mfma_f32_16x16x32_bf16 v[80:83], v[194:197], v[242:245], v[80:83]
	ds_read_b128 v[202:205], v181 offset:11584
	s_waitcnt lgkmcnt(3)
	v_mfma_f32_16x16x32_bf16 v[76:79], v[182:185], v[246:249], v[76:79]
	s_waitcnt vmcnt(7)
	ds_write_b128 v253, v[136:139] offset:36864
	v_mfma_f32_16x16x32_bf16 v[72:75], v[186:189], v[246:249], v[72:75]
	v_mfma_f32_16x16x32_bf16 v[68:71], v[190:193], v[246:249], v[68:71]
	v_lshl_add_u64 v[136:137], v[166:167], 1, s[44:45]
	s_nop 0
	global_load_dwordx4 v[136:139], v[136:137], off offset:256
	v_mfma_f32_16x16x32_bf16 v[64:67], v[194:197], v[246:249], v[64:67]
	ds_read_b128 v[242:245], v181 offset:13888
	s_waitcnt lgkmcnt(3)
	v_mfma_f32_16x16x32_bf16 v[60:63], v[182:185], v[198:201], v[60:63]
	v_mfma_f32_16x16x32_bf16 v[56:59], v[186:189], v[198:201], v[56:59]
	v_mfma_f32_16x16x32_bf16 v[52:55], v[190:193], v[198:201], v[52:55]
	v_mfma_f32_16x16x32_bf16 v[48:51], v[194:197], v[198:201], v[48:51]
	ds_read_b128 v[246:249], v181 offset:16192
	s_waitcnt lgkmcnt(3)
	v_mfma_f32_16x16x32_bf16 v[44:47], v[182:185], v[202:205], v[44:47]
	v_mfma_f32_16x16x32_bf16 v[40:43], v[186:189], v[202:205], v[40:43]
	v_mfma_f32_16x16x32_bf16 v[36:39], v[190:193], v[202:205], v[36:39]
	v_mfma_f32_16x16x32_bf16 v[32:35], v[194:197], v[202:205], v[32:35]
	s_add_i32 s43, s43, 1
	s_and_b32 s98, s43, 1
	s_mul_i32 s98, s98, 0x12000
	v_add3_u32 v206, s98, v171, v180
	v_add3_u32 v181, s98, v170, v180
	s_cmp_lg_u32 s43, 16
	s_waitcnt lgkmcnt(0)
	s_barrier
	s_cbranch_scc0 .Lgm14_exit
	ds_read_b128 v[198:201], v181
	ds_read_b128 v[202:205], v181 offset:2304
	v_mfma_f32_16x16x32_bf16 v[28:31], v[182:185], v[242:245], v[28:31]
	v_mfma_f32_16x16x32_bf16 v[8:11], v[182:185], v[246:249], v[8:11]
	ds_read_b128 v[182:185], v206 offset:36864
	v_mfma_f32_16x16x32_bf16 v[24:27], v[186:189], v[242:245], v[24:27]
	v_mfma_f32_16x16x32_bf16 v[4:7], v[186:189], v[246:249], v[4:7]
	ds_read_b128 v[186:189], v206 offset:39168
	v_mfma_f32_16x16x32_bf16 v[20:23], v[190:193], v[242:245], v[20:23]
	v_mfma_f32_16x16x32_bf16 v[0:3], v[190:193], v[246:249], v[0:3]
	ds_read_b128 v[190:193], v206 offset:41472
	v_mfma_f32_16x16x32_bf16 v[12:15], v[194:197], v[242:245], v[12:15]
	v_mfma_f32_16x16x32_bf16 v[16:19], v[194:197], v[246:249], v[16:19]
	ds_read_b128 v[194:197], v206 offset:43776
	s_branch .Lgm14_main

; DI f32x4 mfma16(bf16x8 a, bf16x8 b, f32x4 c) { return __builtin_amdgcn_mfma_f32_16x16x32_bf16(a, b, c, 0, 0, 0); }
; template <int MI, int NJ, bool SWAP, class AP, class BP>
; DI void gemm_main(f32x4 (&acc)[MI][NJ], const AP& ap, int a_kstep, const BP& bp, int b_kstep, int nk, bf16_t* smem) {
;     ...
;   auto sstore = [&](int buf) {
;     bf16_t* As = smem + buf * L::STAGE; bf16_t* Bs = As + L::A_ELEMS;
; #pragma unroll
;     for (int i = 0; i < CA; ++i) { const int c = tid + NTHR * i; *(u32x4*)(As + (c >> 3) * LDT + (c & 7) * 8) = oka[i] ? ra[i] : (u32x4){0u, 0u, 0u, 0u}; }
; #pragma unroll
;     for (int i = 0; i < CB; ++i) { const int c = tid + NTHR * i; *(u32x4*)(Bs + (c >> 3) * LDT + (c & 7) * 8) = rb[i]; }
;   };
;   gload(0); sstore(0); gload(nk > 1 ? 1 : 0); __syncthreads();
; #pragma unroll 1
;   for (int kt = 0; kt < nk; ++kt) {
;     const int buf = kt & 1;
;     sstore(buf ^ 1);
;     gload(kt + 2 < nk ? kt + 2 : nk - 1);
;     __builtin_amdgcn_sched_barrier(0);
;     const bf16_t* As = smem + buf * L::STAGE + (wm * 16 * MI + l15) * LDT + quad * 8;
;     const bf16_t* Bs = smem + buf * L::STAGE + L::A_ELEMS + (wn * 16 * NJ + l15) * LDT + quad * 8;
; #pragma unroll
;     for (int ks = 0; ks < 2; ++ks) {
;       if (MI * NJ >= 32 && ks == 1) asm volatile("" ::: "memory");
;       bf16x8 b[NJ];
; #pragma unroll
;       for (int j = 0; j < NJ; ++j) b[j] = *(const bf16x8*)(Bs + j * 16 * LDT + ks * 32);
; #pragma unroll
;       for (int i = 0; i < MI; ++i) {
;         const bf16x8 a = *(const bf16x8*)(As + i * 16 * LDT + ks * 32);
; #pragma unroll
;         for (int j = 0; j < NJ; ++j) acc[i][j] = SWAP ? mfma16(b[j], a, acc[i][j]) : mfma16(a, b[j], acc[i][j]);
;       }
.Lgm15_main:
	ds_read_b128 v[242:245], v177 offset:4608
	s_waitcnt lgkmcnt(4)
	v_mfma_f32_16x16x32_bf16 v[156:159], v[178:181], v[194:197], v[156:159]
	s_waitcnt lgkmcnt(3)
	v_mfma_f32_16x16x32_bf16 v[152:155], v[182:185], v[194:197], v[152:155]
	s_waitcnt lgkmcnt(2)
	v_mfma_f32_16x16x32_bf16 v[148:151], v[186:189], v[194:197], v[148:151]
	s_and_b32 s17, s16, 1
	s_min_u32 s18, s16, 41
	s_xor_b32 s19, s17, 1
	s_mul_i32 s19, s19, 0x12000
	v_add3_u32 v250, s19, v172, v170
	s_waitcnt vmcnt(7)
	ds_write_b128 v250, v[112:115]
	s_waitcnt lgkmcnt(2)
	v_mfma_f32_16x16x32_bf16 v[144:147], v[190:193], v[194:197], v[144:147]
	ds_read_b128 v[246:249], v177 offset:6912
	v_mfma_f32_16x16x32_bf16 v[108:111], v[178:181], v[198:201], v[108:111]
	s_lshl_b32 s20, s18, 7
	s_add_u32 s18, s2, s20
	v_add3_u32 v251, s19, v173, v170
	v_add3_u32 v252, s19, v174, v170
	v_add3_u32 v253, s19, v175, v170
	s_addc_u32 s19, s3, 0
	v_lshl_add_u64 v[112:113], s[18:19], 0, v[162:163]
	s_nop 0
	global_load_dwordx4 v[112:115], v[112:113], off offset:256
	v_mfma_f32_16x16x32_bf16 v[104:107], v[182:185], v[198:201], v[104:107]
	v_mfma_f32_16x16x32_bf16 v[100:103], v[186:189], v[198:201], v[100:103]
	v_mfma_f32_16x16x32_bf16 v[96:99], v[190:193], v[198:201], v[96:99]
	ds_read_b128 v[194:197], v177 offset:9216
	s_waitcnt lgkmcnt(3)
	v_mfma_f32_16x16x32_bf16 v[92:95], v[178:181], v[242:245], v[92:95]
	s_waitcnt vmcnt(7)
	ds_write_b128 v251, v[116:119]
	v_mfma_f32_16x16x32_bf16 v[88:91], v[182:185], v[242:245], v[88:91]
	v_mfma_f32_16x16x32_bf16 v[84:87], v[186:189], v[242:245], v[84:87]
	v_lshl_add_u64 v[116:117], s[18:19], 0, v[164:165]
	s_nop 0
	global_load_dwordx4 v[116:119], v[116:117], off offset:256
	v_mfma_f32_16x16x32_bf16 v[80:83], v[190:193], v[242:245], v[80:83]
	ds_read_b128 v[198:201], v177 offset:11520
	s_waitcnt lgkmcnt(3)
	v_mfma_f32_16x16x32_bf16 v[76:79], v[178:181], v[246:249], v[76:79]
	v_mfma_f32_16x16x32_bf16 v[72:75], v[182:185], v[246:249], v[72:75]
	v_mfma_f32_16x16x32_bf16 v[68:71], v[186:189], v[246:249], v[68:71]
	s_waitcnt vmcnt(7)
	ds_write_b128 v252, v[120:123]
	v_mfma_f32_16x16x32_bf16 v[64:67], v[190:193], v[246:249], v[64:67]
	ds_read_b128 v[242:245], v177 offset:13824
	s_waitcnt lgkmcnt(4)
	v_mfma_f32_16x16x32_bf16 v[60:63], v[178:181], v[194:197], v[60:63]
	v_lshl_add_u64 v[120:121], s[18:19], 0, v[166:167]
	s_nop 0
	global_load_dwordx4 v[120:123], v[120:121], off offset:256
	v_mfma_f32_16x16x32_bf16 v[56:59], v[182:185], v[194:197], v[56:59]
	v_mfma_f32_16x16x32_bf16 v[52:55], v[186:189], v[194:197], v[52:55]
	v_mfma_f32_16x16x32_bf16 v[48:51], v[190:193], v[194:197], v[48:51]
	ds_read_b128 v[246:249], v177 offset:16128
	s_waitcnt lgkmcnt(3)
	v_mfma_f32_16x16x32_bf16 v[44:47], v[178:181], v[198:201], v[44:47]
	s_waitcnt vmcnt(7)
	ds_write_b128 v253, v[124:127]
	v_mfma_f32_16x16x32_bf16 v[40:43], v[182:185], v[198:201], v[40:43]
	v_mfma_f32_16x16x32_bf16 v[36:39], v[186:189], v[198:201], v[36:39]
	v_lshl_add_u64 v[124:125], s[18:19], 0, v[168:169]
	s_nop 0
	global_load_dwordx4 v[124:127], v[124:125], off offset:256
	v_mfma_f32_16x16x32_bf16 v[32:35], v[190:193], v[198:201], v[32:35]
	ds_read_b128 v[194:197], v177 offset:64
	s_waitcnt lgkmcnt(3)
	v_mfma_f32_16x16x32_bf16 v[28:31], v[178:181], v[242:245], v[28:31]
	v_mfma_f32_16x16x32_bf16 v[24:27], v[182:185], v[242:245], v[24:27]
	v_mfma_f32_16x16x32_bf16 v[20:23], v[186:189], v[242:245], v[20:23]
	s_waitcnt vmcnt(7)
	ds_write_b128 v250, v[128:131] offset:36864
	v_mfma_f32_16x16x32_bf16 v[16:19], v[190:193], v[242:245], v[16:19]
	ds_read_b128 v[198:201], v177 offset:2368
	s_waitcnt lgkmcnt(4)
	v_mfma_f32_16x16x32_bf16 v[8:11], v[178:181], v[246:249], v[8:11]
	ds_read_b128 v[178:181], v202 offset:36928
	s_add_u32 s18, s4, s20
	s_addc_u32 s19, s5, 0
	v_lshl_add_u64 v[128:129], s[18:19], 0, v[162:163]
	s_nop 0
	global_load_dwordx4 v[128:131], v[128:129], off offset:256
	v_mfma_f32_16x16x32_bf16 v[4:7], v[182:185], v[246:249], v[4:7]
	ds_read_b128 v[182:185], v202 offset:39232
	v_mfma_f32_16x16x32_bf16 v[0:3], v[186:189], v[246:249], v[0:3]
	ds_read_b128 v[186:189], v202 offset:41536
	v_mfma_f32_16x16x32_bf16 v[12:15], v[190:193], v[246:249], v[12:15]
	ds_read_b128 v[190:193], v202 offset:43840
	ds_read_b128 v[242:245], v177 offset:4672
	s_waitcnt lgkmcnt(4)
; DI f32x4 mfma16(bf16x8 a, bf16x8 b, f32x4 c) { return __builtin_amdgcn_mfma_f32_16x16x32_bf16(a, b, c, 0, 0, 0); }
; template <int MI, int NJ, bool SWAP, class AP, class BP>
; DI void gemm_main(f32x4 (&acc)[MI][NJ], const AP& ap, int a_kstep, const BP& bp, int b_kstep, int nk, bf16_t* smem) {
;     ...
;   auto gload = [&](int kt) {
;     const bf16_t* ab = ap.base + (size_t)kt * a_kstep; const bf16_t* bb = bp.base + (size_t)kt * b_kstep;
; #pragma unroll
;     for (int i = 0; i < CA; ++i) ra[i] = *(const u32x4*)(ab + pa[i]);
; #pragma unroll
;     for (int i = 0; i < CB; ++i) rb[i] = *(const u32x4*)(bb + pb[i]);
;   };
;   auto sstore = [&](int buf) {
;     bf16_t* As = smem + buf * L::STAGE; bf16_t* Bs = As + L::A_ELEMS;
; #pragma unroll
;     for (int i = 0; i < CA; ++i) { const int c = tid + NTHR * i; *(u32x4*)(As + (c >> 3) * LDT + (c & 7) * 8) = oka[i] ? ra[i] : (u32x4){0u, 0u, 0u, 0u}; }
; #pragma unroll
;     for (int i = 0; i < CB; ++i) { const int c = tid + NTHR * i; *(u32x4*)(Bs + (c >> 3) * LDT + (c & 7) * 8) = rb[i]; }
;   };
;   gload(0); sstore(0); gload(nk > 1 ? 1 : 0); __syncthreads();
; #pragma unroll 1
;   for (int kt = 0; kt < nk; ++kt) {
;     const int buf = kt & 1;
;     sstore(buf ^ 1);
;     gload(kt + 2 < nk ? kt + 2 : nk - 1);
;     __builtin_amdgcn_sched_barrier(0);
;     const bf16_t* As = smem + buf * L::STAGE + (wm * 16 * MI + l15) * LDT + quad * 8;
;     const bf16_t* Bs = smem + buf * L::STAGE + L::A_ELEMS + (wn * 16 * NJ + l15) * LDT + quad * 8;
; #pragma unroll
;     for (int ks = 0; ks < 2; ++ks) {
;       if (MI * NJ >= 32 && ks == 1) asm volatile("" ::: "memory");
;       bf16x8 b[NJ];
; #pragma unroll
;       for (int j = 0; j < NJ; ++j) b[j] = *(const bf16x8*)(Bs + j * 16 * LDT + ks * 32);
; #pragma unroll
;       for (int i = 0; i < MI; ++i) {
;         const bf16x8 a = *(const bf16x8*)(As + i * 16 * LDT + ks * 32);
; #pragma unroll
;         for (int j = 0; j < NJ; ++j) acc[i][j] = SWAP ? mfma16(b[j], a, acc[i][j]) : mfma16(a, b[j], acc[i][j]);
;       }
;     }
;     __syncthreads();
;   }
	v_mfma_f32_16x16x32_bf16 v[156:159], v[178:181], v[194:197], v[156:159]
	s_waitcnt vmcnt(7)
	ds_write_b128 v251, v[132:135] offset:36864
	s_waitcnt lgkmcnt(4)
	v_mfma_f32_16x16x32_bf16 v[152:155], v[182:185], v[194:197], v[152:155]
	s_waitcnt lgkmcnt(3)
	v_mfma_f32_16x16x32_bf16 v[148:151], v[186:189], v[194:197], v[148:151]
	v_lshl_add_u64 v[132:133], s[18:19], 0, v[164:165]
	s_nop 0
	global_load_dwordx4 v[132:135], v[132:133], off offset:256
	s_waitcnt lgkmcnt(2)
	v_mfma_f32_16x16x32_bf16 v[144:147], v[190:193], v[194:197], v[144:147]
	ds_read_b128 v[246:249], v177 offset:6976
	v_mfma_f32_16x16x32_bf16 v[108:111], v[178:181], v[198:201], v[108:111]
	v_mfma_f32_16x16x32_bf16 v[104:107], v[182:185], v[198:201], v[104:107]
	v_mfma_f32_16x16x32_bf16 v[100:103], v[186:189], v[198:201], v[100:103]
	s_waitcnt vmcnt(7)
	ds_write_b128 v252, v[136:139] offset:36864
	v_mfma_f32_16x16x32_bf16 v[96:99], v[190:193], v[198:201], v[96:99]
	ds_read_b128 v[194:197], v177 offset:9280
	s_waitcnt lgkmcnt(4)
	v_mfma_f32_16x16x32_bf16 v[92:95], v[178:181], v[242:245], v[92:95]
	v_lshl_add_u64 v[136:137], s[18:19], 0, v[166:167]
	s_nop 0
	global_load_dwordx4 v[136:139], v[136:137], off offset:256
	v_mfma_f32_16x16x32_bf16 v[88:91], v[182:185], v[242:245], v[88:91]
	v_mfma_f32_16x16x32_bf16 v[84:87], v[186:189], v[242:245], v[84:87]
	v_mfma_f32_16x16x32_bf16 v[80:83], v[190:193], v[242:245], v[80:83]
	ds_read_b128 v[198:201], v177 offset:11584
	s_waitcnt lgkmcnt(3)
	v_mfma_f32_16x16x32_bf16 v[76:79], v[178:181], v[246:249], v[76:79]
	s_waitcnt vmcnt(7)
	ds_write_b128 v253, v[140:143] offset:36864
	v_mfma_f32_16x16x32_bf16 v[72:75], v[182:185], v[246:249], v[72:75]
	v_mfma_f32_16x16x32_bf16 v[68:71], v[186:189], v[246:249], v[68:71]
	v_lshl_add_u64 v[140:141], s[18:19], 0, v[168:169]
	s_nop 0
	global_load_dwordx4 v[140:143], v[140:141], off offset:256
	v_mfma_f32_16x16x32_bf16 v[64:67], v[190:193], v[246:249], v[64:67]
	ds_read_b128 v[242:245], v177 offset:13888
	s_waitcnt lgkmcnt(3)
	v_mfma_f32_16x16x32_bf16 v[60:63], v[178:181], v[194:197], v[60:63]
	v_mfma_f32_16x16x32_bf16 v[56:59], v[182:185], v[194:197], v[56:59]
	v_mfma_f32_16x16x32_bf16 v[52:55], v[186:189], v[194:197], v[52:55]
	v_mfma_f32_16x16x32_bf16 v[48:51], v[190:193], v[194:197], v[48:51]
	ds_read_b128 v[246:249], v177 offset:16192
	s_waitcnt lgkmcnt(3)
	v_mfma_f32_16x16x32_bf16 v[44:47], v[178:181], v[198:201], v[44:47]
	v_mfma_f32_16x16x32_bf16 v[40:43], v[182:185], v[198:201], v[40:43]
	v_mfma_f32_16x16x32_bf16 v[36:39], v[186:189], v[198:201], v[36:39]
	v_mfma_f32_16x16x32_bf16 v[32:35], v[190:193], v[198:201], v[32:35]
	s_add_i32 s16, s16, 1
	s_and_b32 s98, s16, 1
	s_mul_i32 s98, s98, 0x12000
	v_add3_u32 v202, s98, v160, v176
	v_add3_u32 v177, s98, v171, v176
	s_cmp_lg_u32 s16, 44
	s_waitcnt lgkmcnt(0)
	s_barrier
	s_cbranch_scc0 .Lgm15_exit
	ds_read_b128 v[194:197], v177
	ds_read_b128 v[198:201], v177 offset:2304
	v_mfma_f32_16x16x32_bf16 v[28:31], v[178:181], v[242:245], v[28:31]
	v_mfma_f32_16x16x32_bf16 v[8:11], v[178:181], v[246:249], v[8:11]
	ds_read_b128 v[178:181], v202 offset:36864
	v_mfma_f32_16x16x32_bf16 v[24:27], v[182:185], v[242:245], v[24:27]
	v_mfma_f32_16x16x32_bf16 v[4:7], v[182:185], v[246:249], v[4:7]
	ds_read_b128 v[182:185], v202 offset:39168
	v_mfma_f32_16x16x32_bf16 v[20:23], v[186:189], v[242:245], v[20:23]
	v_mfma_f32_16x16x32_bf16 v[0:3], v[186:189], v[246:249], v[0:3]
	ds_read_b128 v[186:189], v202 offset:41472
	v_mfma_f32_16x16x32_bf16 v[16:19], v[190:193], v[242:245], v[16:19]
	v_mfma_f32_16x16x32_bf16 v[12:15], v[190:193], v[246:249], v[12:15]
	ds_read_b128 v[190:193], v202 offset:43776
	s_branch .Lgm15_main
